# GEMM LDS-DMA staging: M0 write issued before the address VALU so the s_nop 0 after it goes (65 sites, 16 per K-loop iteration)
# baseline (speedup 1.0000x reference)
; #define STG(P, GB) do { const char* _gb = (GB); \
;     _Pragma("unroll") for (int _i = 0; _i < 2; ++_i) { \
;       __builtin_amdgcn_global_load_lds((const unsigned*)(_gb + voff[_i]), \
;         (LAS unsigned*)((LAS char*)(P) + ldsw + _i * 8192), 16, 0, 0); } } while (0)
; #define LDA(dst, b, h) _Pragma("unroll") for (int m = 0; m < 4; ++m) _Pragma("unroll") for (int k = 0; k < 2; ++k) \
;     dst[m][k] = *(const LAS bf16x8*)((LAS char*)SA(b, h) + aoff + m * 2048 + k * 1024)
; #define LDB(dst, b, h) _Pragma("unroll") for (int n = 0; n < 2; ++n) _Pragma("unroll") for (int k = 0; k < 2; ++k) \
;     dst[n][k] = *(const LAS bf16x8*)((LAS char*)SB(b, h) + boff + n * 2048 + k * 1024)
; #define MMA(ai, bj, At_, Bt_) do { __builtin_amdgcn_s_setprio(1); \
;     _Pragma("unroll") for (int m = 0; m < 4; ++m) _Pragma("unroll") for (int n = 0; n < 2; ++n) _Pragma("unroll") for (int k = 0; k < 2; ++k) \
;       acc[ai][bj][m][n] = __builtin_amdgcn_mfma_f32_16x16x32_bf16(Bt_[n][k], At_[m][k], acc[ai][bj][m][n], 0, 0, 0); \
;     __builtin_amdgcn_s_setprio(0); } while (0)
; #define WAIT_L(n) asm volatile("s_waitcnt lgkmcnt(" #n ")" ::: "memory")
; #define BAR __builtin_amdgcn_s_barrier()
; #define SCHED __builtin_amdgcn_sched_barrier(0)
; __device__ __forceinline__ void gemm_phase(const bf16_t* __restrict__ A, const bf16_t* __restrict__ Bt, bf16_t* __restrict__ C, int M, int N, int K,
;                                            int ldc, const int EPI, char* smem, const int wid_u) {
;     ...
;       LDB(B0, 0, 0); SCHED; LDA(At, 0, 0); STG(SA(1, 1), a1 + hstep);
;       WAIT_L(8); BAR; WAIT_L(0); MMA(0, 0, At, B0); BAR; SCHED;
;       LDB(B1, 0, 1); STG(SB(0, 0), b2);
;       BAR; WAIT_L(0); MMA(0, 1, At, B1); BAR;
;       LDA(At, 0, 1); STG(SA(0, 0), a2);
;       BAR; WAIT_L(0); MMA(1, 0, At, B0); BAR; SCHED;
.LBB0_145:
	ds_read_b128 v[150:153], v146
	ds_read_b128 v[154:157], v146 offset:1024
	ds_read_b128 v[158:161], v146 offset:2048
	ds_read_b128 v[162:165], v146 offset:3072
	s_add_u32 s18, s16, 0x100
	s_addc_u32 s19, s17, 0
	s_cmp_eq_u32 s49, 12
	s_cselect_b32 s23, s44, s19
	s_cselect_b32 s22, s45, s18
	s_cselect_b32 s21, s11, s48
	s_cselect_b32 s20, s46, s47
	v_lshl_add_u64 v[142:143], s[16:17], 0, v[136:137]
	s_add_i32 m0, s28, 0xc000
	ds_read_b128 v[166:169], v147
	ds_read_b128 v[170:173], v147 offset:1024
	ds_read_b128 v[174:177], v147 offset:2048
	ds_read_b128 v[178:181], v147 offset:3072
	ds_read_b128 v[182:185], v147 offset:4096
	ds_read_b128 v[186:189], v147 offset:5120
	ds_read_b128 v[190:193], v147 offset:6144
	ds_read_b128 v[194:197], v147 offset:7168
	global_load_lds_dwordx4 v[142:143], off
	s_add_i32 m0, s28, 0xe000
	v_lshl_add_u64 v[142:143], s[16:17], 0, v[134:135]
	global_load_lds_dwordx4 v[142:143], off
	s_waitcnt lgkmcnt(8)
	s_barrier
	s_waitcnt lgkmcnt(0)
	s_waitcnt lgkmcnt(0)
	v_mfma_f32_16x16x32_bf16 v[124:127], v[150:153], v[166:169], v[124:127]
	v_mfma_f32_16x16x32_bf16 v[120:123], v[158:161], v[166:169], v[120:123]
	v_mfma_f32_16x16x32_bf16 v[108:111], v[150:153], v[174:177], v[108:111]
	v_mfma_f32_16x16x32_bf16 v[104:107], v[158:161], v[174:177], v[104:107]
	v_mfma_f32_16x16x32_bf16 v[92:95], v[150:153], v[182:185], v[92:95]
	v_mfma_f32_16x16x32_bf16 v[88:91], v[158:161], v[182:185], v[88:91]
	v_mfma_f32_16x16x32_bf16 v[76:79], v[150:153], v[190:193], v[76:79]
	v_mfma_f32_16x16x32_bf16 v[72:75], v[158:161], v[190:193], v[72:75]
	v_mfma_f32_16x16x32_bf16 v[124:127], v[154:157], v[170:173], v[124:127]
	v_mfma_f32_16x16x32_bf16 v[120:123], v[162:165], v[170:173], v[120:123]
	v_mfma_f32_16x16x32_bf16 v[108:111], v[154:157], v[178:181], v[108:111]
	v_mfma_f32_16x16x32_bf16 v[104:107], v[162:165], v[178:181], v[104:107]
	v_mfma_f32_16x16x32_bf16 v[92:95], v[154:157], v[186:189], v[92:95]
	v_mfma_f32_16x16x32_bf16 v[88:91], v[162:165], v[186:189], v[88:91]
	v_mfma_f32_16x16x32_bf16 v[76:79], v[154:157], v[194:197], v[76:79]
	v_mfma_f32_16x16x32_bf16 v[72:75], v[162:165], v[194:197], v[72:75]
	s_barrier
	s_add_i32 s16, s36, s27
	v_lshl_add_u64 v[142:143], s[20:21], 0, v[130:131]
	s_mov_b32 m0, s16
	ds_read_b128 v[198:201], v148
	ds_read_b128 v[202:205], v148 offset:1024
	ds_read_b128 v[206:209], v148 offset:2048
	ds_read_b128 v[210:213], v148 offset:3072
	global_load_lds_dwordx4 v[142:143], off
	s_add_i32 m0, s16, 0x2000
	v_lshl_add_u64 v[214:215], s[20:21], 0, v[128:129]
	global_load_lds_dwordx4 v[214:215], off
	s_barrier
	s_waitcnt lgkmcnt(0)
	s_waitcnt lgkmcnt(0)
	v_mfma_f32_16x16x32_bf16 v[116:119], v[198:201], v[166:169], v[116:119]
	v_mfma_f32_16x16x32_bf16 v[112:115], v[206:209], v[166:169], v[112:115]
	v_mfma_f32_16x16x32_bf16 v[100:103], v[198:201], v[174:177], v[100:103]
	v_mfma_f32_16x16x32_bf16 v[96:99], v[206:209], v[174:177], v[96:99]
	v_mfma_f32_16x16x32_bf16 v[84:87], v[198:201], v[182:185], v[84:87]
	v_mfma_f32_16x16x32_bf16 v[80:83], v[206:209], v[182:185], v[80:83]
	v_mfma_f32_16x16x32_bf16 v[68:71], v[198:201], v[190:193], v[68:71]
	v_mfma_f32_16x16x32_bf16 v[64:67], v[206:209], v[190:193], v[64:67]
	v_mfma_f32_16x16x32_bf16 v[116:119], v[202:205], v[170:173], v[116:119]
	v_mfma_f32_16x16x32_bf16 v[112:115], v[210:213], v[170:173], v[112:115]
	v_mfma_f32_16x16x32_bf16 v[100:103], v[202:205], v[178:181], v[100:103]
	v_mfma_f32_16x16x32_bf16 v[96:99], v[210:213], v[178:181], v[96:99]
	v_mfma_f32_16x16x32_bf16 v[84:87], v[202:205], v[186:189], v[84:87]
	v_mfma_f32_16x16x32_bf16 v[80:83], v[210:213], v[186:189], v[80:83]
	v_mfma_f32_16x16x32_bf16 v[68:71], v[202:205], v[194:197], v[68:71]
	v_mfma_f32_16x16x32_bf16 v[64:67], v[210:213], v[194:197], v[64:67]
	s_mov_b32 m0, s28
	v_lshl_add_u64 v[216:217], s[22:23], 0, v[130:131]
	s_barrier
	ds_read_b128 v[166:169], v147 offset:16384
	ds_read_b128 v[170:173], v147 offset:17408
	ds_read_b128 v[174:177], v147 offset:18432
	ds_read_b128 v[178:181], v147 offset:19456
	ds_read_b128 v[182:185], v147 offset:20480
	ds_read_b128 v[186:189], v147 offset:21504
	ds_read_b128 v[190:193], v147 offset:22528
	ds_read_b128 v[194:197], v147 offset:23552
	global_load_lds_dwordx4 v[216:217], off
	s_mov_b32 m0, s29
	v_lshl_add_u64 v[218:219], s[22:23], 0, v[128:129]
	global_load_lds_dwordx4 v[218:219], off
	s_barrier
	s_waitcnt lgkmcnt(0)
	s_waitcnt lgkmcnt(0)
	v_mfma_f32_16x16x32_bf16 v[60:63], v[150:153], v[166:169], v[60:63]
	v_mfma_f32_16x16x32_bf16 v[56:59], v[158:161], v[166:169], v[56:59]
	v_mfma_f32_16x16x32_bf16 v[44:47], v[150:153], v[174:177], v[44:47]
	v_mfma_f32_16x16x32_bf16 v[40:43], v[158:161], v[174:177], v[40:43]
	v_mfma_f32_16x16x32_bf16 v[28:31], v[150:153], v[182:185], v[28:31]
	v_mfma_f32_16x16x32_bf16 v[24:27], v[158:161], v[182:185], v[24:27]
	v_mfma_f32_16x16x32_bf16 v[12:15], v[150:153], v[190:193], v[12:15]
	v_mfma_f32_16x16x32_bf16 v[8:11], v[158:161], v[190:193], v[8:11]
	v_mfma_f32_16x16x32_bf16 v[60:63], v[154:157], v[170:173], v[60:63]
	v_mfma_f32_16x16x32_bf16 v[56:59], v[162:165], v[170:173], v[56:59]
	v_mfma_f32_16x16x32_bf16 v[44:47], v[154:157], v[178:181], v[44:47]
	v_mfma_f32_16x16x32_bf16 v[40:43], v[162:165], v[178:181], v[40:43]
	v_mfma_f32_16x16x32_bf16 v[28:31], v[154:157], v[186:189], v[28:31]
	v_mfma_f32_16x16x32_bf16 v[24:27], v[162:165], v[186:189], v[24:27]
	v_mfma_f32_16x16x32_bf16 v[12:15], v[154:157], v[194:197], v[12:15]
	v_mfma_f32_16x16x32_bf16 v[8:11], v[162:165], v[194:197], v[8:11]
	s_barrier
; #define STG(P, GB) do { const char* _gb = (GB); \
;     _Pragma("unroll") for (int _i = 0; _i < 2; ++_i) { \
;       __builtin_amdgcn_global_load_lds((const unsigned*)(_gb + voff[_i]), \
;         (LAS unsigned*)((LAS char*)(P) + ldsw + _i * 8192), 16, 0, 0); } } while (0)
; #define LDA(dst, b, h) _Pragma("unroll") for (int m = 0; m < 4; ++m) _Pragma("unroll") for (int k = 0; k < 2; ++k) \
;     dst[m][k] = *(const LAS bf16x8*)((LAS char*)SA(b, h) + aoff + m * 2048 + k * 1024)
; #define LDB(dst, b, h) _Pragma("unroll") for (int n = 0; n < 2; ++n) _Pragma("unroll") for (int k = 0; k < 2; ++k) \
;     dst[n][k] = *(const LAS bf16x8*)((LAS char*)SB(b, h) + boff + n * 2048 + k * 1024)
; #define MMA(ai, bj, At_, Bt_) do { __builtin_amdgcn_s_setprio(1); \
;     _Pragma("unroll") for (int m = 0; m < 4; ++m) _Pragma("unroll") for (int n = 0; n < 2; ++n) _Pragma("unroll") for (int k = 0; k < 2; ++k) \
;       acc[ai][bj][m][n] = __builtin_amdgcn_mfma_f32_16x16x32_bf16(Bt_[n][k], At_[m][k], acc[ai][bj][m][n], 0, 0, 0); \
;     __builtin_amdgcn_s_setprio(0); } while (0)
; #define WAIT_V(n) asm volatile("s_waitcnt vmcnt(" #n ")" ::: "memory")
; #define WAIT_L(n) asm volatile("s_waitcnt lgkmcnt(" #n ")" ::: "memory")
; #define BAR __builtin_amdgcn_s_barrier()
; #define SCHED __builtin_amdgcn_sched_barrier(0)
; __device__ __forceinline__ void gemm_phase(const bf16_t* __restrict__ A, const bf16_t* __restrict__ Bt, bf16_t* __restrict__ C, int M, int N, int K,
;                                            int ldc, const int EPI, char* smem, const int wid_u) {
;     ...
;       LDB(B0, 0, 0); SCHED; LDA(At, 0, 0); STG(SA(1, 1), a1 + hstep);
;       WAIT_L(8); BAR; WAIT_L(0); MMA(0, 0, At, B0); BAR; SCHED;
;       LDB(B1, 0, 1); STG(SB(0, 0), b2);
;       BAR; WAIT_L(0); MMA(0, 1, At, B1); BAR;
;       LDA(At, 0, 1); STG(SA(0, 0), a2);
;       BAR; WAIT_L(0); MMA(1, 0, At, B0); BAR; SCHED;
;       STG(SB(0, 1), b2 + hstep);
;       WAIT_V(6); BAR; MMA(1, 1, At, B1); BAR;
;       LDB(B0, 1, 0); SCHED; LDA(At, 1, 0); STG(SA(0, 1), a2 + hstep);
;       WAIT_L(8); BAR; WAIT_L(0); MMA(0, 0, At, B0); BAR; SCHED;
;       LDB(B1, 1, 1); STG(SB(1, 0), b3);
;       BAR; WAIT_L(0); MMA(0, 1, At, B1); BAR;
;       LDA(At, 1, 1); STG(SA(1, 0), a3);
;       BAR; WAIT_L(0); MMA(1, 0, At, B0); BAR; SCHED;
;       STG(SB(1, 1), b3 + hstep);
;       WAIT_V(6); BAR; MMA(1, 1, At, B1); BAR;
	s_add_u32 s16, s20, 0x40000
	s_addc_u32 s17, s21, 0
	s_add_i32 s50, s37, s27
	s_mov_b32 m0, s50
	v_lshl_add_u64 v[150:151], s[16:17], 0, v[130:131]
	global_load_lds_dwordx4 v[150:151], off
	s_add_i32 m0, s50, 0x2000
	v_lshl_add_u64 v[150:151], s[16:17], 0, v[128:129]
	global_load_lds_dwordx4 v[150:151], off
	s_waitcnt vmcnt(6)
	s_barrier
	v_mfma_f32_16x16x32_bf16 v[52:55], v[198:201], v[166:169], v[52:55]
	v_mfma_f32_16x16x32_bf16 v[48:51], v[206:209], v[166:169], v[48:51]
	v_mfma_f32_16x16x32_bf16 v[36:39], v[198:201], v[174:177], v[36:39]
	v_mfma_f32_16x16x32_bf16 v[32:35], v[206:209], v[174:177], v[32:35]
	v_mfma_f32_16x16x32_bf16 v[20:23], v[198:201], v[182:185], v[20:23]
	v_mfma_f32_16x16x32_bf16 v[16:19], v[206:209], v[182:185], v[16:19]
	v_mfma_f32_16x16x32_bf16 v[4:7], v[198:201], v[190:193], v[4:7]
	v_mfma_f32_16x16x32_bf16 v[0:3], v[206:209], v[190:193], v[0:3]
	v_mfma_f32_16x16x32_bf16 v[52:55], v[202:205], v[170:173], v[52:55]
	v_mfma_f32_16x16x32_bf16 v[48:51], v[210:213], v[170:173], v[48:51]
	v_mfma_f32_16x16x32_bf16 v[36:39], v[202:205], v[178:181], v[36:39]
	v_mfma_f32_16x16x32_bf16 v[32:35], v[210:213], v[178:181], v[32:35]
	v_mfma_f32_16x16x32_bf16 v[20:23], v[202:205], v[186:189], v[20:23]
	v_mfma_f32_16x16x32_bf16 v[16:19], v[210:213], v[186:189], v[16:19]
	v_mfma_f32_16x16x32_bf16 v[4:7], v[202:205], v[194:197], v[4:7]
	v_mfma_f32_16x16x32_bf16 v[0:3], v[210:213], v[194:197], v[0:3]
	s_add_i32 s50, 0, 0x18000
	v_add_u32_e32 v149, s50, v145
	s_barrier
	ds_read_b128 v[150:153], v149
	ds_read_b128 v[154:157], v149 offset:1024
	ds_read_b128 v[158:161], v149 offset:2048
	ds_read_b128 v[162:165], v149 offset:3072
	s_add_u32 s16, s22, 0x40000
	s_addc_u32 s17, s23, 0
	s_mov_b32 m0, s30
	v_lshl_add_u64 v[198:199], s[16:17], 0, v[130:131]
	ds_read_b128 v[166:169], v147 offset:32768
	ds_read_b128 v[170:173], v147 offset:33792
	ds_read_b128 v[174:177], v147 offset:34816
	ds_read_b128 v[178:181], v147 offset:35840
	ds_read_b128 v[182:185], v147 offset:36864
	ds_read_b128 v[186:189], v147 offset:37888
	ds_read_b128 v[190:193], v147 offset:38912
	ds_read_b128 v[194:197], v147 offset:39936
	global_load_lds_dwordx4 v[198:199], off
	s_mov_b32 m0, s31
	v_lshl_add_u64 v[198:199], s[16:17], 0, v[128:129]
	global_load_lds_dwordx4 v[198:199], off
	s_waitcnt lgkmcnt(8)
	s_barrier
	s_waitcnt lgkmcnt(0)
	s_waitcnt lgkmcnt(0)
	v_mfma_f32_16x16x32_bf16 v[124:127], v[150:153], v[166:169], v[124:127]
	v_mfma_f32_16x16x32_bf16 v[120:123], v[158:161], v[166:169], v[120:123]
	v_mfma_f32_16x16x32_bf16 v[108:111], v[150:153], v[174:177], v[108:111]
	v_mfma_f32_16x16x32_bf16 v[104:107], v[158:161], v[174:177], v[104:107]
	v_mfma_f32_16x16x32_bf16 v[92:95], v[150:153], v[182:185], v[92:95]
	v_mfma_f32_16x16x32_bf16 v[88:91], v[158:161], v[182:185], v[88:91]
	v_mfma_f32_16x16x32_bf16 v[76:79], v[150:153], v[190:193], v[76:79]
	v_mfma_f32_16x16x32_bf16 v[72:75], v[158:161], v[190:193], v[72:75]
	v_mfma_f32_16x16x32_bf16 v[124:127], v[154:157], v[170:173], v[124:127]
	v_mfma_f32_16x16x32_bf16 v[120:123], v[162:165], v[170:173], v[120:123]
	v_mfma_f32_16x16x32_bf16 v[108:111], v[154:157], v[178:181], v[108:111]
	v_mfma_f32_16x16x32_bf16 v[104:107], v[162:165], v[178:181], v[104:107]
	v_mfma_f32_16x16x32_bf16 v[92:95], v[154:157], v[186:189], v[92:95]
	v_mfma_f32_16x16x32_bf16 v[88:91], v[162:165], v[186:189], v[88:91]
	v_mfma_f32_16x16x32_bf16 v[76:79], v[154:157], v[194:197], v[76:79]
	v_mfma_f32_16x16x32_bf16 v[72:75], v[162:165], v[194:197], v[72:75]
	s_barrier
	s_add_i32 s22, 0, 0x1c000
	s_add_i32 s16, s50, s27
	v_add_u32_e32 v149, s22, v145
	v_lshl_add_u64 v[142:143], v[142:143], 0, s[6:7]
	s_mov_b32 m0, s16
	ds_read_b128 v[198:201], v149
	ds_read_b128 v[202:205], v149 offset:1024
	ds_read_b128 v[206:209], v149 offset:2048
	ds_read_b128 v[210:213], v149 offset:3072
	global_load_lds_dwordx4 v[142:143], off
	s_add_i32 m0, s16, 0x2000
	v_lshl_add_u64 v[142:143], v[214:215], 0, s[6:7]
	global_load_lds_dwordx4 v[142:143], off
	s_barrier
	s_waitcnt lgkmcnt(0)
	s_waitcnt lgkmcnt(0)
	v_mfma_f32_16x16x32_bf16 v[116:119], v[198:201], v[166:169], v[116:119]
	v_mfma_f32_16x16x32_bf16 v[112:115], v[206:209], v[166:169], v[112:115]
	v_mfma_f32_16x16x32_bf16 v[100:103], v[198:201], v[174:177], v[100:103]
	v_mfma_f32_16x16x32_bf16 v[96:99], v[206:209], v[174:177], v[96:99]
	v_mfma_f32_16x16x32_bf16 v[84:87], v[198:201], v[182:185], v[84:87]
	v_mfma_f32_16x16x32_bf16 v[80:83], v[206:209], v[182:185], v[80:83]
	v_mfma_f32_16x16x32_bf16 v[68:71], v[198:201], v[190:193], v[68:71]
	v_mfma_f32_16x16x32_bf16 v[64:67], v[206:209], v[190:193], v[64:67]
	v_mfma_f32_16x16x32_bf16 v[116:119], v[202:205], v[170:173], v[116:119]
	v_mfma_f32_16x16x32_bf16 v[112:115], v[210:213], v[170:173], v[112:115]
	v_mfma_f32_16x16x32_bf16 v[100:103], v[202:205], v[178:181], v[100:103]
	v_mfma_f32_16x16x32_bf16 v[96:99], v[210:213], v[178:181], v[96:99]
	v_mfma_f32_16x16x32_bf16 v[84:87], v[202:205], v[186:189], v[84:87]
	v_mfma_f32_16x16x32_bf16 v[80:83], v[210:213], v[186:189], v[80:83]
	v_mfma_f32_16x16x32_bf16 v[68:71], v[202:205], v[194:197], v[68:71]
	v_mfma_f32_16x16x32_bf16 v[64:67], v[210:213], v[194:197], v[64:67]
	s_mov_b32 m0, s34
	v_lshl_add_u64 v[142:143], v[216:217], 0, s[6:7]
	s_barrier
	ds_read_b128 v[166:169], v147 offset:49152
	ds_read_b128 v[170:173], v147 offset:50176
	ds_read_b128 v[174:177], v147 offset:51200
	ds_read_b128 v[178:181], v147 offset:52224
	ds_read_b128 v[182:185], v147 offset:53248
	ds_read_b128 v[186:189], v147 offset:54272
	ds_read_b128 v[190:193], v147 offset:55296
	ds_read_b128 v[194:197], v147 offset:56320
	global_load_lds_dwordx4 v[142:143], off
	s_mov_b32 m0, s35
	v_lshl_add_u64 v[142:143], v[218:219], 0, s[6:7]
	global_load_lds_dwordx4 v[142:143], off
	s_barrier
; #define STG(P, GB) do { const char* _gb = (GB); \
;     _Pragma("unroll") for (int _i = 0; _i < 2; ++_i) { \
;       __builtin_amdgcn_global_load_lds((const unsigned*)(_gb + voff[_i]), \
;         (LAS unsigned*)((LAS char*)(P) + ldsw + _i * 8192), 16, 0, 0); } } while (0)
; #define LDA(dst, b, h) _Pragma("unroll") for (int m = 0; m < 4; ++m) _Pragma("unroll") for (int k = 0; k < 2; ++k) \
;     dst[m][k] = *(const LAS bf16x8*)((LAS char*)SA(b, h) + aoff + m * 2048 + k * 1024)
; #define WAIT_V(n) asm volatile("s_waitcnt vmcnt(" #n ")" ::: "memory")
; #define BAR __builtin_amdgcn_s_barrier()
; __device__ __forceinline__ void gemm_phase(const bf16_t* __restrict__ A, const bf16_t* __restrict__ Bt, bf16_t* __restrict__ C, int M, int N, int K,
;                                            int ldc, const int EPI, char* smem, const int wid_u) {
;     ...
;       WAIT_V(6); BAR; MMA(1, 1, At, B1); BAR;
;       LDB(B0, 1, 0); SCHED; LDA(At, 1, 0); STG(SA(0, 1), a2 + hstep);
;       WAIT_L(8); BAR; WAIT_L(0); MMA(0, 0, At, B0); BAR; SCHED;
;       LDB(B1, 1, 1); STG(SB(1, 0), b3);
;       BAR; WAIT_L(0); MMA(0, 1, At, B1); BAR;
;       LDA(At, 1, 1); STG(SA(1, 0), a3);
;       BAR; WAIT_L(0); MMA(1, 0, At, B0); BAR; SCHED;
;       STG(SB(1, 1), b3 + hstep);
;       WAIT_V(6); BAR; MMA(1, 1, At, B1); BAR;
;     ...
;       const int brow = pm * BM, bcol = pn * BM;
; #pragma unroll
;       for (int ai = 0; ai < 2; ++ai)
; #pragma unroll
;         for (int m = 0; m < 4; ++m) {
;           const size_t row = (size_t)(brow + ai * HALF + wr * 64 + m * 16 + fr);
;           if (EPI == 0) {
; #pragma unroll
;             for (int bj = 0; bj < 2; ++bj) {
;               const f32x4 v0 = acc[ai][bj][m][0], v1 = acc[ai][bj][m][1];
;               uint4 u; u.x = cvt_pk_bf16(v0[0], v0[1]); u.y = cvt_pk_bf16(v0[2], v0[3]); u.z = cvt_pk_bf16(v1[0], v1[1]); u.w = cvt_pk_bf16(v1[2], v1[3]);
;               *(uint4*)(C + row * ldc + bcol + bj * HALF + wc * 32 + fq * 8) = u;
;             }
;           } else {
;             float o[8];
; #pragma unroll
;             for (int n = 0; n < 2; ++n) {
;               const f32x4 a = acc[ai][0][m][n], b = acc[ai][1][m][n];
; #pragma unroll
;               for (int j = 0; j < 4; ++j) o[n * 4 + j] = a[j] * __builtin_amdgcn_rcpf(1.f + __expf(-a[j])) * b[j];
;             }
;             *(uint4*)(C + row * ldc + (bcol >> 1) + wc * 32 + fq * 8) = pack8(o);
	s_waitcnt lgkmcnt(0)
	s_waitcnt lgkmcnt(0)
	v_mfma_f32_16x16x32_bf16 v[60:63], v[150:153], v[166:169], v[60:63]
	v_mfma_f32_16x16x32_bf16 v[56:59], v[158:161], v[166:169], v[56:59]
	v_mfma_f32_16x16x32_bf16 v[44:47], v[150:153], v[174:177], v[44:47]
	v_mfma_f32_16x16x32_bf16 v[40:43], v[158:161], v[174:177], v[40:43]
	v_mfma_f32_16x16x32_bf16 v[28:31], v[150:153], v[182:185], v[28:31]
	v_mfma_f32_16x16x32_bf16 v[24:27], v[158:161], v[182:185], v[24:27]
	v_mfma_f32_16x16x32_bf16 v[12:15], v[150:153], v[190:193], v[12:15]
	v_mfma_f32_16x16x32_bf16 v[8:11], v[158:161], v[190:193], v[8:11]
	v_mfma_f32_16x16x32_bf16 v[60:63], v[154:157], v[170:173], v[60:63]
	v_mfma_f32_16x16x32_bf16 v[56:59], v[162:165], v[170:173], v[56:59]
	v_mfma_f32_16x16x32_bf16 v[44:47], v[154:157], v[178:181], v[44:47]
	v_mfma_f32_16x16x32_bf16 v[40:43], v[162:165], v[178:181], v[40:43]
	v_mfma_f32_16x16x32_bf16 v[28:31], v[154:157], v[186:189], v[28:31]
	v_mfma_f32_16x16x32_bf16 v[24:27], v[162:165], v[186:189], v[24:27]
	v_mfma_f32_16x16x32_bf16 v[12:15], v[154:157], v[194:197], v[12:15]
	v_mfma_f32_16x16x32_bf16 v[8:11], v[162:165], v[194:197], v[8:11]
	s_barrier
	s_add_u32 s16, s20, 0x40080
	s_addc_u32 s17, s21, 0
	s_add_i32 s20, s22, s27
	s_mov_b32 m0, s20
	v_lshl_add_u64 v[142:143], s[16:17], 0, v[130:131]
	global_load_lds_dwordx4 v[142:143], off
	s_add_i32 m0, s20, 0x2000
	v_lshl_add_u64 v[142:143], s[16:17], 0, v[128:129]
	global_load_lds_dwordx4 v[142:143], off
	s_waitcnt vmcnt(6)
	s_barrier
	v_mfma_f32_16x16x32_bf16 v[52:55], v[198:201], v[166:169], v[52:55]
	v_mfma_f32_16x16x32_bf16 v[48:51], v[206:209], v[166:169], v[48:51]
	v_mfma_f32_16x16x32_bf16 v[36:39], v[198:201], v[174:177], v[36:39]
	v_mfma_f32_16x16x32_bf16 v[32:35], v[206:209], v[174:177], v[32:35]
	v_mfma_f32_16x16x32_bf16 v[20:23], v[198:201], v[182:185], v[20:23]
	v_mfma_f32_16x16x32_bf16 v[16:19], v[206:209], v[182:185], v[16:19]
	v_mfma_f32_16x16x32_bf16 v[4:7], v[198:201], v[190:193], v[4:7]
	v_mfma_f32_16x16x32_bf16 v[0:3], v[206:209], v[190:193], v[0:3]
	v_mfma_f32_16x16x32_bf16 v[52:55], v[202:205], v[170:173], v[52:55]
	v_mfma_f32_16x16x32_bf16 v[48:51], v[210:213], v[170:173], v[48:51]
	v_mfma_f32_16x16x32_bf16 v[36:39], v[202:205], v[178:181], v[36:39]
	v_mfma_f32_16x16x32_bf16 v[32:35], v[210:213], v[178:181], v[32:35]
	v_mfma_f32_16x16x32_bf16 v[20:23], v[202:205], v[186:189], v[20:23]
	v_mfma_f32_16x16x32_bf16 v[16:19], v[210:213], v[186:189], v[16:19]
	v_mfma_f32_16x16x32_bf16 v[4:7], v[202:205], v[194:197], v[4:7]
	v_mfma_f32_16x16x32_bf16 v[0:3], v[210:213], v[194:197], v[0:3]
	s_add_i32 s49, s49, 2
	s_add_u32 s47, s47, 0x100
	s_addc_u32 s48, s48, 0
	s_cmp_gt_u32 s49, 13
	s_mov_b64 s[16:17], s[18:19]
	s_barrier
	s_cbranch_scc0 .LBB0_145
	v_mul_f32_e32 v142, 0xbfb8aa3b, v124
	v_exp_f32_e32 v142, v142
	v_mul_f32_e32 v143, 0xbfb8aa3b, v125
	v_exp_f32_e32 v143, v143
	s_lshl_b32 s16, s40, 8
	v_add_f32_e32 v142, 1.0, v142
	v_rcp_f32_e32 v150, v142
	v_add_f32_e32 v142, 1.0, v143
	v_rcp_f32_e32 v151, v142
	s_mov_b32 s17, s9
	v_lshl_add_u32 v149, s41, 8, v144
	v_lshl_add_u64 v[142:143], v[132:133], 0, s[16:17]
	v_pk_mul_f32 v[124:125], v[124:125], v[150:151]
	v_mul_f32_e32 v150, 0xbfb8aa3b, v126
	v_mul_f32_e32 v151, 0xbfb8aa3b, v127
	v_exp_f32_e32 v150, v150
	v_exp_f32_e32 v151, v151
	v_pk_mul_f32 v[116:117], v[124:125], v[116:117]
	s_and_b64 vcc, exec, s[2:3]
	v_add_f32_e32 v124, 1.0, v150
	v_add_f32_e32 v125, 1.0, v151
	v_mul_f32_e32 v150, 0xbfb8aa3b, v120
	v_mul_f32_e32 v151, 0xbfb8aa3b, v121
	v_rcp_f32_e32 v124, v124
	v_rcp_f32_e32 v125, v125
	v_exp_f32_e32 v150, v150
	v_exp_f32_e32 v151, v151
	s_mov_b32 s41, s8
	v_pk_mul_f32 v[124:125], v[126:127], v[124:125]
	v_add_f32_e32 v126, 1.0, v150
	v_add_f32_e32 v127, 1.0, v151
	v_mul_f32_e32 v150, 0xbfb8aa3b, v122
	v_mul_f32_e32 v151, 0xbfb8aa3b, v123
	v_exp_f32_e32 v150, v150
	v_exp_f32_e32 v151, v151
	v_rcp_f32_e32 v126, v126
	v_rcp_f32_e32 v127, v127
	v_add_f32_e32 v150, 1.0, v150
	v_add_f32_e32 v151, 1.0, v151
	v_rcp_f32_e32 v150, v150
	v_rcp_f32_e32 v151, v151
	v_pk_mul_f32 v[120:121], v[120:121], v[126:127]
	v_pk_mul_f32 v[118:119], v[124:125], v[118:119]
	v_pk_mul_f32 v[120:121], v[120:121], v[112:113]
	v_pk_mul_f32 v[112:113], v[122:123], v[150:151]
	s_mov_b32 s40, s10
	v_pk_mul_f32 v[122:123], v[112:113], v[114:115]
	v_mul_f32_e32 v115, 0xbfb8aa3b, v108
	v_cvt_pk_bf16_f32 v112, v116, v117
	v_exp_f32_e32 v116, v115
	v_mul_f32_e32 v115, 0xbfb8aa3b, v109
	v_exp_f32_e32 v117, v115
	v_cvt_pk_bf16_f32 v113, v118, v119
	v_cvt_pk_bf16_f32 v114, v120, v121
	v_cvt_pk_bf16_f32 v115, v122, v123
	v_add_f32_e32 v116, 1.0, v116
	v_add_f32_e32 v117, 1.0, v117
	v_mad_i64_i32 v[118:119], s[16:17], v149, s38, v[142:143]
	v_rcp_f32_e32 v116, v116
	v_rcp_f32_e32 v117, v117
	global_store_dwordx4 v[118:119], v[112:115], off
	s_mov_b64 s[18:19], s[14:15]
	v_pk_mul_f32 v[108:109], v[108:109], v[116:117]
	v_mul_f32_e32 v112, 0xbfb8aa3b, v110
	v_mul_f32_e32 v113, 0xbfb8aa3b, v111
	v_exp_f32_e32 v112, v112
	v_exp_f32_e32 v113, v113
	v_pk_mul_f32 v[100:101], v[108:109], v[100:101]
	v_or_b32_e32 v114, 16, v149
	v_add_f32_e32 v108, 1.0, v112
	v_add_f32_e32 v109, 1.0, v113
	v_mul_f32_e32 v112, 0xbfb8aa3b, v104
	v_mul_f32_e32 v113, 0xbfb8aa3b, v105
	v_rcp_f32_e32 v108, v108
	v_rcp_f32_e32 v109, v109
	v_exp_f32_e32 v112, v112
	v_exp_f32_e32 v113, v113
	v_pk_mul_f32 v[108:109], v[110:111], v[108:109]
	v_add_f32_e32 v110, 1.0, v112
	v_add_f32_e32 v111, 1.0, v113
	v_mul_f32_e32 v112, 0xbfb8aa3b, v106
	v_mul_f32_e32 v113, 0xbfb8aa3b, v107
	v_exp_f32_e32 v112, v112
	v_exp_f32_e32 v113, v113
	v_rcp_f32_e32 v110, v110
	v_rcp_f32_e32 v111, v111
	v_add_f32_e32 v112, 1.0, v112
; __device__ __forceinline__ void gemm_phase(const bf16_t* __restrict__ A, const bf16_t* __restrict__ Bt, bf16_t* __restrict__ C, int M, int N, int K,
;                                            int ldc, const int EPI, char* smem, const int wid_u) {
;     ...
;             float o[8];
; #pragma unroll
;             for (int n = 0; n < 2; ++n) {
;               const f32x4 a = acc[ai][0][m][n], b = acc[ai][1][m][n];
; #pragma unroll
;               for (int j = 0; j < 4; ++j) o[n * 4 + j] = a[j] * __builtin_amdgcn_rcpf(1.f + __expf(-a[j])) * b[j];
;             }
;             *(uint4*)(C + row * ldc + (bcol >> 1) + wc * 32 + fq * 8) = pack8(o);
	v_add_f32_e32 v113, 1.0, v113
	v_rcp_f32_e32 v112, v112
	v_rcp_f32_e32 v113, v113
	v_pk_mul_f32 v[104:105], v[104:105], v[110:111]
	v_pk_mul_f32 v[102:103], v[108:109], v[102:103]
	v_pk_mul_f32 v[104:105], v[104:105], v[96:97]
	v_pk_mul_f32 v[96:97], v[106:107], v[112:113]
	s_nop 0
	v_pk_mul_f32 v[106:107], v[96:97], v[98:99]
	v_mul_f32_e32 v99, 0xbfb8aa3b, v92
	v_cvt_pk_bf16_f32 v96, v100, v101
	v_exp_f32_e32 v100, v99
	v_mul_f32_e32 v99, 0xbfb8aa3b, v93
	v_exp_f32_e32 v101, v99
	v_cvt_pk_bf16_f32 v97, v102, v103
	v_cvt_pk_bf16_f32 v98, v104, v105
	v_cvt_pk_bf16_f32 v99, v106, v107
	v_add_f32_e32 v100, 1.0, v100
	v_add_f32_e32 v101, 1.0, v101
	v_mad_i64_i32 v[102:103], s[16:17], v114, s38, v[142:143]
	v_rcp_f32_e32 v100, v100
	v_rcp_f32_e32 v101, v101
	global_store_dwordx4 v[102:103], v[96:99], off
	v_pk_mul_f32 v[92:93], v[92:93], v[100:101]
	s_nop 0
	v_mul_f32_e32 v96, 0xbfb8aa3b, v94
	v_mul_f32_e32 v97, 0xbfb8aa3b, v95
	v_exp_f32_e32 v96, v96
	v_exp_f32_e32 v97, v97
	v_pk_mul_f32 v[84:85], v[92:93], v[84:85]
	v_or_b32_e32 v98, 32, v149
	v_add_f32_e32 v92, 1.0, v96
	v_add_f32_e32 v93, 1.0, v97
	v_mul_f32_e32 v96, 0xbfb8aa3b, v88
	v_mul_f32_e32 v97, 0xbfb8aa3b, v89
	v_rcp_f32_e32 v92, v92
	v_rcp_f32_e32 v93, v93
	v_exp_f32_e32 v96, v96
	v_exp_f32_e32 v97, v97
	v_pk_mul_f32 v[92:93], v[94:95], v[92:93]
	v_add_f32_e32 v94, 1.0, v96
	v_add_f32_e32 v95, 1.0, v97
	v_mul_f32_e32 v96, 0xbfb8aa3b, v90
	v_mul_f32_e32 v97, 0xbfb8aa3b, v91
	v_exp_f32_e32 v96, v96
	v_exp_f32_e32 v97, v97
	v_rcp_f32_e32 v94, v94
	v_rcp_f32_e32 v95, v95
	v_add_f32_e32 v96, 1.0, v96
	v_add_f32_e32 v97, 1.0, v97
	v_rcp_f32_e32 v96, v96
	v_rcp_f32_e32 v97, v97
	v_pk_mul_f32 v[88:89], v[88:89], v[94:95]
	v_pk_mul_f32 v[86:87], v[92:93], v[86:87]
	v_pk_mul_f32 v[88:89], v[88:89], v[80:81]
	v_pk_mul_f32 v[80:81], v[90:91], v[96:97]
	s_nop 0
	v_pk_mul_f32 v[90:91], v[80:81], v[82:83]
	v_mul_f32_e32 v83, 0xbfb8aa3b, v76
	v_cvt_pk_bf16_f32 v80, v84, v85
	v_exp_f32_e32 v84, v83
	v_mul_f32_e32 v83, 0xbfb8aa3b, v77
	v_exp_f32_e32 v85, v83
	v_cvt_pk_bf16_f32 v81, v86, v87
	v_cvt_pk_bf16_f32 v82, v88, v89
	v_cvt_pk_bf16_f32 v83, v90, v91
	v_add_f32_e32 v84, 1.0, v84
	v_add_f32_e32 v85, 1.0, v85
	v_mad_i64_i32 v[86:87], s[16:17], v98, s38, v[142:143]
	v_rcp_f32_e32 v84, v84
	v_rcp_f32_e32 v85, v85
	global_store_dwordx4 v[86:87], v[80:83], off
	v_pk_mul_f32 v[76:77], v[76:77], v[84:85]
	s_nop 0
	v_mul_f32_e32 v80, 0xbfb8aa3b, v78
	v_mul_f32_e32 v81, 0xbfb8aa3b, v79
	v_exp_f32_e32 v80, v80
	v_exp_f32_e32 v81, v81
	v_pk_mul_f32 v[68:69], v[76:77], v[68:69]
	v_or_b32_e32 v82, 48, v149
	v_add_f32_e32 v76, 1.0, v80
	v_add_f32_e32 v77, 1.0, v81
	v_mul_f32_e32 v80, 0xbfb8aa3b, v72
	v_mul_f32_e32 v81, 0xbfb8aa3b, v73
	v_rcp_f32_e32 v76, v76
	v_rcp_f32_e32 v77, v77
	v_exp_f32_e32 v80, v80
	v_exp_f32_e32 v81, v81
	v_pk_mul_f32 v[76:77], v[78:79], v[76:77]
	v_add_f32_e32 v78, 1.0, v80
	v_add_f32_e32 v79, 1.0, v81
	v_mul_f32_e32 v80, 0xbfb8aa3b, v74
	v_mul_f32_e32 v81, 0xbfb8aa3b, v75
	v_exp_f32_e32 v80, v80
	v_exp_f32_e32 v81, v81
	v_rcp_f32_e32 v78, v78
	v_rcp_f32_e32 v79, v79
	v_add_f32_e32 v80, 1.0, v80
	v_add_f32_e32 v81, 1.0, v81
	v_rcp_f32_e32 v80, v80
	v_rcp_f32_e32 v81, v81
	v_pk_mul_f32 v[72:73], v[72:73], v[78:79]
	v_pk_mul_f32 v[70:71], v[76:77], v[70:71]
	v_pk_mul_f32 v[72:73], v[72:73], v[64:65]
	v_pk_mul_f32 v[64:65], v[74:75], v[80:81]
	s_nop 0
	v_pk_mul_f32 v[74:75], v[64:65], v[66:67]
	v_mul_f32_e32 v67, 0xbfb8aa3b, v60
	v_cvt_pk_bf16_f32 v64, v68, v69
	v_exp_f32_e32 v68, v67
	v_mul_f32_e32 v67, 0xbfb8aa3b, v61
	v_exp_f32_e32 v69, v67
	v_cvt_pk_bf16_f32 v65, v70, v71
	v_cvt_pk_bf16_f32 v66, v72, v73
	v_cvt_pk_bf16_f32 v67, v74, v75
	v_add_f32_e32 v68, 1.0, v68
	v_add_f32_e32 v69, 1.0, v69
	v_mad_i64_i32 v[70:71], s[16:17], v82, s38, v[142:143]
	v_rcp_f32_e32 v68, v68
	v_rcp_f32_e32 v69, v69
	global_store_dwordx4 v[70:71], v[64:67], off
	v_pk_mul_f32 v[60:61], v[60:61], v[68:69]
	s_nop 0
	v_mul_f32_e32 v64, 0xbfb8aa3b, v62
	v_mul_f32_e32 v65, 0xbfb8aa3b, v63
	v_exp_f32_e32 v64, v64
	v_exp_f32_e32 v65, v65
	v_pk_mul_f32 v[52:53], v[60:61], v[52:53]
	v_add_u32_e32 v66, 0x80, v149
	v_add_f32_e32 v60, 1.0, v64
	v_add_f32_e32 v61, 1.0, v65
	v_mul_f32_e32 v64, 0xbfb8aa3b, v56
	v_mul_f32_e32 v65, 0xbfb8aa3b, v57
	v_rcp_f32_e32 v60, v60
	v_rcp_f32_e32 v61, v61
	v_exp_f32_e32 v64, v64
	v_exp_f32_e32 v65, v65
	v_pk_mul_f32 v[60:61], v[62:63], v[60:61]
	v_add_f32_e32 v62, 1.0, v64
	v_add_f32_e32 v63, 1.0, v65
	v_mul_f32_e32 v64, 0xbfb8aa3b, v58
	v_mul_f32_e32 v65, 0xbfb8aa3b, v59
	v_exp_f32_e32 v64, v64
	v_exp_f32_e32 v65, v65
	v_rcp_f32_e32 v62, v62
	v_rcp_f32_e32 v63, v63
	v_add_f32_e32 v64, 1.0, v64
	v_add_f32_e32 v65, 1.0, v65
	v_rcp_f32_e32 v64, v64
	v_rcp_f32_e32 v65, v65
	v_pk_mul_f32 v[56:57], v[56:57], v[62:63]
	v_pk_mul_f32 v[54:55], v[60:61], v[54:55]
	v_pk_mul_f32 v[56:57], v[56:57], v[48:49]
	v_pk_mul_f32 v[48:49], v[58:59], v[64:65]
	s_nop 0
	v_pk_mul_f32 v[58:59], v[48:49], v[50:51]
; #define WAIT_V(n) asm volatile("s_waitcnt vmcnt(" #n ")" ::: "memory")
; #define BAR __builtin_amdgcn_s_barrier()
; __device__ __forceinline__ void gemm_phase(const bf16_t* __restrict__ A, const bf16_t* __restrict__ Bt, bf16_t* __restrict__ C, int M, int N, int K,
;                                            int ldc, const int EPI, char* smem, const int wid_u) {
;     ...
;         for (int m = 0; m < 4; ++m) {
;           const size_t row = (size_t)(brow + ai * HALF + wr * 64 + m * 16 + fr);
;           if (EPI == 0) {
; #pragma unroll
;             for (int bj = 0; bj < 2; ++bj) {
;               const f32x4 v0 = acc[ai][bj][m][0], v1 = acc[ai][bj][m][1];
;               uint4 u; u.x = cvt_pk_bf16(v0[0], v0[1]); u.y = cvt_pk_bf16(v0[2], v0[3]); u.z = cvt_pk_bf16(v1[0], v1[1]); u.w = cvt_pk_bf16(v1[2], v1[3]);
;               *(uint4*)(C + row * ldc + bcol + bj * HALF + wc * 32 + fq * 8) = u;
;             }
;           } else {
;             float o[8];
; #pragma unroll
;             for (int n = 0; n < 2; ++n) {
;               const f32x4 a = acc[ai][0][m][n], b = acc[ai][1][m][n];
; #pragma unroll
;               for (int j = 0; j < 4; ++j) o[n * 4 + j] = a[j] * __builtin_amdgcn_rcpf(1.f + __expf(-a[j])) * b[j];
;             }
;             *(uint4*)(C + row * ldc + (bcol >> 1) + wc * 32 + fq * 8) = pack8(o);
;           }
;         }
;     }
;     if (!has_next) break;
; #pragma unroll
;     for (int a = 0; a < 2; ++a)
; #pragma unroll
;       for (int b = 0; b < 2; ++b)
; #pragma unroll
;         for (int m = 0; m < 4; ++m)
; #pragma unroll
;           for (int n = 0; n < 2; ++n) acc[a][b][m][n] = (f32x4){0.f, 0.f, 0.f, 0.f};
;     pm = npm; pn = npn; cA = nA; cB = nB; ++ui;
;   }
;   WAIT_V(0);
;   if (wr == 0) BAR;
;   BAR;
	v_mul_f32_e32 v51, 0xbfb8aa3b, v44
	v_cvt_pk_bf16_f32 v48, v52, v53
	v_exp_f32_e32 v52, v51
	v_mul_f32_e32 v51, 0xbfb8aa3b, v45
	v_exp_f32_e32 v53, v51
	v_cvt_pk_bf16_f32 v49, v54, v55
	v_cvt_pk_bf16_f32 v50, v56, v57
	v_cvt_pk_bf16_f32 v51, v58, v59
	v_add_f32_e32 v52, 1.0, v52
	v_add_f32_e32 v53, 1.0, v53
	v_mad_i64_i32 v[54:55], s[16:17], v66, s38, v[142:143]
	v_rcp_f32_e32 v52, v52
	v_rcp_f32_e32 v53, v53
	global_store_dwordx4 v[54:55], v[48:51], off
	v_pk_mul_f32 v[44:45], v[44:45], v[52:53]
	s_nop 0
	v_mul_f32_e32 v48, 0xbfb8aa3b, v46
	v_mul_f32_e32 v49, 0xbfb8aa3b, v47
	v_exp_f32_e32 v48, v48
	v_exp_f32_e32 v49, v49
	v_pk_mul_f32 v[36:37], v[44:45], v[36:37]
	v_add_u32_e32 v50, 0x90, v149
	v_add_f32_e32 v44, 1.0, v48
	v_add_f32_e32 v45, 1.0, v49
	v_mul_f32_e32 v48, 0xbfb8aa3b, v40
	v_mul_f32_e32 v49, 0xbfb8aa3b, v41
	v_rcp_f32_e32 v44, v44
	v_rcp_f32_e32 v45, v45
	v_exp_f32_e32 v48, v48
	v_exp_f32_e32 v49, v49
	v_pk_mul_f32 v[44:45], v[46:47], v[44:45]
	v_add_f32_e32 v46, 1.0, v48
	v_add_f32_e32 v47, 1.0, v49
	v_mul_f32_e32 v48, 0xbfb8aa3b, v42
	v_mul_f32_e32 v49, 0xbfb8aa3b, v43
	v_exp_f32_e32 v48, v48
	v_exp_f32_e32 v49, v49
	v_rcp_f32_e32 v46, v46
	v_rcp_f32_e32 v47, v47
	v_add_f32_e32 v48, 1.0, v48
	v_add_f32_e32 v49, 1.0, v49
	v_rcp_f32_e32 v48, v48
	v_rcp_f32_e32 v49, v49
	v_pk_mul_f32 v[40:41], v[40:41], v[46:47]
	v_pk_mul_f32 v[38:39], v[44:45], v[38:39]
	v_pk_mul_f32 v[40:41], v[40:41], v[32:33]
	v_pk_mul_f32 v[32:33], v[42:43], v[48:49]
	s_nop 0
	v_pk_mul_f32 v[42:43], v[32:33], v[34:35]
	v_mul_f32_e32 v35, 0xbfb8aa3b, v28
	v_cvt_pk_bf16_f32 v32, v36, v37
	v_exp_f32_e32 v36, v35
	v_mul_f32_e32 v35, 0xbfb8aa3b, v29
	v_exp_f32_e32 v37, v35
	v_cvt_pk_bf16_f32 v33, v38, v39
	v_cvt_pk_bf16_f32 v34, v40, v41
	v_cvt_pk_bf16_f32 v35, v42, v43
	v_add_f32_e32 v36, 1.0, v36
	v_add_f32_e32 v37, 1.0, v37
	v_mad_i64_i32 v[38:39], s[16:17], v50, s38, v[142:143]
	v_rcp_f32_e32 v36, v36
	v_rcp_f32_e32 v37, v37
	global_store_dwordx4 v[38:39], v[32:35], off
	v_pk_mul_f32 v[28:29], v[28:29], v[36:37]
	s_nop 0
	v_mul_f32_e32 v32, 0xbfb8aa3b, v30
	v_mul_f32_e32 v33, 0xbfb8aa3b, v31
	v_exp_f32_e32 v32, v32
	v_exp_f32_e32 v33, v33
	v_pk_mul_f32 v[20:21], v[28:29], v[20:21]
	v_add_u32_e32 v34, 0xa0, v149
	v_add_f32_e32 v28, 1.0, v32
	v_add_f32_e32 v29, 1.0, v33
	v_mul_f32_e32 v32, 0xbfb8aa3b, v24
	v_mul_f32_e32 v33, 0xbfb8aa3b, v25
	v_rcp_f32_e32 v28, v28
	v_rcp_f32_e32 v29, v29
	v_exp_f32_e32 v32, v32
	v_exp_f32_e32 v33, v33
	v_pk_mul_f32 v[28:29], v[30:31], v[28:29]
	v_add_f32_e32 v30, 1.0, v32
	v_add_f32_e32 v31, 1.0, v33
	v_mul_f32_e32 v32, 0xbfb8aa3b, v26
	v_mul_f32_e32 v33, 0xbfb8aa3b, v27
	v_exp_f32_e32 v32, v32
	v_exp_f32_e32 v33, v33
	v_rcp_f32_e32 v30, v30
	v_rcp_f32_e32 v31, v31
	v_add_f32_e32 v32, 1.0, v32
	v_add_f32_e32 v33, 1.0, v33
	v_rcp_f32_e32 v32, v32
	v_rcp_f32_e32 v33, v33
	v_pk_mul_f32 v[24:25], v[24:25], v[30:31]
	v_pk_mul_f32 v[22:23], v[28:29], v[22:23]
	v_pk_mul_f32 v[24:25], v[24:25], v[16:17]
	v_pk_mul_f32 v[16:17], v[26:27], v[32:33]
	s_nop 0
	v_pk_mul_f32 v[26:27], v[16:17], v[18:19]
	v_mul_f32_e32 v19, 0xbfb8aa3b, v12
	v_cvt_pk_bf16_f32 v16, v20, v21
	v_exp_f32_e32 v20, v19
	v_mul_f32_e32 v19, 0xbfb8aa3b, v13
	v_exp_f32_e32 v21, v19
	v_cvt_pk_bf16_f32 v17, v22, v23
	v_cvt_pk_bf16_f32 v18, v24, v25
	v_cvt_pk_bf16_f32 v19, v26, v27
	v_add_f32_e32 v20, 1.0, v20
	v_add_f32_e32 v21, 1.0, v21
	v_mad_i64_i32 v[22:23], s[16:17], v34, s38, v[142:143]
	v_rcp_f32_e32 v20, v20
	v_rcp_f32_e32 v21, v21
	global_store_dwordx4 v[22:23], v[16:19], off
	v_pk_mul_f32 v[12:13], v[12:13], v[20:21]
	s_nop 0
	v_mul_f32_e32 v16, 0xbfb8aa3b, v14
	v_mul_f32_e32 v17, 0xbfb8aa3b, v15
	v_exp_f32_e32 v16, v16
	v_exp_f32_e32 v17, v17
	v_pk_mul_f32 v[4:5], v[12:13], v[4:5]
	v_add_u32_e32 v18, 0xb0, v149
	v_add_f32_e32 v12, 1.0, v16
	v_add_f32_e32 v13, 1.0, v17
	v_mul_f32_e32 v16, 0xbfb8aa3b, v8
	v_mul_f32_e32 v17, 0xbfb8aa3b, v9
	v_rcp_f32_e32 v12, v12
	v_rcp_f32_e32 v13, v13
	v_exp_f32_e32 v16, v16
	v_exp_f32_e32 v17, v17
	v_pk_mul_f32 v[12:13], v[14:15], v[12:13]
	v_add_f32_e32 v14, 1.0, v16
	v_add_f32_e32 v15, 1.0, v17
	v_mul_f32_e32 v16, 0xbfb8aa3b, v10
	v_mul_f32_e32 v17, 0xbfb8aa3b, v11
	v_exp_f32_e32 v16, v16
	v_exp_f32_e32 v17, v17
	v_rcp_f32_e32 v14, v14
	v_rcp_f32_e32 v15, v15
	v_add_f32_e32 v16, 1.0, v16
	v_add_f32_e32 v17, 1.0, v17
	v_rcp_f32_e32 v16, v16
	v_rcp_f32_e32 v17, v17
	v_pk_mul_f32 v[8:9], v[8:9], v[14:15]
	v_pk_mul_f32 v[6:7], v[12:13], v[6:7]
	v_pk_mul_f32 v[8:9], v[8:9], v[0:1]
	v_pk_mul_f32 v[0:1], v[10:11], v[16:17]
	s_nop 0
	v_pk_mul_f32 v[10:11], v[0:1], v[2:3]
	v_cvt_pk_bf16_f32 v0, v4, v5
	v_mad_i64_i32 v[4:5], s[16:17], v18, s38, v[142:143]
	v_cvt_pk_bf16_f32 v1, v6, v7
	v_cvt_pk_bf16_f32 v2, v8, v9
	v_cvt_pk_bf16_f32 v3, v10, v11
	s_mov_b64 s[16:17], s[12:13]
	global_store_dwordx4 v[4:5], v[0:3], off
	s_cbranch_vccz .LBB0_142
	s_waitcnt vmcnt(0)
	s_cmpk_gt_u32 s24, 0xff
	s_cbranch_scc1 .LBB0_149
	s_barrier

; #define STG(P, GB) do { const char* _gb = (GB); \
;     _Pragma("unroll") for (int _i = 0; _i < 2; ++_i) { \
;       __builtin_amdgcn_global_load_lds((const unsigned*)(_gb + voff[_i]), \
;         (LAS unsigned*)((LAS char*)(P) + ldsw + _i * 8192), 16, 0, 0); } } while (0)
; #define LDA(dst, b, h) _Pragma("unroll") for (int m = 0; m < 4; ++m) _Pragma("unroll") for (int k = 0; k < 2; ++k) \
;     dst[m][k] = *(const LAS bf16x8*)((LAS char*)SA(b, h) + aoff + m * 2048 + k * 1024)
; #define LDB(dst, b, h) _Pragma("unroll") for (int n = 0; n < 2; ++n) _Pragma("unroll") for (int k = 0; k < 2; ++k) \
;     dst[n][k] = *(const LAS bf16x8*)((LAS char*)SB(b, h) + boff + n * 2048 + k * 1024)
; #define MMA(ai, bj, At_, Bt_) do { __builtin_amdgcn_s_setprio(1); \
;     _Pragma("unroll") for (int m = 0; m < 4; ++m) _Pragma("unroll") for (int n = 0; n < 2; ++n) _Pragma("unroll") for (int k = 0; k < 2; ++k) \
;       acc[ai][bj][m][n] = __builtin_amdgcn_mfma_f32_16x16x32_bf16(Bt_[n][k], At_[m][k], acc[ai][bj][m][n], 0, 0, 0); \
;     __builtin_amdgcn_s_setprio(0); } while (0)
; #define WAIT_V(n) asm volatile("s_waitcnt vmcnt(" #n ")" ::: "memory")
; #define WAIT_L(n) asm volatile("s_waitcnt lgkmcnt(" #n ")" ::: "memory")
; #define BAR __builtin_amdgcn_s_barrier()
; #define SCHED __builtin_amdgcn_sched_barrier(0)
; __device__ __forceinline__ void gemm_phase(const bf16_t* __restrict__ A, const bf16_t* __restrict__ Bt, bf16_t* __restrict__ C, int M, int N, int K,
;                                            int ldc, const int EPI, char* smem, const int wid_u) {
;     ...
;       LDB(B0, 0, 0); SCHED; LDA(At, 0, 0); STG(SA(1, 1), a1 + hstep);
;       WAIT_L(8); BAR; WAIT_L(0); MMA(0, 0, At, B0); BAR; SCHED;
;       LDB(B1, 0, 1); STG(SB(0, 0), b2);
;       BAR; WAIT_L(0); MMA(0, 1, At, B1); BAR;
;       LDA(At, 0, 1); STG(SA(0, 0), a2);
;       BAR; WAIT_L(0); MMA(1, 0, At, B0); BAR; SCHED;
;       STG(SB(0, 1), b2 + hstep);
;       WAIT_V(6); BAR; MMA(1, 1, At, B1); BAR;
;       LDB(B0, 1, 0); SCHED; LDA(At, 1, 0); STG(SA(0, 1), a2 + hstep);
;       WAIT_L(8); BAR; WAIT_L(0); MMA(0, 0, At, B0); BAR; SCHED;
;       LDB(B1, 1, 1); STG(SB(1, 0), b3);
;       BAR; WAIT_L(0); MMA(0, 1, At, B1); BAR;
;       LDA(At, 1, 1); STG(SA(1, 0), a3);
;       BAR; WAIT_L(0); MMA(1, 0, At, B0); BAR; SCHED;
;       STG(SB(1, 1), b3 + hstep);
;       WAIT_V(6); BAR; MMA(1, 1, At, B1); BAR;
.LBB0_213:
	ds_read_b128 v[148:151], v143
	ds_read_b128 v[152:155], v143 offset:1024
	ds_read_b128 v[156:159], v143 offset:2048
	ds_read_b128 v[160:163], v143 offset:3072
	s_add_u32 s16, s14, 0x100
	s_addc_u32 s17, s15, 0
	s_cmp_eq_u32 s53, 40
	s_cselect_b32 s21, s5, s17
	s_cselect_b32 s20, s4, s16
	s_cselect_b32 s19, s7, s52
	s_cselect_b32 s18, s6, s51
	s_mov_b32 m0, s36
	v_lshl_add_u64 v[196:197], s[14:15], 0, v[136:137]
	ds_read_b128 v[164:167], v144
	ds_read_b128 v[168:171], v144 offset:1024
	ds_read_b128 v[172:175], v144 offset:2048
	ds_read_b128 v[176:179], v144 offset:3072
	ds_read_b128 v[180:183], v144 offset:4096
	ds_read_b128 v[184:187], v144 offset:5120
	ds_read_b128 v[188:191], v144 offset:6144
	ds_read_b128 v[192:195], v144 offset:7168
	global_load_lds_dwordx4 v[196:197], off
	s_mov_b32 m0, s37
	v_lshl_add_u64 v[196:197], s[14:15], 0, v[134:135]
	global_load_lds_dwordx4 v[196:197], off
	s_waitcnt lgkmcnt(8)
	s_barrier
	s_waitcnt lgkmcnt(0)
	s_waitcnt lgkmcnt(0)
	v_mfma_f32_16x16x32_bf16 v[124:127], v[148:151], v[164:167], v[124:127]
	v_mfma_f32_16x16x32_bf16 v[120:123], v[156:159], v[164:167], v[120:123]
	v_mfma_f32_16x16x32_bf16 v[116:119], v[148:151], v[172:175], v[116:119]
	v_mfma_f32_16x16x32_bf16 v[112:115], v[156:159], v[172:175], v[112:115]
	v_mfma_f32_16x16x32_bf16 v[100:103], v[148:151], v[180:183], v[100:103]
	v_mfma_f32_16x16x32_bf16 v[96:99], v[156:159], v[180:183], v[96:99]
	v_mfma_f32_16x16x32_bf16 v[84:87], v[148:151], v[188:191], v[84:87]
	v_mfma_f32_16x16x32_bf16 v[80:83], v[156:159], v[188:191], v[80:83]
	v_mfma_f32_16x16x32_bf16 v[124:127], v[152:155], v[168:171], v[124:127]
	v_mfma_f32_16x16x32_bf16 v[120:123], v[160:163], v[168:171], v[120:123]
	v_mfma_f32_16x16x32_bf16 v[116:119], v[152:155], v[176:179], v[116:119]
	v_mfma_f32_16x16x32_bf16 v[112:115], v[160:163], v[176:179], v[112:115]
	v_mfma_f32_16x16x32_bf16 v[100:103], v[152:155], v[184:187], v[100:103]
	v_mfma_f32_16x16x32_bf16 v[96:99], v[160:163], v[184:187], v[96:99]
	v_mfma_f32_16x16x32_bf16 v[84:87], v[152:155], v[192:195], v[84:87]
	v_mfma_f32_16x16x32_bf16 v[80:83], v[160:163], v[192:195], v[80:83]
	s_barrier
	s_mov_b32 m0, s38
	v_lshl_add_u64 v[212:213], s[18:19], 0, v[130:131]
	ds_read_b128 v[196:199], v145
	ds_read_b128 v[200:203], v145 offset:1024
	ds_read_b128 v[204:207], v145 offset:2048
	ds_read_b128 v[208:211], v145 offset:3072
	global_load_lds_dwordx4 v[212:213], off
	s_mov_b32 m0, s39
	v_lshl_add_u64 v[214:215], s[18:19], 0, v[128:129]
	global_load_lds_dwordx4 v[214:215], off
	s_barrier
	s_waitcnt lgkmcnt(0)
	s_waitcnt lgkmcnt(0)
	v_mfma_f32_16x16x32_bf16 v[108:111], v[196:199], v[164:167], v[108:111]
	v_mfma_f32_16x16x32_bf16 v[104:107], v[204:207], v[164:167], v[104:107]
	v_mfma_f32_16x16x32_bf16 v[92:95], v[196:199], v[172:175], v[92:95]
	v_mfma_f32_16x16x32_bf16 v[88:91], v[204:207], v[172:175], v[88:91]
	v_mfma_f32_16x16x32_bf16 v[76:79], v[196:199], v[180:183], v[76:79]
	v_mfma_f32_16x16x32_bf16 v[72:75], v[204:207], v[180:183], v[72:75]
	v_mfma_f32_16x16x32_bf16 v[68:71], v[196:199], v[188:191], v[68:71]
	v_mfma_f32_16x16x32_bf16 v[64:67], v[204:207], v[188:191], v[64:67]
	v_mfma_f32_16x16x32_bf16 v[108:111], v[200:203], v[168:171], v[108:111]
	v_mfma_f32_16x16x32_bf16 v[104:107], v[208:211], v[168:171], v[104:107]
	v_mfma_f32_16x16x32_bf16 v[92:95], v[200:203], v[176:179], v[92:95]
	v_mfma_f32_16x16x32_bf16 v[88:91], v[208:211], v[176:179], v[88:91]
	v_mfma_f32_16x16x32_bf16 v[76:79], v[200:203], v[184:187], v[76:79]
	v_mfma_f32_16x16x32_bf16 v[72:75], v[208:211], v[184:187], v[72:75]
	v_mfma_f32_16x16x32_bf16 v[68:71], v[200:203], v[192:195], v[68:71]
	v_mfma_f32_16x16x32_bf16 v[64:67], v[208:211], v[192:195], v[64:67]
	s_mov_b32 m0, s28
	v_lshl_add_u64 v[216:217], s[20:21], 0, v[130:131]
	s_barrier
	ds_read_b128 v[164:167], v144 offset:16384
	ds_read_b128 v[168:171], v144 offset:17408
	ds_read_b128 v[172:175], v144 offset:18432
	ds_read_b128 v[176:179], v144 offset:19456
	ds_read_b128 v[180:183], v144 offset:20480
	ds_read_b128 v[184:187], v144 offset:21504
	ds_read_b128 v[188:191], v144 offset:22528
	ds_read_b128 v[192:195], v144 offset:23552
	global_load_lds_dwordx4 v[216:217], off
	s_mov_b32 m0, s29
	v_lshl_add_u64 v[218:219], s[20:21], 0, v[128:129]
	global_load_lds_dwordx4 v[218:219], off
	s_barrier
	s_waitcnt lgkmcnt(0)
	s_waitcnt lgkmcnt(0)
	v_mfma_f32_16x16x32_bf16 v[60:63], v[148:151], v[164:167], v[60:63]
	v_mfma_f32_16x16x32_bf16 v[56:59], v[156:159], v[164:167], v[56:59]
	v_mfma_f32_16x16x32_bf16 v[52:55], v[148:151], v[172:175], v[52:55]
	v_mfma_f32_16x16x32_bf16 v[48:51], v[156:159], v[172:175], v[48:51]
	v_mfma_f32_16x16x32_bf16 v[36:39], v[148:151], v[180:183], v[36:39]
	v_mfma_f32_16x16x32_bf16 v[32:35], v[156:159], v[180:183], v[32:35]
	v_mfma_f32_16x16x32_bf16 v[20:23], v[148:151], v[188:191], v[20:23]
	v_mfma_f32_16x16x32_bf16 v[16:19], v[156:159], v[188:191], v[16:19]
	v_mfma_f32_16x16x32_bf16 v[60:63], v[152:155], v[168:171], v[60:63]
	v_mfma_f32_16x16x32_bf16 v[56:59], v[160:163], v[168:171], v[56:59]
	v_mfma_f32_16x16x32_bf16 v[52:55], v[152:155], v[176:179], v[52:55]
	v_mfma_f32_16x16x32_bf16 v[48:51], v[160:163], v[176:179], v[48:51]
	v_mfma_f32_16x16x32_bf16 v[36:39], v[152:155], v[184:187], v[36:39]
	v_mfma_f32_16x16x32_bf16 v[32:35], v[160:163], v[184:187], v[32:35]
	v_mfma_f32_16x16x32_bf16 v[20:23], v[152:155], v[192:195], v[20:23]
	v_mfma_f32_16x16x32_bf16 v[16:19], v[160:163], v[192:195], v[16:19]
	s_barrier
	s_add_u32 s14, s18, 0xb0000
	s_addc_u32 s15, s19, 0
	s_mov_b32 m0, s40
	v_lshl_add_u64 v[148:149], s[14:15], 0, v[130:131]
	global_load_lds_dwordx4 v[148:149], off
	s_mov_b32 m0, s41
	v_lshl_add_u64 v[148:149], s[14:15], 0, v[128:129]
	global_load_lds_dwordx4 v[148:149], off
	s_waitcnt vmcnt(6)
	s_barrier
; #define STG(P, GB) do { const char* _gb = (GB); \
;     _Pragma("unroll") for (int _i = 0; _i < 2; ++_i) { \
;       __builtin_amdgcn_global_load_lds((const unsigned*)(_gb + voff[_i]), \
;         (LAS unsigned*)((LAS char*)(P) + ldsw + _i * 8192), 16, 0, 0); } } while (0)
; #define LDA(dst, b, h) _Pragma("unroll") for (int m = 0; m < 4; ++m) _Pragma("unroll") for (int k = 0; k < 2; ++k) \
;     dst[m][k] = *(const LAS bf16x8*)((LAS char*)SA(b, h) + aoff + m * 2048 + k * 1024)
; #define LDB(dst, b, h) _Pragma("unroll") for (int n = 0; n < 2; ++n) _Pragma("unroll") for (int k = 0; k < 2; ++k) \
;     dst[n][k] = *(const LAS bf16x8*)((LAS char*)SB(b, h) + boff + n * 2048 + k * 1024)
; #define MMA(ai, bj, At_, Bt_) do { __builtin_amdgcn_s_setprio(1); \
;     _Pragma("unroll") for (int m = 0; m < 4; ++m) _Pragma("unroll") for (int n = 0; n < 2; ++n) _Pragma("unroll") for (int k = 0; k < 2; ++k) \
;       acc[ai][bj][m][n] = __builtin_amdgcn_mfma_f32_16x16x32_bf16(Bt_[n][k], At_[m][k], acc[ai][bj][m][n], 0, 0, 0); \
;     __builtin_amdgcn_s_setprio(0); } while (0)
; #define WAIT_V(n) asm volatile("s_waitcnt vmcnt(" #n ")" ::: "memory")
; #define WAIT_L(n) asm volatile("s_waitcnt lgkmcnt(" #n ")" ::: "memory")
; #define BAR __builtin_amdgcn_s_barrier()
; #define SCHED __builtin_amdgcn_sched_barrier(0)
; __device__ __forceinline__ void gemm_phase(const bf16_t* __restrict__ A, const bf16_t* __restrict__ Bt, bf16_t* __restrict__ C, int M, int N, int K,
;                                            int ldc, const int EPI, char* smem, const int wid_u) {
;     ...
;       LDB(B0, 0, 0); SCHED; LDA(At, 0, 0); STG(SA(1, 1), a1 + hstep);
;       WAIT_L(8); BAR; WAIT_L(0); MMA(0, 0, At, B0); BAR; SCHED;
;       LDB(B1, 0, 1); STG(SB(0, 0), b2);
;       BAR; WAIT_L(0); MMA(0, 1, At, B1); BAR;
;       LDA(At, 0, 1); STG(SA(0, 0), a2);
;       BAR; WAIT_L(0); MMA(1, 0, At, B0); BAR; SCHED;
;       STG(SB(0, 1), b2 + hstep);
;       WAIT_V(6); BAR; MMA(1, 1, At, B1); BAR;
;       LDB(B0, 1, 0); SCHED; LDA(At, 1, 0); STG(SA(0, 1), a2 + hstep);
;       WAIT_L(8); BAR; WAIT_L(0); MMA(0, 0, At, B0); BAR; SCHED;
;       LDB(B1, 1, 1); STG(SB(1, 0), b3);
;       BAR; WAIT_L(0); MMA(0, 1, At, B1); BAR;
;       LDA(At, 1, 1); STG(SA(1, 0), a3);
;       BAR; WAIT_L(0); MMA(1, 0, At, B0); BAR; SCHED;
;       STG(SB(1, 1), b3 + hstep);
;       WAIT_V(6); BAR; MMA(1, 1, At, B1); BAR;
	v_mfma_f32_16x16x32_bf16 v[44:47], v[196:199], v[164:167], v[44:47]
	v_mfma_f32_16x16x32_bf16 v[40:43], v[204:207], v[164:167], v[40:43]
	v_mfma_f32_16x16x32_bf16 v[28:31], v[196:199], v[172:175], v[28:31]
	v_mfma_f32_16x16x32_bf16 v[24:27], v[204:207], v[172:175], v[24:27]
	v_mfma_f32_16x16x32_bf16 v[12:15], v[196:199], v[180:183], v[12:15]
	v_mfma_f32_16x16x32_bf16 v[8:11], v[204:207], v[180:183], v[8:11]
	v_mfma_f32_16x16x32_bf16 v[4:7], v[196:199], v[188:191], v[4:7]
	v_mfma_f32_16x16x32_bf16 v[0:3], v[204:207], v[188:191], v[0:3]
	v_mfma_f32_16x16x32_bf16 v[44:47], v[200:203], v[168:171], v[44:47]
	v_mfma_f32_16x16x32_bf16 v[40:43], v[208:211], v[168:171], v[40:43]
	v_mfma_f32_16x16x32_bf16 v[28:31], v[200:203], v[176:179], v[28:31]
	v_mfma_f32_16x16x32_bf16 v[24:27], v[208:211], v[176:179], v[24:27]
	v_mfma_f32_16x16x32_bf16 v[12:15], v[200:203], v[184:187], v[12:15]
	v_mfma_f32_16x16x32_bf16 v[8:11], v[208:211], v[184:187], v[8:11]
	v_mfma_f32_16x16x32_bf16 v[4:7], v[200:203], v[192:195], v[4:7]
	v_mfma_f32_16x16x32_bf16 v[0:3], v[208:211], v[192:195], v[0:3]
	s_barrier
	ds_read_b128 v[148:151], v146
	ds_read_b128 v[152:155], v146 offset:1024
	ds_read_b128 v[156:159], v146 offset:2048
	ds_read_b128 v[160:163], v146 offset:3072
	s_add_u32 s14, s20, 0xb0000
	s_addc_u32 s15, s21, 0
	s_mov_b32 m0, s30
	v_lshl_add_u64 v[196:197], s[14:15], 0, v[130:131]
	ds_read_b128 v[164:167], v144 offset:32768
	ds_read_b128 v[168:171], v144 offset:33792
	ds_read_b128 v[172:175], v144 offset:34816
	ds_read_b128 v[176:179], v144 offset:35840
	ds_read_b128 v[180:183], v144 offset:36864
	ds_read_b128 v[184:187], v144 offset:37888
	ds_read_b128 v[188:191], v144 offset:38912
	ds_read_b128 v[192:195], v144 offset:39936
	global_load_lds_dwordx4 v[196:197], off
	s_mov_b32 m0, s31
	v_lshl_add_u64 v[196:197], s[14:15], 0, v[128:129]
	global_load_lds_dwordx4 v[196:197], off
	s_waitcnt lgkmcnt(8)
	s_barrier
	s_waitcnt lgkmcnt(0)
	s_waitcnt lgkmcnt(0)
	v_mfma_f32_16x16x32_bf16 v[124:127], v[148:151], v[164:167], v[124:127]
	v_mfma_f32_16x16x32_bf16 v[120:123], v[156:159], v[164:167], v[120:123]
	v_mfma_f32_16x16x32_bf16 v[116:119], v[148:151], v[172:175], v[116:119]
	v_mfma_f32_16x16x32_bf16 v[112:115], v[156:159], v[172:175], v[112:115]
	v_mfma_f32_16x16x32_bf16 v[100:103], v[148:151], v[180:183], v[100:103]
	v_mfma_f32_16x16x32_bf16 v[96:99], v[156:159], v[180:183], v[96:99]
	v_mfma_f32_16x16x32_bf16 v[84:87], v[148:151], v[188:191], v[84:87]
	v_mfma_f32_16x16x32_bf16 v[80:83], v[156:159], v[188:191], v[80:83]
	v_mfma_f32_16x16x32_bf16 v[124:127], v[152:155], v[168:171], v[124:127]
	v_mfma_f32_16x16x32_bf16 v[120:123], v[160:163], v[168:171], v[120:123]
	v_mfma_f32_16x16x32_bf16 v[116:119], v[152:155], v[176:179], v[116:119]
	v_mfma_f32_16x16x32_bf16 v[112:115], v[160:163], v[176:179], v[112:115]
	v_mfma_f32_16x16x32_bf16 v[100:103], v[152:155], v[184:187], v[100:103]
	v_mfma_f32_16x16x32_bf16 v[96:99], v[160:163], v[184:187], v[96:99]
	v_mfma_f32_16x16x32_bf16 v[84:87], v[152:155], v[192:195], v[84:87]
	v_mfma_f32_16x16x32_bf16 v[80:83], v[160:163], v[192:195], v[80:83]
	s_barrier
	s_mov_b32 m0, s45
	v_lshl_add_u64 v[212:213], v[212:213], 0, s[12:13]
	ds_read_b128 v[196:199], v147
	ds_read_b128 v[200:203], v147 offset:1024
	ds_read_b128 v[204:207], v147 offset:2048
	ds_read_b128 v[208:211], v147 offset:3072
	global_load_lds_dwordx4 v[212:213], off
	s_mov_b32 m0, s46
	v_lshl_add_u64 v[212:213], v[214:215], 0, s[12:13]
	global_load_lds_dwordx4 v[212:213], off
	s_barrier
	s_waitcnt lgkmcnt(0)
	s_waitcnt lgkmcnt(0)
	v_mfma_f32_16x16x32_bf16 v[108:111], v[196:199], v[164:167], v[108:111]
	v_mfma_f32_16x16x32_bf16 v[104:107], v[204:207], v[164:167], v[104:107]
	v_mfma_f32_16x16x32_bf16 v[92:95], v[196:199], v[172:175], v[92:95]
	v_mfma_f32_16x16x32_bf16 v[88:91], v[204:207], v[172:175], v[88:91]
	v_mfma_f32_16x16x32_bf16 v[76:79], v[196:199], v[180:183], v[76:79]
	v_mfma_f32_16x16x32_bf16 v[72:75], v[204:207], v[180:183], v[72:75]
	v_mfma_f32_16x16x32_bf16 v[68:71], v[196:199], v[188:191], v[68:71]
	v_mfma_f32_16x16x32_bf16 v[64:67], v[204:207], v[188:191], v[64:67]
	v_mfma_f32_16x16x32_bf16 v[108:111], v[200:203], v[168:171], v[108:111]
	v_mfma_f32_16x16x32_bf16 v[104:107], v[208:211], v[168:171], v[104:107]
	v_mfma_f32_16x16x32_bf16 v[92:95], v[200:203], v[176:179], v[92:95]
	v_mfma_f32_16x16x32_bf16 v[88:91], v[208:211], v[176:179], v[88:91]
	v_mfma_f32_16x16x32_bf16 v[76:79], v[200:203], v[184:187], v[76:79]
	v_mfma_f32_16x16x32_bf16 v[72:75], v[208:211], v[184:187], v[72:75]
	v_mfma_f32_16x16x32_bf16 v[68:71], v[200:203], v[192:195], v[68:71]
	v_mfma_f32_16x16x32_bf16 v[64:67], v[208:211], v[192:195], v[64:67]
	s_mov_b32 m0, s34
	v_lshl_add_u64 v[212:213], v[216:217], 0, s[12:13]
	s_barrier
	ds_read_b128 v[164:167], v144 offset:49152
	ds_read_b128 v[168:171], v144 offset:50176
	ds_read_b128 v[172:175], v144 offset:51200
	ds_read_b128 v[176:179], v144 offset:52224
	ds_read_b128 v[180:183], v144 offset:53248
	ds_read_b128 v[184:187], v144 offset:54272
	ds_read_b128 v[188:191], v144 offset:55296
	ds_read_b128 v[192:195], v144 offset:56320
	global_load_lds_dwordx4 v[212:213], off
	s_mov_b32 m0, s35
	v_lshl_add_u64 v[212:213], v[218:219], 0, s[12:13]
	global_load_lds_dwordx4 v[212:213], off
	s_barrier
; #define STG(P, GB) do { const char* _gb = (GB); \
;     _Pragma("unroll") for (int _i = 0; _i < 2; ++_i) { \
;       __builtin_amdgcn_global_load_lds((const unsigned*)(_gb + voff[_i]), \
;         (LAS unsigned*)((LAS char*)(P) + ldsw + _i * 8192), 16, 0, 0); } } while (0)
; #define LDA(dst, b, h) _Pragma("unroll") for (int m = 0; m < 4; ++m) _Pragma("unroll") for (int k = 0; k < 2; ++k) \
;     dst[m][k] = *(const LAS bf16x8*)((LAS char*)SA(b, h) + aoff + m * 2048 + k * 1024)
; #define MMA(ai, bj, At_, Bt_) do { __builtin_amdgcn_s_setprio(1); \
;     _Pragma("unroll") for (int m = 0; m < 4; ++m) _Pragma("unroll") for (int n = 0; n < 2; ++n) _Pragma("unroll") for (int k = 0; k < 2; ++k) \
;       acc[ai][bj][m][n] = __builtin_amdgcn_mfma_f32_16x16x32_bf16(Bt_[n][k], At_[m][k], acc[ai][bj][m][n], 0, 0, 0); \
;     __builtin_amdgcn_s_setprio(0); } while (0)
; #define WAIT_V(n) asm volatile("s_waitcnt vmcnt(" #n ")" ::: "memory")
; #define WAIT_L(n) asm volatile("s_waitcnt lgkmcnt(" #n ")" ::: "memory")
; #define BAR __builtin_amdgcn_s_barrier()
; #define SCHED __builtin_amdgcn_sched_barrier(0)
; __device__ __forceinline__ void gemm_phase(const bf16_t* __restrict__ A, const bf16_t* __restrict__ Bt, bf16_t* __restrict__ C, int M, int N, int K,
;                                            int ldc, const int EPI, char* smem, const int wid_u) {
;     ...
;       BAR; WAIT_L(0); MMA(0, 1, At, B1); BAR;
;       LDA(At, 1, 1); STG(SA(1, 0), a3);
;       BAR; WAIT_L(0); MMA(1, 0, At, B0); BAR; SCHED;
;       STG(SB(1, 1), b3 + hstep);
;       WAIT_V(6); BAR; MMA(1, 1, At, B1); BAR;
	s_waitcnt lgkmcnt(0)
	s_waitcnt lgkmcnt(0)
	v_mfma_f32_16x16x32_bf16 v[60:63], v[148:151], v[164:167], v[60:63]
	v_mfma_f32_16x16x32_bf16 v[56:59], v[156:159], v[164:167], v[56:59]
	v_mfma_f32_16x16x32_bf16 v[52:55], v[148:151], v[172:175], v[52:55]
	v_mfma_f32_16x16x32_bf16 v[48:51], v[156:159], v[172:175], v[48:51]
	v_mfma_f32_16x16x32_bf16 v[36:39], v[148:151], v[180:183], v[36:39]
	v_mfma_f32_16x16x32_bf16 v[32:35], v[156:159], v[180:183], v[32:35]
	v_mfma_f32_16x16x32_bf16 v[20:23], v[148:151], v[188:191], v[20:23]
	v_mfma_f32_16x16x32_bf16 v[16:19], v[156:159], v[188:191], v[16:19]
	v_mfma_f32_16x16x32_bf16 v[60:63], v[152:155], v[168:171], v[60:63]
	v_mfma_f32_16x16x32_bf16 v[56:59], v[160:163], v[168:171], v[56:59]
	v_mfma_f32_16x16x32_bf16 v[52:55], v[152:155], v[176:179], v[52:55]
	v_mfma_f32_16x16x32_bf16 v[48:51], v[160:163], v[176:179], v[48:51]
	v_mfma_f32_16x16x32_bf16 v[36:39], v[152:155], v[184:187], v[36:39]
	v_mfma_f32_16x16x32_bf16 v[32:35], v[160:163], v[184:187], v[32:35]
	v_mfma_f32_16x16x32_bf16 v[20:23], v[152:155], v[192:195], v[20:23]
	v_mfma_f32_16x16x32_bf16 v[16:19], v[160:163], v[192:195], v[16:19]
	s_barrier
	s_add_u32 s14, s18, 0xb0080
	s_addc_u32 s15, s19, 0
	s_add_i32 s18, s44, s27
	s_mov_b32 m0, s18
	v_lshl_add_u64 v[148:149], s[14:15], 0, v[130:131]
	global_load_lds_dwordx4 v[148:149], off
	s_add_i32 m0, s18, 0x2000
	v_lshl_add_u64 v[148:149], s[14:15], 0, v[128:129]
	global_load_lds_dwordx4 v[148:149], off
	s_waitcnt vmcnt(6)
	s_barrier
	v_mfma_f32_16x16x32_bf16 v[44:47], v[196:199], v[164:167], v[44:47]
	v_mfma_f32_16x16x32_bf16 v[40:43], v[204:207], v[164:167], v[40:43]
	v_mfma_f32_16x16x32_bf16 v[28:31], v[196:199], v[172:175], v[28:31]
	v_mfma_f32_16x16x32_bf16 v[24:27], v[204:207], v[172:175], v[24:27]
	v_mfma_f32_16x16x32_bf16 v[12:15], v[196:199], v[180:183], v[12:15]
	v_mfma_f32_16x16x32_bf16 v[8:11], v[204:207], v[180:183], v[8:11]
	v_mfma_f32_16x16x32_bf16 v[4:7], v[196:199], v[188:191], v[4:7]
	v_mfma_f32_16x16x32_bf16 v[0:3], v[204:207], v[188:191], v[0:3]
	v_mfma_f32_16x16x32_bf16 v[44:47], v[200:203], v[168:171], v[44:47]
	v_mfma_f32_16x16x32_bf16 v[40:43], v[208:211], v[168:171], v[40:43]
	v_mfma_f32_16x16x32_bf16 v[28:31], v[200:203], v[176:179], v[28:31]
	v_mfma_f32_16x16x32_bf16 v[24:27], v[208:211], v[176:179], v[24:27]
	v_mfma_f32_16x16x32_bf16 v[12:15], v[200:203], v[184:187], v[12:15]
	v_mfma_f32_16x16x32_bf16 v[8:11], v[208:211], v[184:187], v[8:11]
	v_mfma_f32_16x16x32_bf16 v[4:7], v[200:203], v[192:195], v[4:7]
	v_mfma_f32_16x16x32_bf16 v[0:3], v[208:211], v[192:195], v[0:3]
	s_add_i32 s53, s53, 2
	s_add_u32 s51, s51, 0x100
	s_addc_u32 s52, s52, 0
	s_cmp_gt_u32 s53, 41
	s_mov_b64 s[14:15], s[16:17]
	s_barrier
	s_cbranch_scc0 .LBB0_213
; #define WAIT_V(n) asm volatile("s_waitcnt vmcnt(" #n ")" ::: "memory")
; #define BAR __builtin_amdgcn_s_barrier()
; __device__ __forceinline__ void gemm_phase(const bf16_t* __restrict__ A, const bf16_t* __restrict__ Bt, bf16_t* __restrict__ C, int M, int N, int K,
;                                            int ldc, const int EPI, char* smem, const int wid_u) {
;     ...
;       const int brow = pm * BM, bcol = pn * BM;
; #pragma unroll
;       for (int ai = 0; ai < 2; ++ai)
; #pragma unroll
;         for (int m = 0; m < 4; ++m) {
;           const size_t row = (size_t)(brow + ai * HALF + wr * 64 + m * 16 + fr);
;           if (EPI == 0) {
; #pragma unroll
;             for (int bj = 0; bj < 2; ++bj) {
;               const f32x4 v0 = acc[ai][bj][m][0], v1 = acc[ai][bj][m][1];
;               uint4 u; u.x = cvt_pk_bf16(v0[0], v0[1]); u.y = cvt_pk_bf16(v0[2], v0[3]); u.z = cvt_pk_bf16(v1[0], v1[1]); u.w = cvt_pk_bf16(v1[2], v1[3]);
;               *(uint4*)(C + row * ldc + bcol + bj * HALF + wc * 32 + fq * 8) = u;
;             }
;           } else {
;             float o[8];
; #pragma unroll
;             for (int n = 0; n < 2; ++n) {
;               const f32x4 a = acc[ai][0][m][n], b = acc[ai][1][m][n];
; #pragma unroll
;               for (int j = 0; j < 4; ++j) o[n * 4 + j] = a[j] * __builtin_amdgcn_rcpf(1.f + __expf(-a[j])) * b[j];
;             }
;             *(uint4*)(C + row * ldc + (bcol >> 1) + wc * 32 + fq * 8) = pack8(o);
;           }
;         }
;     }
;     if (!has_next) break;
; #pragma unroll
;     for (int a = 0; a < 2; ++a)
; #pragma unroll
;       for (int b = 0; b < 2; ++b)
; #pragma unroll
;         for (int m = 0; m < 4; ++m)
; #pragma unroll
;           for (int n = 0; n < 2; ++n) acc[a][b][m][n] = (f32x4){0.f, 0.f, 0.f, 0.f};
;     pm = npm; pn = npn; cA = nA; cB = nB; ++ui;
;   }
;   WAIT_V(0);
;   if (wr == 0) BAR;
;   BAR;
	v_lshl_add_u32 v148, s10, 8, v142
	v_cvt_pk_bf16_f32 v68, v68, v69
	v_cvt_pk_bf16_f32 v69, v70, v71
	v_cvt_pk_bf16_f32 v70, v64, v65
	v_add_u32_e32 v64, 0x80, v148
	s_lshl_b32 s10, s50, 9
	v_ashrrev_i32_e32 v149, 31, v148
	v_cvt_pk_bf16_f32 v108, v108, v109
	v_cvt_pk_bf16_f32 v109, v110, v111
	v_cvt_pk_bf16_f32 v110, v104, v105
	v_or_b32_e32 v104, 16, v148
	v_ashrrev_i32_e32 v65, 31, v64
	v_cvt_pk_bf16_f32 v44, v44, v45
	v_cvt_pk_bf16_f32 v45, v46, v47
	v_cvt_pk_bf16_f32 v46, v40, v41
	v_add_u32_e32 v40, 0x90, v148
	v_lshl_add_u64 v[150:151], v[132:133], 0, s[10:11]
	v_lshlrev_b64 v[152:153], 11, v[148:149]
	v_ashrrev_i32_e32 v105, 31, v104
	v_cvt_pk_bf16_f32 v92, v92, v93
	v_cvt_pk_bf16_f32 v93, v94, v95
	v_cvt_pk_bf16_f32 v94, v88, v89
	v_or_b32_e32 v88, 32, v148
	v_lshlrev_b64 v[64:65], 11, v[64:65]
	v_ashrrev_i32_e32 v41, 31, v40
	v_cvt_pk_bf16_f32 v28, v28, v29
	v_cvt_pk_bf16_f32 v29, v30, v31
	v_cvt_pk_bf16_f32 v30, v24, v25
	v_add_u32_e32 v24, 0xa0, v148
	v_lshl_add_u64 v[152:153], v[150:151], 0, v[152:153]
	v_cvt_pk_bf16_f32 v111, v106, v107
	v_lshlrev_b64 v[104:105], 11, v[104:105]
	v_ashrrev_i32_e32 v89, 31, v88
	v_cvt_pk_bf16_f32 v76, v76, v77
	v_cvt_pk_bf16_f32 v77, v78, v79
	v_cvt_pk_bf16_f32 v78, v72, v73
	v_or_b32_e32 v72, 48, v148
	v_lshl_add_u64 v[64:65], v[150:151], 0, v[64:65]
	v_cvt_pk_bf16_f32 v47, v42, v43
	v_lshlrev_b64 v[40:41], 11, v[40:41]
	v_ashrrev_i32_e32 v25, 31, v24
	v_cvt_pk_bf16_f32 v12, v12, v13
	v_cvt_pk_bf16_f32 v13, v14, v15
	v_cvt_pk_bf16_f32 v14, v8, v9
	v_add_u32_e32 v8, 0xb0, v148
	global_store_dwordx4 v[152:153], v[108:111], off offset:256
	v_cvt_pk_bf16_f32 v95, v90, v91
	v_lshlrev_b64 v[88:89], 11, v[88:89]
	v_lshl_add_u64 v[108:109], v[150:151], 0, v[104:105]
	v_ashrrev_i32_e32 v73, 31, v72
	global_store_dwordx4 v[64:65], v[44:47], off offset:256
	v_cvt_pk_bf16_f32 v31, v26, v27
	v_lshlrev_b64 v[24:25], 11, v[24:25]
	v_lshl_add_u64 v[44:45], v[150:151], 0, v[40:41]
	v_ashrrev_i32_e32 v9, 31, v8
	global_store_dwordx4 v[108:109], v[92:95], off offset:256
	v_cvt_pk_bf16_f32 v79, v74, v75
	v_lshlrev_b64 v[72:73], 11, v[72:73]
	v_lshl_add_u64 v[92:93], v[150:151], 0, v[88:89]
	global_store_dwordx4 v[44:45], v[28:31], off offset:256
	v_cvt_pk_bf16_f32 v15, v10, v11
	v_lshlrev_b64 v[8:9], 11, v[8:9]
	v_lshl_add_u64 v[28:29], v[150:151], 0, v[24:25]
	v_cvt_pk_bf16_f32 v124, v124, v125
	v_cvt_pk_bf16_f32 v125, v126, v127
	v_cvt_pk_bf16_f32 v126, v120, v121
	v_cvt_pk_bf16_f32 v127, v122, v123
	v_cvt_pk_bf16_f32 v104, v116, v117
	v_cvt_pk_bf16_f32 v105, v118, v119
	v_cvt_pk_bf16_f32 v106, v112, v113
	v_cvt_pk_bf16_f32 v107, v114, v115
	v_cvt_pk_bf16_f32 v88, v100, v101
	v_cvt_pk_bf16_f32 v89, v102, v103
	v_cvt_pk_bf16_f32 v90, v96, v97
	v_cvt_pk_bf16_f32 v91, v98, v99
	global_store_dwordx4 v[92:93], v[76:79], off offset:256
	v_cvt_pk_bf16_f32 v74, v80, v81
	v_cvt_pk_bf16_f32 v75, v82, v83
	v_lshl_add_u64 v[76:77], v[150:151], 0, v[72:73]
	v_cvt_pk_bf16_f32 v72, v84, v85
	v_cvt_pk_bf16_f32 v73, v86, v87
	v_cvt_pk_bf16_f32 v71, v66, v67
	v_cvt_pk_bf16_f32 v60, v60, v61
	v_cvt_pk_bf16_f32 v61, v62, v63
	v_cvt_pk_bf16_f32 v62, v56, v57
	v_cvt_pk_bf16_f32 v63, v58, v59
	v_cvt_pk_bf16_f32 v40, v52, v53
	v_cvt_pk_bf16_f32 v41, v54, v55
	v_cvt_pk_bf16_f32 v42, v48, v49
	v_cvt_pk_bf16_f32 v43, v50, v51
	v_cvt_pk_bf16_f32 v24, v36, v37
	v_cvt_pk_bf16_f32 v25, v38, v39
	v_cvt_pk_bf16_f32 v26, v32, v33
	v_cvt_pk_bf16_f32 v27, v34, v35
	global_store_dwordx4 v[28:29], v[12:15], off offset:256
	v_cvt_pk_bf16_f32 v10, v16, v17
	v_cvt_pk_bf16_f32 v11, v18, v19
	v_lshl_add_u64 v[12:13], v[150:151], 0, v[8:9]
	v_cvt_pk_bf16_f32 v8, v20, v21
	v_cvt_pk_bf16_f32 v9, v22, v23
	v_cvt_pk_bf16_f32 v4, v4, v5
	v_cvt_pk_bf16_f32 v5, v6, v7
	v_cvt_pk_bf16_f32 v6, v0, v1
	v_cvt_pk_bf16_f32 v7, v2, v3
	s_and_b64 vcc, exec, s[2:3]
	s_mov_b32 s10, s48
	s_mov_b32 s50, s49
	s_mov_b64 s[16:17], s[6:7]
	s_mov_b64 s[14:15], s[4:5]
	global_store_dwordx4 v[152:153], v[124:127], off
	global_store_dwordx4 v[108:109], v[104:107], off
	global_store_dwordx4 v[92:93], v[88:91], off
	global_store_dwordx4 v[76:77], v[72:75], off
	global_store_dwordx4 v[76:77], v[68:71], off offset:256
	global_store_dwordx4 v[64:65], v[60:63], off
	global_store_dwordx4 v[44:45], v[40:43], off
	global_store_dwordx4 v[28:29], v[24:27], off
	global_store_dwordx4 v[12:13], v[8:11], off
	global_store_dwordx4 v[12:13], v[4:7], off offset:256
	s_cbranch_vccz .LBB0_206
	s_waitcnt vmcnt(0)
	s_cmpk_gt_u32 s22, 0xff
	s_cbranch_scc1 .LBB0_217
	s_barrier

; #define STG(P, GB) do { const char* _gb = (GB); \
;     _Pragma("unroll") for (int _i = 0; _i < 2; ++_i) { \
;       __builtin_amdgcn_global_load_lds((const unsigned*)(_gb + voff[_i]), \
;         (LAS unsigned*)((LAS char*)(P) + ldsw + _i * 8192), 16, 0, 0); } } while (0)
; #define LDA(dst, b, h) _Pragma("unroll") for (int m = 0; m < 4; ++m) _Pragma("unroll") for (int k = 0; k < 2; ++k) \
;     dst[m][k] = *(const LAS bf16x8*)((LAS char*)SA(b, h) + aoff + m * 2048 + k * 1024)
; #define LDB(dst, b, h) _Pragma("unroll") for (int n = 0; n < 2; ++n) _Pragma("unroll") for (int k = 0; k < 2; ++k) \
;     dst[n][k] = *(const LAS bf16x8*)((LAS char*)SB(b, h) + boff + n * 2048 + k * 1024)
; #define MMA(ai, bj, At_, Bt_) do { __builtin_amdgcn_s_setprio(1); \
;     _Pragma("unroll") for (int m = 0; m < 4; ++m) _Pragma("unroll") for (int n = 0; n < 2; ++n) _Pragma("unroll") for (int k = 0; k < 2; ++k) \
;       acc[ai][bj][m][n] = __builtin_amdgcn_mfma_f32_16x16x32_bf16(Bt_[n][k], At_[m][k], acc[ai][bj][m][n], 0, 0, 0); \
;     __builtin_amdgcn_s_setprio(0); } while (0)
; #define WAIT_V(n) asm volatile("s_waitcnt vmcnt(" #n ")" ::: "memory")
; #define WAIT_L(n) asm volatile("s_waitcnt lgkmcnt(" #n ")" ::: "memory")
; #define BAR __builtin_amdgcn_s_barrier()
; #define SCHED __builtin_amdgcn_sched_barrier(0)
; __device__ __forceinline__ void gemm_phase(const bf16_t* __restrict__ A, const bf16_t* __restrict__ Bt, bf16_t* __restrict__ C, int M, int N, int K,
;                                            int ldc, const int EPI, char* smem, const int wid_u) {
;     ...
;       LDB(B0, 0, 0); SCHED; LDA(At, 0, 0); STG(SA(1, 1), a1 + hstep);
;       WAIT_L(8); BAR; WAIT_L(0); MMA(0, 0, At, B0); BAR; SCHED;
;       LDB(B1, 0, 1); STG(SB(0, 0), b2);
;       BAR; WAIT_L(0); MMA(0, 1, At, B1); BAR;
;       LDA(At, 0, 1); STG(SA(0, 0), a2);
;       BAR; WAIT_L(0); MMA(1, 0, At, B0); BAR; SCHED;
;       STG(SB(0, 1), b2 + hstep);
;       WAIT_V(6); BAR; MMA(1, 1, At, B1); BAR;
;       LDB(B0, 1, 0); SCHED; LDA(At, 1, 0); STG(SA(0, 1), a2 + hstep);
;       WAIT_L(8); BAR; WAIT_L(0); MMA(0, 0, At, B0); BAR; SCHED;
;       LDB(B1, 1, 1); STG(SB(1, 0), b3);
;       BAR; WAIT_L(0); MMA(0, 1, At, B1); BAR;
;       LDA(At, 1, 1); STG(SA(1, 0), a3);
;       BAR; WAIT_L(0); MMA(1, 0, At, B0); BAR; SCHED;
;       STG(SB(1, 1), b3 + hstep);
;       WAIT_V(6); BAR; MMA(1, 1, At, B1); BAR;
.LBB0_334:
	ds_read_b128 v[148:151], v144
	ds_read_b128 v[152:155], v144 offset:1024
	ds_read_b128 v[156:159], v144 offset:2048
	ds_read_b128 v[160:163], v144 offset:3072
	s_add_u32 s18, s16, 0x100
	s_addc_u32 s19, s17, 0
	s_cmp_eq_u32 s51, 12
	s_cselect_b32 s23, s46, s19
	s_cselect_b32 s22, s47, s18
	s_cselect_b32 s21, s11, s50
	s_cselect_b32 s20, s48, s49
	v_lshl_add_u64 v[196:197], s[16:17], 0, v[136:137]
	s_add_i32 m0, s30, 0xc000
	ds_read_b128 v[164:167], v145
	ds_read_b128 v[168:171], v145 offset:1024
	ds_read_b128 v[172:175], v145 offset:2048
	ds_read_b128 v[176:179], v145 offset:3072
	ds_read_b128 v[180:183], v145 offset:4096
	ds_read_b128 v[184:187], v145 offset:5120
	ds_read_b128 v[188:191], v145 offset:6144
	ds_read_b128 v[192:195], v145 offset:7168
	global_load_lds_dwordx4 v[196:197], off
	s_add_i32 m0, s30, 0xe000
	v_lshl_add_u64 v[196:197], s[16:17], 0, v[134:135]
	global_load_lds_dwordx4 v[196:197], off
	s_waitcnt lgkmcnt(8)
	s_barrier
	s_waitcnt lgkmcnt(0)
	s_waitcnt lgkmcnt(0)
	v_mfma_f32_16x16x32_bf16 v[124:127], v[148:151], v[164:167], v[124:127]
	v_mfma_f32_16x16x32_bf16 v[120:123], v[156:159], v[164:167], v[120:123]
	v_mfma_f32_16x16x32_bf16 v[116:119], v[148:151], v[172:175], v[116:119]
	v_mfma_f32_16x16x32_bf16 v[112:115], v[156:159], v[172:175], v[112:115]
	v_mfma_f32_16x16x32_bf16 v[100:103], v[148:151], v[180:183], v[100:103]
	v_mfma_f32_16x16x32_bf16 v[96:99], v[156:159], v[180:183], v[96:99]
	v_mfma_f32_16x16x32_bf16 v[84:87], v[148:151], v[188:191], v[84:87]
	v_mfma_f32_16x16x32_bf16 v[80:83], v[156:159], v[188:191], v[80:83]
	v_mfma_f32_16x16x32_bf16 v[124:127], v[152:155], v[168:171], v[124:127]
	v_mfma_f32_16x16x32_bf16 v[120:123], v[160:163], v[168:171], v[120:123]
	v_mfma_f32_16x16x32_bf16 v[116:119], v[152:155], v[176:179], v[116:119]
	v_mfma_f32_16x16x32_bf16 v[112:115], v[160:163], v[176:179], v[112:115]
	v_mfma_f32_16x16x32_bf16 v[100:103], v[152:155], v[184:187], v[100:103]
	v_mfma_f32_16x16x32_bf16 v[96:99], v[160:163], v[184:187], v[96:99]
	v_mfma_f32_16x16x32_bf16 v[84:87], v[152:155], v[192:195], v[84:87]
	v_mfma_f32_16x16x32_bf16 v[80:83], v[160:163], v[192:195], v[80:83]
	s_barrier
	s_add_i32 s16, s38, s29
	v_lshl_add_u64 v[212:213], s[20:21], 0, v[130:131]
	s_mov_b32 m0, s16
	ds_read_b128 v[196:199], v146
	ds_read_b128 v[200:203], v146 offset:1024
	ds_read_b128 v[204:207], v146 offset:2048
	ds_read_b128 v[208:211], v146 offset:3072
	global_load_lds_dwordx4 v[212:213], off
	s_add_i32 m0, s16, 0x2000
	v_lshl_add_u64 v[214:215], s[20:21], 0, v[128:129]
	global_load_lds_dwordx4 v[214:215], off
	s_barrier
	s_waitcnt lgkmcnt(0)
	s_waitcnt lgkmcnt(0)
	v_mfma_f32_16x16x32_bf16 v[108:111], v[196:199], v[164:167], v[108:111]
	v_mfma_f32_16x16x32_bf16 v[104:107], v[204:207], v[164:167], v[104:107]
	v_mfma_f32_16x16x32_bf16 v[92:95], v[196:199], v[172:175], v[92:95]
	v_mfma_f32_16x16x32_bf16 v[88:91], v[204:207], v[172:175], v[88:91]
	v_mfma_f32_16x16x32_bf16 v[76:79], v[196:199], v[180:183], v[76:79]
	v_mfma_f32_16x16x32_bf16 v[72:75], v[204:207], v[180:183], v[72:75]
	v_mfma_f32_16x16x32_bf16 v[68:71], v[196:199], v[188:191], v[68:71]
	v_mfma_f32_16x16x32_bf16 v[64:67], v[204:207], v[188:191], v[64:67]
	v_mfma_f32_16x16x32_bf16 v[108:111], v[200:203], v[168:171], v[108:111]
	v_mfma_f32_16x16x32_bf16 v[104:107], v[208:211], v[168:171], v[104:107]
	v_mfma_f32_16x16x32_bf16 v[92:95], v[200:203], v[176:179], v[92:95]
	v_mfma_f32_16x16x32_bf16 v[88:91], v[208:211], v[176:179], v[88:91]
	v_mfma_f32_16x16x32_bf16 v[76:79], v[200:203], v[184:187], v[76:79]
	v_mfma_f32_16x16x32_bf16 v[72:75], v[208:211], v[184:187], v[72:75]
	v_mfma_f32_16x16x32_bf16 v[68:71], v[200:203], v[192:195], v[68:71]
	v_mfma_f32_16x16x32_bf16 v[64:67], v[208:211], v[192:195], v[64:67]
	s_mov_b32 m0, s30
	v_lshl_add_u64 v[216:217], s[22:23], 0, v[130:131]
	s_barrier
	ds_read_b128 v[164:167], v145 offset:16384
	ds_read_b128 v[168:171], v145 offset:17408
	ds_read_b128 v[172:175], v145 offset:18432
	ds_read_b128 v[176:179], v145 offset:19456
	ds_read_b128 v[180:183], v145 offset:20480
	ds_read_b128 v[184:187], v145 offset:21504
	ds_read_b128 v[188:191], v145 offset:22528
	ds_read_b128 v[192:195], v145 offset:23552
	global_load_lds_dwordx4 v[216:217], off
	s_mov_b32 m0, s31
	v_lshl_add_u64 v[218:219], s[22:23], 0, v[128:129]
	global_load_lds_dwordx4 v[218:219], off
	s_barrier
	s_waitcnt lgkmcnt(0)
	s_waitcnt lgkmcnt(0)
	v_mfma_f32_16x16x32_bf16 v[60:63], v[148:151], v[164:167], v[60:63]
	v_mfma_f32_16x16x32_bf16 v[56:59], v[156:159], v[164:167], v[56:59]
	v_mfma_f32_16x16x32_bf16 v[52:55], v[148:151], v[172:175], v[52:55]
	v_mfma_f32_16x16x32_bf16 v[48:51], v[156:159], v[172:175], v[48:51]
	v_mfma_f32_16x16x32_bf16 v[36:39], v[148:151], v[180:183], v[36:39]
	v_mfma_f32_16x16x32_bf16 v[32:35], v[156:159], v[180:183], v[32:35]
	v_mfma_f32_16x16x32_bf16 v[20:23], v[148:151], v[188:191], v[20:23]
	v_mfma_f32_16x16x32_bf16 v[16:19], v[156:159], v[188:191], v[16:19]
	v_mfma_f32_16x16x32_bf16 v[60:63], v[152:155], v[168:171], v[60:63]
	v_mfma_f32_16x16x32_bf16 v[56:59], v[160:163], v[168:171], v[56:59]
	v_mfma_f32_16x16x32_bf16 v[52:55], v[152:155], v[176:179], v[52:55]
	v_mfma_f32_16x16x32_bf16 v[48:51], v[160:163], v[176:179], v[48:51]
	v_mfma_f32_16x16x32_bf16 v[36:39], v[152:155], v[184:187], v[36:39]
	v_mfma_f32_16x16x32_bf16 v[32:35], v[160:163], v[184:187], v[32:35]
	v_mfma_f32_16x16x32_bf16 v[20:23], v[152:155], v[192:195], v[20:23]
	v_mfma_f32_16x16x32_bf16 v[16:19], v[160:163], v[192:195], v[16:19]
	s_barrier
; #define STG(P, GB) do { const char* _gb = (GB); \
;     _Pragma("unroll") for (int _i = 0; _i < 2; ++_i) { \
;       __builtin_amdgcn_global_load_lds((const unsigned*)(_gb + voff[_i]), \
;         (LAS unsigned*)((LAS char*)(P) + ldsw + _i * 8192), 16, 0, 0); } } while (0)
; #define LDA(dst, b, h) _Pragma("unroll") for (int m = 0; m < 4; ++m) _Pragma("unroll") for (int k = 0; k < 2; ++k) \
;     dst[m][k] = *(const LAS bf16x8*)((LAS char*)SA(b, h) + aoff + m * 2048 + k * 1024)
; #define LDB(dst, b, h) _Pragma("unroll") for (int n = 0; n < 2; ++n) _Pragma("unroll") for (int k = 0; k < 2; ++k) \
;     dst[n][k] = *(const LAS bf16x8*)((LAS char*)SB(b, h) + boff + n * 2048 + k * 1024)
; #define MMA(ai, bj, At_, Bt_) do { __builtin_amdgcn_s_setprio(1); \
;     _Pragma("unroll") for (int m = 0; m < 4; ++m) _Pragma("unroll") for (int n = 0; n < 2; ++n) _Pragma("unroll") for (int k = 0; k < 2; ++k) \
;       acc[ai][bj][m][n] = __builtin_amdgcn_mfma_f32_16x16x32_bf16(Bt_[n][k], At_[m][k], acc[ai][bj][m][n], 0, 0, 0); \
;     __builtin_amdgcn_s_setprio(0); } while (0)
; #define WAIT_V(n) asm volatile("s_waitcnt vmcnt(" #n ")" ::: "memory")
; #define WAIT_L(n) asm volatile("s_waitcnt lgkmcnt(" #n ")" ::: "memory")
; #define BAR __builtin_amdgcn_s_barrier()
; #define SCHED __builtin_amdgcn_sched_barrier(0)
; __device__ __forceinline__ void gemm_phase(const bf16_t* __restrict__ A, const bf16_t* __restrict__ Bt, bf16_t* __restrict__ C, int M, int N, int K,
;                                            int ldc, const int EPI, char* smem, const int wid_u) {
;     ...
;       LDB(B0, 0, 0); SCHED; LDA(At, 0, 0); STG(SA(1, 1), a1 + hstep);
;       WAIT_L(8); BAR; WAIT_L(0); MMA(0, 0, At, B0); BAR; SCHED;
;       LDB(B1, 0, 1); STG(SB(0, 0), b2);
;       BAR; WAIT_L(0); MMA(0, 1, At, B1); BAR;
;       LDA(At, 0, 1); STG(SA(0, 0), a2);
;       BAR; WAIT_L(0); MMA(1, 0, At, B0); BAR; SCHED;
;       STG(SB(0, 1), b2 + hstep);
;       WAIT_V(6); BAR; MMA(1, 1, At, B1); BAR;
;       LDB(B0, 1, 0); SCHED; LDA(At, 1, 0); STG(SA(0, 1), a2 + hstep);
;       WAIT_L(8); BAR; WAIT_L(0); MMA(0, 0, At, B0); BAR; SCHED;
;       LDB(B1, 1, 1); STG(SB(1, 0), b3);
;       BAR; WAIT_L(0); MMA(0, 1, At, B1); BAR;
;       LDA(At, 1, 1); STG(SA(1, 0), a3);
;       BAR; WAIT_L(0); MMA(1, 0, At, B0); BAR; SCHED;
;       STG(SB(1, 1), b3 + hstep);
;       WAIT_V(6); BAR; MMA(1, 1, At, B1); BAR;
	s_add_u32 s16, s20, 0x40000
	s_addc_u32 s17, s21, 0
	s_add_i32 s52, s39, s29
	s_mov_b32 m0, s52
	v_lshl_add_u64 v[148:149], s[16:17], 0, v[130:131]
	global_load_lds_dwordx4 v[148:149], off
	s_add_i32 m0, s52, 0x2000
	v_lshl_add_u64 v[148:149], s[16:17], 0, v[128:129]
	global_load_lds_dwordx4 v[148:149], off
	s_waitcnt vmcnt(6)
	s_barrier
	v_mfma_f32_16x16x32_bf16 v[44:47], v[196:199], v[164:167], v[44:47]
	v_mfma_f32_16x16x32_bf16 v[40:43], v[204:207], v[164:167], v[40:43]
	v_mfma_f32_16x16x32_bf16 v[28:31], v[196:199], v[172:175], v[28:31]
	v_mfma_f32_16x16x32_bf16 v[24:27], v[204:207], v[172:175], v[24:27]
	v_mfma_f32_16x16x32_bf16 v[12:15], v[196:199], v[180:183], v[12:15]
	v_mfma_f32_16x16x32_bf16 v[8:11], v[204:207], v[180:183], v[8:11]
	v_mfma_f32_16x16x32_bf16 v[4:7], v[196:199], v[188:191], v[4:7]
	v_mfma_f32_16x16x32_bf16 v[0:3], v[204:207], v[188:191], v[0:3]
	v_mfma_f32_16x16x32_bf16 v[44:47], v[200:203], v[168:171], v[44:47]
	v_mfma_f32_16x16x32_bf16 v[40:43], v[208:211], v[168:171], v[40:43]
	v_mfma_f32_16x16x32_bf16 v[28:31], v[200:203], v[176:179], v[28:31]
	v_mfma_f32_16x16x32_bf16 v[24:27], v[208:211], v[176:179], v[24:27]
	v_mfma_f32_16x16x32_bf16 v[12:15], v[200:203], v[184:187], v[12:15]
	v_mfma_f32_16x16x32_bf16 v[8:11], v[208:211], v[184:187], v[8:11]
	v_mfma_f32_16x16x32_bf16 v[4:7], v[200:203], v[192:195], v[4:7]
	v_mfma_f32_16x16x32_bf16 v[0:3], v[208:211], v[192:195], v[0:3]
	s_add_i32 s52, 0, 0x18000
	v_add_u32_e32 v147, s52, v143
	s_barrier
	ds_read_b128 v[148:151], v147
	ds_read_b128 v[152:155], v147 offset:1024
	ds_read_b128 v[156:159], v147 offset:2048
	ds_read_b128 v[160:163], v147 offset:3072
	s_add_u32 s16, s22, 0x40000
	s_addc_u32 s17, s23, 0
	s_mov_b32 m0, s34
	v_lshl_add_u64 v[196:197], s[16:17], 0, v[130:131]
	ds_read_b128 v[164:167], v145 offset:32768
	ds_read_b128 v[168:171], v145 offset:33792
	ds_read_b128 v[172:175], v145 offset:34816
	ds_read_b128 v[176:179], v145 offset:35840
	ds_read_b128 v[180:183], v145 offset:36864
	ds_read_b128 v[184:187], v145 offset:37888
	ds_read_b128 v[188:191], v145 offset:38912
	ds_read_b128 v[192:195], v145 offset:39936
	global_load_lds_dwordx4 v[196:197], off
	s_mov_b32 m0, s35
	v_lshl_add_u64 v[196:197], s[16:17], 0, v[128:129]
	global_load_lds_dwordx4 v[196:197], off
	s_waitcnt lgkmcnt(8)
	s_barrier
	s_waitcnt lgkmcnt(0)
	s_waitcnt lgkmcnt(0)
	v_mfma_f32_16x16x32_bf16 v[124:127], v[148:151], v[164:167], v[124:127]
	v_mfma_f32_16x16x32_bf16 v[120:123], v[156:159], v[164:167], v[120:123]
	v_mfma_f32_16x16x32_bf16 v[116:119], v[148:151], v[172:175], v[116:119]
	v_mfma_f32_16x16x32_bf16 v[112:115], v[156:159], v[172:175], v[112:115]
	v_mfma_f32_16x16x32_bf16 v[100:103], v[148:151], v[180:183], v[100:103]
	v_mfma_f32_16x16x32_bf16 v[96:99], v[156:159], v[180:183], v[96:99]
	v_mfma_f32_16x16x32_bf16 v[84:87], v[148:151], v[188:191], v[84:87]
	v_mfma_f32_16x16x32_bf16 v[80:83], v[156:159], v[188:191], v[80:83]
	v_mfma_f32_16x16x32_bf16 v[124:127], v[152:155], v[168:171], v[124:127]
	v_mfma_f32_16x16x32_bf16 v[120:123], v[160:163], v[168:171], v[120:123]
	v_mfma_f32_16x16x32_bf16 v[116:119], v[152:155], v[176:179], v[116:119]
	v_mfma_f32_16x16x32_bf16 v[112:115], v[160:163], v[176:179], v[112:115]
	v_mfma_f32_16x16x32_bf16 v[100:103], v[152:155], v[184:187], v[100:103]
	v_mfma_f32_16x16x32_bf16 v[96:99], v[160:163], v[184:187], v[96:99]
	v_mfma_f32_16x16x32_bf16 v[84:87], v[152:155], v[192:195], v[84:87]
	v_mfma_f32_16x16x32_bf16 v[80:83], v[160:163], v[192:195], v[80:83]
	s_barrier
	s_add_i32 s22, 0, 0x1c000
	s_add_i32 s16, s52, s29
	v_add_u32_e32 v147, s22, v143
	v_lshl_add_u64 v[212:213], v[212:213], 0, s[8:9]
	s_mov_b32 m0, s16
	ds_read_b128 v[196:199], v147
	ds_read_b128 v[200:203], v147 offset:1024
	ds_read_b128 v[204:207], v147 offset:2048
	ds_read_b128 v[208:211], v147 offset:3072
	global_load_lds_dwordx4 v[212:213], off
	s_add_i32 m0, s16, 0x2000
	v_lshl_add_u64 v[212:213], v[214:215], 0, s[8:9]
	global_load_lds_dwordx4 v[212:213], off
	s_barrier
	s_waitcnt lgkmcnt(0)
	s_waitcnt lgkmcnt(0)
	v_mfma_f32_16x16x32_bf16 v[108:111], v[196:199], v[164:167], v[108:111]
	v_mfma_f32_16x16x32_bf16 v[104:107], v[204:207], v[164:167], v[104:107]
	v_mfma_f32_16x16x32_bf16 v[92:95], v[196:199], v[172:175], v[92:95]
	v_mfma_f32_16x16x32_bf16 v[88:91], v[204:207], v[172:175], v[88:91]
	v_mfma_f32_16x16x32_bf16 v[76:79], v[196:199], v[180:183], v[76:79]
	v_mfma_f32_16x16x32_bf16 v[72:75], v[204:207], v[180:183], v[72:75]
	v_mfma_f32_16x16x32_bf16 v[68:71], v[196:199], v[188:191], v[68:71]
	v_mfma_f32_16x16x32_bf16 v[64:67], v[204:207], v[188:191], v[64:67]
	v_mfma_f32_16x16x32_bf16 v[108:111], v[200:203], v[168:171], v[108:111]
	v_mfma_f32_16x16x32_bf16 v[104:107], v[208:211], v[168:171], v[104:107]
	v_mfma_f32_16x16x32_bf16 v[92:95], v[200:203], v[176:179], v[92:95]
	v_mfma_f32_16x16x32_bf16 v[88:91], v[208:211], v[176:179], v[88:91]
	v_mfma_f32_16x16x32_bf16 v[76:79], v[200:203], v[184:187], v[76:79]
	v_mfma_f32_16x16x32_bf16 v[72:75], v[208:211], v[184:187], v[72:75]
	v_mfma_f32_16x16x32_bf16 v[68:71], v[200:203], v[192:195], v[68:71]
	v_mfma_f32_16x16x32_bf16 v[64:67], v[208:211], v[192:195], v[64:67]
	s_mov_b32 m0, s36
	v_lshl_add_u64 v[212:213], v[216:217], 0, s[8:9]
	s_barrier
	ds_read_b128 v[164:167], v145 offset:49152
	ds_read_b128 v[168:171], v145 offset:50176
	ds_read_b128 v[172:175], v145 offset:51200
	ds_read_b128 v[176:179], v145 offset:52224
	ds_read_b128 v[180:183], v145 offset:53248
	ds_read_b128 v[184:187], v145 offset:54272
	ds_read_b128 v[188:191], v145 offset:55296
	ds_read_b128 v[192:195], v145 offset:56320
	global_load_lds_dwordx4 v[212:213], off
	s_mov_b32 m0, s37
	v_lshl_add_u64 v[212:213], v[218:219], 0, s[8:9]
	global_load_lds_dwordx4 v[212:213], off
	s_barrier
; #define STG(P, GB) do { const char* _gb = (GB); \
;     _Pragma("unroll") for (int _i = 0; _i < 2; ++_i) { \
;       __builtin_amdgcn_global_load_lds((const unsigned*)(_gb + voff[_i]), \
;         (LAS unsigned*)((LAS char*)(P) + ldsw + _i * 8192), 16, 0, 0); } } while (0)
; #define MMA(ai, bj, At_, Bt_) do { __builtin_amdgcn_s_setprio(1); \
;     _Pragma("unroll") for (int m = 0; m < 4; ++m) _Pragma("unroll") for (int n = 0; n < 2; ++n) _Pragma("unroll") for (int k = 0; k < 2; ++k) \
;       acc[ai][bj][m][n] = __builtin_amdgcn_mfma_f32_16x16x32_bf16(Bt_[n][k], At_[m][k], acc[ai][bj][m][n], 0, 0, 0); \
;     __builtin_amdgcn_s_setprio(0); } while (0)
; #define WAIT_V(n) asm volatile("s_waitcnt vmcnt(" #n ")" ::: "memory")
; #define WAIT_L(n) asm volatile("s_waitcnt lgkmcnt(" #n ")" ::: "memory")
; #define BAR __builtin_amdgcn_s_barrier()
; #define SCHED __builtin_amdgcn_sched_barrier(0)
; __device__ __forceinline__ void gemm_phase(const bf16_t* __restrict__ A, const bf16_t* __restrict__ Bt, bf16_t* __restrict__ C, int M, int N, int K,
;                                            int ldc, const int EPI, char* smem, const int wid_u) {
;     ...
;       BAR; WAIT_L(0); MMA(1, 0, At, B0); BAR; SCHED;
;       STG(SB(1, 1), b3 + hstep);
;       WAIT_V(6); BAR; MMA(1, 1, At, B1); BAR;
;     }
;     {
;       const int brow = pm * BM, bcol = pn * BM;
; #pragma unroll
;       for (int ai = 0; ai < 2; ++ai)
; #pragma unroll
;         for (int m = 0; m < 4; ++m) {
;           const size_t row = (size_t)(brow + ai * HALF + wr * 64 + m * 16 + fr);
;           if (EPI == 0) {
; #pragma unroll
;             for (int bj = 0; bj < 2; ++bj) {
;               const f32x4 v0 = acc[ai][bj][m][0], v1 = acc[ai][bj][m][1];
;               uint4 u; u.x = cvt_pk_bf16(v0[0], v0[1]); u.y = cvt_pk_bf16(v0[2], v0[3]); u.z = cvt_pk_bf16(v1[0], v1[1]); u.w = cvt_pk_bf16(v1[2], v1[3]);
;               *(uint4*)(C + row * ldc + bcol + bj * HALF + wc * 32 + fq * 8) = u;
;             }
;     ...
;     if (!has_next) break;
; #pragma unroll
;     for (int a = 0; a < 2; ++a)
; #pragma unroll
;       for (int b = 0; b < 2; ++b)
; #pragma unroll
;         for (int m = 0; m < 4; ++m)
; #pragma unroll
;           for (int n = 0; n < 2; ++n) acc[a][b][m][n] = (f32x4){0.f, 0.f, 0.f, 0.f};
;     pm = npm; pn = npn; cA = nA; cB = nB; ++ui;
;   }
;   WAIT_V(0);
;   if (wr == 0) BAR;
;   BAR;
	s_waitcnt lgkmcnt(0)
	s_waitcnt lgkmcnt(0)
	v_mfma_f32_16x16x32_bf16 v[60:63], v[148:151], v[164:167], v[60:63]
	v_mfma_f32_16x16x32_bf16 v[56:59], v[156:159], v[164:167], v[56:59]
	v_mfma_f32_16x16x32_bf16 v[52:55], v[148:151], v[172:175], v[52:55]
	v_mfma_f32_16x16x32_bf16 v[48:51], v[156:159], v[172:175], v[48:51]
	v_mfma_f32_16x16x32_bf16 v[36:39], v[148:151], v[180:183], v[36:39]
	v_mfma_f32_16x16x32_bf16 v[32:35], v[156:159], v[180:183], v[32:35]
	v_mfma_f32_16x16x32_bf16 v[20:23], v[148:151], v[188:191], v[20:23]
	v_mfma_f32_16x16x32_bf16 v[16:19], v[156:159], v[188:191], v[16:19]
	v_mfma_f32_16x16x32_bf16 v[60:63], v[152:155], v[168:171], v[60:63]
	v_mfma_f32_16x16x32_bf16 v[56:59], v[160:163], v[168:171], v[56:59]
	v_mfma_f32_16x16x32_bf16 v[52:55], v[152:155], v[176:179], v[52:55]
	v_mfma_f32_16x16x32_bf16 v[48:51], v[160:163], v[176:179], v[48:51]
	v_mfma_f32_16x16x32_bf16 v[36:39], v[152:155], v[184:187], v[36:39]
	v_mfma_f32_16x16x32_bf16 v[32:35], v[160:163], v[184:187], v[32:35]
	v_mfma_f32_16x16x32_bf16 v[20:23], v[152:155], v[192:195], v[20:23]
	v_mfma_f32_16x16x32_bf16 v[16:19], v[160:163], v[192:195], v[16:19]
	s_barrier
	s_add_u32 s16, s20, 0x40080
	s_addc_u32 s17, s21, 0
	s_add_i32 s20, s22, s29
	s_mov_b32 m0, s20
	v_lshl_add_u64 v[148:149], s[16:17], 0, v[130:131]
	global_load_lds_dwordx4 v[148:149], off
	s_add_i32 m0, s20, 0x2000
	v_lshl_add_u64 v[148:149], s[16:17], 0, v[128:129]
	global_load_lds_dwordx4 v[148:149], off
	s_waitcnt vmcnt(6)
	s_barrier
	v_mfma_f32_16x16x32_bf16 v[44:47], v[196:199], v[164:167], v[44:47]
	v_mfma_f32_16x16x32_bf16 v[40:43], v[204:207], v[164:167], v[40:43]
	v_mfma_f32_16x16x32_bf16 v[28:31], v[196:199], v[172:175], v[28:31]
	v_mfma_f32_16x16x32_bf16 v[24:27], v[204:207], v[172:175], v[24:27]
	v_mfma_f32_16x16x32_bf16 v[12:15], v[196:199], v[180:183], v[12:15]
	v_mfma_f32_16x16x32_bf16 v[8:11], v[204:207], v[180:183], v[8:11]
	v_mfma_f32_16x16x32_bf16 v[4:7], v[196:199], v[188:191], v[4:7]
	v_mfma_f32_16x16x32_bf16 v[0:3], v[204:207], v[188:191], v[0:3]
	v_mfma_f32_16x16x32_bf16 v[44:47], v[200:203], v[168:171], v[44:47]
	v_mfma_f32_16x16x32_bf16 v[40:43], v[208:211], v[168:171], v[40:43]
	v_mfma_f32_16x16x32_bf16 v[28:31], v[200:203], v[176:179], v[28:31]
	v_mfma_f32_16x16x32_bf16 v[24:27], v[208:211], v[176:179], v[24:27]
	v_mfma_f32_16x16x32_bf16 v[12:15], v[200:203], v[184:187], v[12:15]
	v_mfma_f32_16x16x32_bf16 v[8:11], v[208:211], v[184:187], v[8:11]
	v_mfma_f32_16x16x32_bf16 v[4:7], v[200:203], v[192:195], v[4:7]
	v_mfma_f32_16x16x32_bf16 v[0:3], v[208:211], v[192:195], v[0:3]
	s_add_i32 s51, s51, 2
	s_add_u32 s49, s49, 0x100
	s_addc_u32 s50, s50, 0
	s_cmp_gt_u32 s51, 13
	s_mov_b64 s[16:17], s[18:19]
	s_barrier
	s_cbranch_scc0 .LBB0_334
	v_lshl_add_u32 v147, s44, 8, v142
	s_lshl_b32 s16, s45, 9
	s_mov_b32 s17, s7
	v_lshl_add_u64 v[148:149], v[132:133], 0, s[16:17]
	v_cvt_pk_bf16_f32 v68, v68, v69
	v_cvt_pk_bf16_f32 v69, v70, v71
	v_cvt_pk_bf16_f32 v70, v64, v65
	v_add_u32_e32 v64, 0x80, v147
	v_mad_i64_i32 v[150:151], s[16:17], v147, s40, v[148:149]
	v_cvt_pk_bf16_f32 v108, v108, v109
	v_cvt_pk_bf16_f32 v109, v110, v111
	v_cvt_pk_bf16_f32 v110, v104, v105
	v_cvt_pk_bf16_f32 v111, v106, v107
	v_or_b32_e32 v104, 16, v147
	v_mad_i64_i32 v[64:65], s[16:17], v64, s40, v[148:149]
	v_cvt_pk_bf16_f32 v44, v44, v45
	v_cvt_pk_bf16_f32 v45, v46, v47
	v_cvt_pk_bf16_f32 v46, v40, v41
	v_cvt_pk_bf16_f32 v47, v42, v43
	v_add_u32_e32 v40, 0x90, v147
	global_store_dwordx4 v[150:151], v[108:111], off offset:256
	v_cvt_pk_bf16_f32 v92, v92, v93
	v_cvt_pk_bf16_f32 v93, v94, v95
	v_mad_i64_i32 v[108:109], s[16:17], v104, s40, v[148:149]
	v_cvt_pk_bf16_f32 v94, v88, v89
	v_cvt_pk_bf16_f32 v95, v90, v91
	v_or_b32_e32 v88, 32, v147
	global_store_dwordx4 v[64:65], v[44:47], off offset:256
	v_cvt_pk_bf16_f32 v28, v28, v29
	v_cvt_pk_bf16_f32 v29, v30, v31
	v_mad_i64_i32 v[44:45], s[16:17], v40, s40, v[148:149]
	v_cvt_pk_bf16_f32 v30, v24, v25
	v_cvt_pk_bf16_f32 v31, v26, v27
	v_add_u32_e32 v24, 0xa0, v147
	global_store_dwordx4 v[108:109], v[92:95], off offset:256
	v_cvt_pk_bf16_f32 v76, v76, v77
	v_cvt_pk_bf16_f32 v77, v78, v79
	v_mad_i64_i32 v[92:93], s[16:17], v88, s40, v[148:149]
	v_cvt_pk_bf16_f32 v78, v72, v73
	v_cvt_pk_bf16_f32 v79, v74, v75
	v_or_b32_e32 v72, 48, v147
	global_store_dwordx4 v[44:45], v[28:31], off offset:256
	v_cvt_pk_bf16_f32 v12, v12, v13
	v_cvt_pk_bf16_f32 v13, v14, v15
	v_mad_i64_i32 v[28:29], s[16:17], v24, s40, v[148:149]
	v_cvt_pk_bf16_f32 v14, v8, v9
	v_cvt_pk_bf16_f32 v15, v10, v11
	v_add_u32_e32 v8, 0xb0, v147
	global_store_dwordx4 v[92:93], v[76:79], off offset:256
	global_store_dwordx4 v[28:29], v[12:15], off offset:256
	v_cvt_pk_bf16_f32 v124, v124, v125
	v_mad_i64_i32 v[76:77], s[16:17], v72, s40, v[148:149]
	v_mad_i64_i32 v[12:13], s[16:17], v8, s40, v[148:149]
	v_cvt_pk_bf16_f32 v125, v126, v127
	v_cvt_pk_bf16_f32 v126, v120, v121
	v_cvt_pk_bf16_f32 v127, v122, v123
	v_cvt_pk_bf16_f32 v104, v116, v117
	v_cvt_pk_bf16_f32 v105, v118, v119
	v_cvt_pk_bf16_f32 v106, v112, v113
	v_cvt_pk_bf16_f32 v107, v114, v115
	v_cvt_pk_bf16_f32 v88, v100, v101
	v_cvt_pk_bf16_f32 v89, v102, v103
	v_cvt_pk_bf16_f32 v90, v96, v97
	v_cvt_pk_bf16_f32 v91, v98, v99
	v_cvt_pk_bf16_f32 v72, v84, v85
	v_cvt_pk_bf16_f32 v73, v86, v87
	v_cvt_pk_bf16_f32 v74, v80, v81
	v_cvt_pk_bf16_f32 v75, v82, v83
	v_cvt_pk_bf16_f32 v71, v66, v67
	v_cvt_pk_bf16_f32 v60, v60, v61
	v_cvt_pk_bf16_f32 v61, v62, v63
	v_cvt_pk_bf16_f32 v62, v56, v57
	v_cvt_pk_bf16_f32 v63, v58, v59
	v_cvt_pk_bf16_f32 v40, v52, v53
	v_cvt_pk_bf16_f32 v41, v54, v55
	v_cvt_pk_bf16_f32 v42, v48, v49
	v_cvt_pk_bf16_f32 v43, v50, v51
	v_cvt_pk_bf16_f32 v24, v36, v37
	v_cvt_pk_bf16_f32 v25, v38, v39
	v_cvt_pk_bf16_f32 v26, v32, v33
	v_cvt_pk_bf16_f32 v27, v34, v35
	v_cvt_pk_bf16_f32 v8, v20, v21
	v_cvt_pk_bf16_f32 v9, v22, v23
	v_cvt_pk_bf16_f32 v10, v16, v17
	v_cvt_pk_bf16_f32 v11, v18, v19
	v_cvt_pk_bf16_f32 v4, v4, v5
	v_cvt_pk_bf16_f32 v5, v6, v7
	v_cvt_pk_bf16_f32 v6, v0, v1
	v_cvt_pk_bf16_f32 v7, v2, v3
	s_and_b64 vcc, exec, s[2:3]
	s_mov_b32 s44, s6
	s_mov_b32 s45, s10
	s_mov_b64 s[18:19], s[14:15]
	s_mov_b64 s[16:17], s[12:13]
	global_store_dwordx4 v[150:151], v[124:127], off
	global_store_dwordx4 v[108:109], v[104:107], off
	global_store_dwordx4 v[92:93], v[88:91], off
	global_store_dwordx4 v[76:77], v[72:75], off
	global_store_dwordx4 v[76:77], v[68:71], off offset:256
	global_store_dwordx4 v[64:65], v[60:63], off
	global_store_dwordx4 v[44:45], v[40:43], off
	global_store_dwordx4 v[28:29], v[24:27], off
	global_store_dwordx4 v[12:13], v[8:11], off
	global_store_dwordx4 v[12:13], v[4:7], off offset:256
	s_cbranch_vccz .LBB0_331
	s_waitcnt vmcnt(0)
	s_cmpk_gt_u32 s24, 0xff
	s_cbranch_scc1 .LBB0_338
	s_barrier

; #define STG(P, GB) do { const char* _gb = (GB); \
;     _Pragma("unroll") for (int _i = 0; _i < 2; ++_i) { \
;       __builtin_amdgcn_global_load_lds((const unsigned*)(_gb + voff[_i]), \
;         (LAS unsigned*)((LAS char*)(P) + ldsw + _i * 8192), 16, 0, 0); } } while (0)
; #define LDA(dst, b, h) _Pragma("unroll") for (int m = 0; m < 4; ++m) _Pragma("unroll") for (int k = 0; k < 2; ++k) \
;     dst[m][k] = *(const LAS bf16x8*)((LAS char*)SA(b, h) + aoff + m * 2048 + k * 1024)
; #define LDB(dst, b, h) _Pragma("unroll") for (int n = 0; n < 2; ++n) _Pragma("unroll") for (int k = 0; k < 2; ++k) \
;     dst[n][k] = *(const LAS bf16x8*)((LAS char*)SB(b, h) + boff + n * 2048 + k * 1024)
; #define MMA(ai, bj, At_, Bt_) do { __builtin_amdgcn_s_setprio(1); \
;     _Pragma("unroll") for (int m = 0; m < 4; ++m) _Pragma("unroll") for (int n = 0; n < 2; ++n) _Pragma("unroll") for (int k = 0; k < 2; ++k) \
;       acc[ai][bj][m][n] = __builtin_amdgcn_mfma_f32_16x16x32_bf16(Bt_[n][k], At_[m][k], acc[ai][bj][m][n], 0, 0, 0); \
;     __builtin_amdgcn_s_setprio(0); } while (0)
; #define WAIT_V(n) asm volatile("s_waitcnt vmcnt(" #n ")" ::: "memory")
; #define WAIT_L(n) asm volatile("s_waitcnt lgkmcnt(" #n ")" ::: "memory")
; #define BAR __builtin_amdgcn_s_barrier()
; #define SCHED __builtin_amdgcn_sched_barrier(0)
; __device__ __forceinline__ void gemm_phase(const bf16_t* __restrict__ A, const bf16_t* __restrict__ Bt, bf16_t* __restrict__ C, int M, int N, int K,
;                                            int ldc, const int EPI, char* smem, const int wid_u) {
;     ...
;       LDB(B0, 0, 0); SCHED; LDA(At, 0, 0); STG(SA(1, 1), a1 + hstep);
;       WAIT_L(8); BAR; WAIT_L(0); MMA(0, 0, At, B0); BAR; SCHED;
;       LDB(B1, 0, 1); STG(SB(0, 0), b2);
;       BAR; WAIT_L(0); MMA(0, 1, At, B1); BAR;
;       LDA(At, 0, 1); STG(SA(0, 0), a2);
;       BAR; WAIT_L(0); MMA(1, 0, At, B0); BAR; SCHED;
;       STG(SB(0, 1), b2 + hstep);
;       WAIT_V(6); BAR; MMA(1, 1, At, B1); BAR;
;       LDB(B0, 1, 0); SCHED; LDA(At, 1, 0); STG(SA(0, 1), a2 + hstep);
;       WAIT_L(8); BAR; WAIT_L(0); MMA(0, 0, At, B0); BAR; SCHED;
;       LDB(B1, 1, 1); STG(SB(1, 0), b3);
;       BAR; WAIT_L(0); MMA(0, 1, At, B1); BAR;
;       LDA(At, 1, 1); STG(SA(1, 0), a3);
;       BAR; WAIT_L(0); MMA(1, 0, At, B0); BAR; SCHED;
;       STG(SB(1, 1), b3 + hstep);
;       WAIT_V(6); BAR; MMA(1, 1, At, B1); BAR;
.LBB0_905:
	ds_read_b128 v[148:151], v144
	ds_read_b128 v[152:155], v144 offset:1024
	ds_read_b128 v[156:159], v144 offset:2048
	ds_read_b128 v[160:163], v144 offset:3072
	s_add_u32 s18, s16, 0x100
	s_addc_u32 s19, s17, 0
	s_cmp_eq_u32 s55, 12
	s_cselect_b32 s23, s49, s19
	s_cselect_b32 s22, s50, s18
	s_cselect_b32 s21, s51, s54
	s_cselect_b32 s20, s52, s53
	s_mov_b32 m0, s38
	v_lshl_add_u64 v[196:197], s[16:17], 0, v[136:137]
	ds_read_b128 v[164:167], v145
	ds_read_b128 v[168:171], v145 offset:1024
	ds_read_b128 v[172:175], v145 offset:2048
	ds_read_b128 v[176:179], v145 offset:3072
	ds_read_b128 v[180:183], v145 offset:4096
	ds_read_b128 v[184:187], v145 offset:5120
	ds_read_b128 v[188:191], v145 offset:6144
	ds_read_b128 v[192:195], v145 offset:7168
	global_load_lds_dwordx4 v[196:197], off
	s_mov_b32 m0, s39
	v_lshl_add_u64 v[196:197], s[16:17], 0, v[134:135]
	global_load_lds_dwordx4 v[196:197], off
	s_waitcnt lgkmcnt(8)
	s_barrier
	s_waitcnt lgkmcnt(0)
	s_waitcnt lgkmcnt(0)
	v_mfma_f32_16x16x32_bf16 v[124:127], v[148:151], v[164:167], v[124:127]
	v_mfma_f32_16x16x32_bf16 v[120:123], v[156:159], v[164:167], v[120:123]
	v_mfma_f32_16x16x32_bf16 v[116:119], v[148:151], v[172:175], v[116:119]
	v_mfma_f32_16x16x32_bf16 v[112:115], v[156:159], v[172:175], v[112:115]
	v_mfma_f32_16x16x32_bf16 v[100:103], v[148:151], v[180:183], v[100:103]
	v_mfma_f32_16x16x32_bf16 v[96:99], v[156:159], v[180:183], v[96:99]
	v_mfma_f32_16x16x32_bf16 v[84:87], v[148:151], v[188:191], v[84:87]
	v_mfma_f32_16x16x32_bf16 v[80:83], v[156:159], v[188:191], v[80:83]
	v_mfma_f32_16x16x32_bf16 v[124:127], v[152:155], v[168:171], v[124:127]
	v_mfma_f32_16x16x32_bf16 v[120:123], v[160:163], v[168:171], v[120:123]
	v_mfma_f32_16x16x32_bf16 v[116:119], v[152:155], v[176:179], v[116:119]
	v_mfma_f32_16x16x32_bf16 v[112:115], v[160:163], v[176:179], v[112:115]
	v_mfma_f32_16x16x32_bf16 v[100:103], v[152:155], v[184:187], v[100:103]
	v_mfma_f32_16x16x32_bf16 v[96:99], v[160:163], v[184:187], v[96:99]
	v_mfma_f32_16x16x32_bf16 v[84:87], v[152:155], v[192:195], v[84:87]
	v_mfma_f32_16x16x32_bf16 v[80:83], v[160:163], v[192:195], v[80:83]
	s_barrier
	s_mov_b32 m0, s40
	v_lshl_add_u64 v[212:213], s[20:21], 0, v[130:131]
	ds_read_b128 v[196:199], v146
	ds_read_b128 v[200:203], v146 offset:1024
	ds_read_b128 v[204:207], v146 offset:2048
	ds_read_b128 v[208:211], v146 offset:3072
	global_load_lds_dwordx4 v[212:213], off
	s_mov_b32 m0, s41
	v_lshl_add_u64 v[214:215], s[20:21], 0, v[128:129]
	global_load_lds_dwordx4 v[214:215], off
	s_barrier
	s_waitcnt lgkmcnt(0)
	s_waitcnt lgkmcnt(0)
	v_mfma_f32_16x16x32_bf16 v[108:111], v[196:199], v[164:167], v[108:111]
	v_mfma_f32_16x16x32_bf16 v[104:107], v[204:207], v[164:167], v[104:107]
	v_mfma_f32_16x16x32_bf16 v[92:95], v[196:199], v[172:175], v[92:95]
	v_mfma_f32_16x16x32_bf16 v[88:91], v[204:207], v[172:175], v[88:91]
	v_mfma_f32_16x16x32_bf16 v[76:79], v[196:199], v[180:183], v[76:79]
	v_mfma_f32_16x16x32_bf16 v[72:75], v[204:207], v[180:183], v[72:75]
	v_mfma_f32_16x16x32_bf16 v[68:71], v[196:199], v[188:191], v[68:71]
	v_mfma_f32_16x16x32_bf16 v[64:67], v[204:207], v[188:191], v[64:67]
	v_mfma_f32_16x16x32_bf16 v[108:111], v[200:203], v[168:171], v[108:111]
	v_mfma_f32_16x16x32_bf16 v[104:107], v[208:211], v[168:171], v[104:107]
	v_mfma_f32_16x16x32_bf16 v[92:95], v[200:203], v[176:179], v[92:95]
	v_mfma_f32_16x16x32_bf16 v[88:91], v[208:211], v[176:179], v[88:91]
	v_mfma_f32_16x16x32_bf16 v[76:79], v[200:203], v[184:187], v[76:79]
	v_mfma_f32_16x16x32_bf16 v[72:75], v[208:211], v[184:187], v[72:75]
	v_mfma_f32_16x16x32_bf16 v[68:71], v[200:203], v[192:195], v[68:71]
	v_mfma_f32_16x16x32_bf16 v[64:67], v[208:211], v[192:195], v[64:67]
	s_mov_b32 m0, s30
	v_lshl_add_u64 v[216:217], s[22:23], 0, v[130:131]
	s_barrier
	ds_read_b128 v[164:167], v145 offset:16384
	ds_read_b128 v[168:171], v145 offset:17408
	ds_read_b128 v[172:175], v145 offset:18432
	ds_read_b128 v[176:179], v145 offset:19456
	ds_read_b128 v[180:183], v145 offset:20480
	ds_read_b128 v[184:187], v145 offset:21504
	ds_read_b128 v[188:191], v145 offset:22528
	ds_read_b128 v[192:195], v145 offset:23552
	global_load_lds_dwordx4 v[216:217], off
	s_mov_b32 m0, s31
	v_lshl_add_u64 v[218:219], s[22:23], 0, v[128:129]
	global_load_lds_dwordx4 v[218:219], off
	s_barrier
	s_waitcnt lgkmcnt(0)
	s_waitcnt lgkmcnt(0)
	v_mfma_f32_16x16x32_bf16 v[60:63], v[148:151], v[164:167], v[60:63]
	v_mfma_f32_16x16x32_bf16 v[56:59], v[156:159], v[164:167], v[56:59]
	v_mfma_f32_16x16x32_bf16 v[52:55], v[148:151], v[172:175], v[52:55]
	v_mfma_f32_16x16x32_bf16 v[48:51], v[156:159], v[172:175], v[48:51]
	v_mfma_f32_16x16x32_bf16 v[36:39], v[148:151], v[180:183], v[36:39]
	v_mfma_f32_16x16x32_bf16 v[32:35], v[156:159], v[180:183], v[32:35]
	v_mfma_f32_16x16x32_bf16 v[20:23], v[148:151], v[188:191], v[20:23]
	v_mfma_f32_16x16x32_bf16 v[16:19], v[156:159], v[188:191], v[16:19]
	v_mfma_f32_16x16x32_bf16 v[60:63], v[152:155], v[168:171], v[60:63]
	v_mfma_f32_16x16x32_bf16 v[56:59], v[160:163], v[168:171], v[56:59]
	v_mfma_f32_16x16x32_bf16 v[52:55], v[152:155], v[176:179], v[52:55]
	v_mfma_f32_16x16x32_bf16 v[48:51], v[160:163], v[176:179], v[48:51]
	v_mfma_f32_16x16x32_bf16 v[36:39], v[152:155], v[184:187], v[36:39]
	v_mfma_f32_16x16x32_bf16 v[32:35], v[160:163], v[184:187], v[32:35]
	v_mfma_f32_16x16x32_bf16 v[20:23], v[152:155], v[192:195], v[20:23]
	v_mfma_f32_16x16x32_bf16 v[16:19], v[160:163], v[192:195], v[16:19]
	s_barrier
	s_add_u32 s16, s20, 0x40000
	s_addc_u32 s17, s21, 0
	s_mov_b32 m0, s44
	v_lshl_add_u64 v[148:149], s[16:17], 0, v[130:131]
	global_load_lds_dwordx4 v[148:149], off
	s_add_i32 m0, s44, 0x2000
	v_lshl_add_u64 v[148:149], s[16:17], 0, v[128:129]
	global_load_lds_dwordx4 v[148:149], off
	s_waitcnt vmcnt(6)
	s_barrier
; #define STG(P, GB) do { const char* _gb = (GB); \
;     _Pragma("unroll") for (int _i = 0; _i < 2; ++_i) { \
;       __builtin_amdgcn_global_load_lds((const unsigned*)(_gb + voff[_i]), \
;         (LAS unsigned*)((LAS char*)(P) + ldsw + _i * 8192), 16, 0, 0); } } while (0)
; #define LDA(dst, b, h) _Pragma("unroll") for (int m = 0; m < 4; ++m) _Pragma("unroll") for (int k = 0; k < 2; ++k) \
;     dst[m][k] = *(const LAS bf16x8*)((LAS char*)SA(b, h) + aoff + m * 2048 + k * 1024)
; #define LDB(dst, b, h) _Pragma("unroll") for (int n = 0; n < 2; ++n) _Pragma("unroll") for (int k = 0; k < 2; ++k) \
;     dst[n][k] = *(const LAS bf16x8*)((LAS char*)SB(b, h) + boff + n * 2048 + k * 1024)
; #define MMA(ai, bj, At_, Bt_) do { __builtin_amdgcn_s_setprio(1); \
;     _Pragma("unroll") for (int m = 0; m < 4; ++m) _Pragma("unroll") for (int n = 0; n < 2; ++n) _Pragma("unroll") for (int k = 0; k < 2; ++k) \
;       acc[ai][bj][m][n] = __builtin_amdgcn_mfma_f32_16x16x32_bf16(Bt_[n][k], At_[m][k], acc[ai][bj][m][n], 0, 0, 0); \
;     __builtin_amdgcn_s_setprio(0); } while (0)
; #define WAIT_V(n) asm volatile("s_waitcnt vmcnt(" #n ")" ::: "memory")
; #define WAIT_L(n) asm volatile("s_waitcnt lgkmcnt(" #n ")" ::: "memory")
; #define BAR __builtin_amdgcn_s_barrier()
; #define SCHED __builtin_amdgcn_sched_barrier(0)
; __device__ __forceinline__ void gemm_phase(const bf16_t* __restrict__ A, const bf16_t* __restrict__ Bt, bf16_t* __restrict__ C, int M, int N, int K,
;                                            int ldc, const int EPI, char* smem, const int wid_u) {
;     ...
;       LDB(B0, 0, 0); SCHED; LDA(At, 0, 0); STG(SA(1, 1), a1 + hstep);
;       WAIT_L(8); BAR; WAIT_L(0); MMA(0, 0, At, B0); BAR; SCHED;
;       LDB(B1, 0, 1); STG(SB(0, 0), b2);
;       BAR; WAIT_L(0); MMA(0, 1, At, B1); BAR;
;       LDA(At, 0, 1); STG(SA(0, 0), a2);
;       BAR; WAIT_L(0); MMA(1, 0, At, B0); BAR; SCHED;
;       STG(SB(0, 1), b2 + hstep);
;       WAIT_V(6); BAR; MMA(1, 1, At, B1); BAR;
;       LDB(B0, 1, 0); SCHED; LDA(At, 1, 0); STG(SA(0, 1), a2 + hstep);
;       WAIT_L(8); BAR; WAIT_L(0); MMA(0, 0, At, B0); BAR; SCHED;
;       LDB(B1, 1, 1); STG(SB(1, 0), b3);
;       BAR; WAIT_L(0); MMA(0, 1, At, B1); BAR;
;       LDA(At, 1, 1); STG(SA(1, 0), a3);
;       BAR; WAIT_L(0); MMA(1, 0, At, B0); BAR; SCHED;
;       STG(SB(1, 1), b3 + hstep);
;       WAIT_V(6); BAR; MMA(1, 1, At, B1); BAR;
	v_mfma_f32_16x16x32_bf16 v[44:47], v[196:199], v[164:167], v[44:47]
	v_mfma_f32_16x16x32_bf16 v[40:43], v[204:207], v[164:167], v[40:43]
	v_mfma_f32_16x16x32_bf16 v[28:31], v[196:199], v[172:175], v[28:31]
	v_mfma_f32_16x16x32_bf16 v[24:27], v[204:207], v[172:175], v[24:27]
	v_mfma_f32_16x16x32_bf16 v[12:15], v[196:199], v[180:183], v[12:15]
	v_mfma_f32_16x16x32_bf16 v[8:11], v[204:207], v[180:183], v[8:11]
	v_mfma_f32_16x16x32_bf16 v[4:7], v[196:199], v[188:191], v[4:7]
	v_mfma_f32_16x16x32_bf16 v[0:3], v[204:207], v[188:191], v[0:3]
	v_mfma_f32_16x16x32_bf16 v[44:47], v[200:203], v[168:171], v[44:47]
	v_mfma_f32_16x16x32_bf16 v[40:43], v[208:211], v[168:171], v[40:43]
	v_mfma_f32_16x16x32_bf16 v[28:31], v[200:203], v[176:179], v[28:31]
	v_mfma_f32_16x16x32_bf16 v[24:27], v[208:211], v[176:179], v[24:27]
	v_mfma_f32_16x16x32_bf16 v[12:15], v[200:203], v[184:187], v[12:15]
	v_mfma_f32_16x16x32_bf16 v[8:11], v[208:211], v[184:187], v[8:11]
	v_mfma_f32_16x16x32_bf16 v[4:7], v[200:203], v[192:195], v[4:7]
	v_mfma_f32_16x16x32_bf16 v[0:3], v[208:211], v[192:195], v[0:3]
	s_add_i32 s56, 0, 0x18000
	v_add_u32_e32 v147, s56, v143
	s_barrier
	ds_read_b128 v[148:151], v147
	ds_read_b128 v[152:155], v147 offset:1024
	ds_read_b128 v[156:159], v147 offset:2048
	ds_read_b128 v[160:163], v147 offset:3072
	s_add_u32 s16, s22, 0x40000
	s_addc_u32 s17, s23, 0
	s_mov_b32 m0, s34
	v_lshl_add_u64 v[196:197], s[16:17], 0, v[130:131]
	ds_read_b128 v[164:167], v145 offset:32768
	ds_read_b128 v[168:171], v145 offset:33792
	ds_read_b128 v[172:175], v145 offset:34816
	ds_read_b128 v[176:179], v145 offset:35840
	ds_read_b128 v[180:183], v145 offset:36864
	ds_read_b128 v[184:187], v145 offset:37888
	ds_read_b128 v[188:191], v145 offset:38912
	ds_read_b128 v[192:195], v145 offset:39936
	global_load_lds_dwordx4 v[196:197], off
	s_mov_b32 m0, s35
	v_lshl_add_u64 v[196:197], s[16:17], 0, v[128:129]
	global_load_lds_dwordx4 v[196:197], off
	s_waitcnt lgkmcnt(8)
	s_barrier
	s_waitcnt lgkmcnt(0)
	s_waitcnt lgkmcnt(0)
	v_mfma_f32_16x16x32_bf16 v[124:127], v[148:151], v[164:167], v[124:127]
	v_mfma_f32_16x16x32_bf16 v[120:123], v[156:159], v[164:167], v[120:123]
	v_mfma_f32_16x16x32_bf16 v[116:119], v[148:151], v[172:175], v[116:119]
	v_mfma_f32_16x16x32_bf16 v[112:115], v[156:159], v[172:175], v[112:115]
	v_mfma_f32_16x16x32_bf16 v[100:103], v[148:151], v[180:183], v[100:103]
	v_mfma_f32_16x16x32_bf16 v[96:99], v[156:159], v[180:183], v[96:99]
	v_mfma_f32_16x16x32_bf16 v[84:87], v[148:151], v[188:191], v[84:87]
	v_mfma_f32_16x16x32_bf16 v[80:83], v[156:159], v[188:191], v[80:83]
	v_mfma_f32_16x16x32_bf16 v[124:127], v[152:155], v[168:171], v[124:127]
	v_mfma_f32_16x16x32_bf16 v[120:123], v[160:163], v[168:171], v[120:123]
	v_mfma_f32_16x16x32_bf16 v[116:119], v[152:155], v[176:179], v[116:119]
	v_mfma_f32_16x16x32_bf16 v[112:115], v[160:163], v[176:179], v[112:115]
	v_mfma_f32_16x16x32_bf16 v[100:103], v[152:155], v[184:187], v[100:103]
	v_mfma_f32_16x16x32_bf16 v[96:99], v[160:163], v[184:187], v[96:99]
	v_mfma_f32_16x16x32_bf16 v[84:87], v[152:155], v[192:195], v[84:87]
	v_mfma_f32_16x16x32_bf16 v[80:83], v[160:163], v[192:195], v[80:83]
	s_barrier
	s_add_i32 s22, 0, 0x1c000
	s_add_i32 s16, s56, s29
	v_add_u32_e32 v147, s22, v143
	v_lshl_add_u64 v[212:213], v[212:213], 0, s[10:11]
	s_mov_b32 m0, s16
	ds_read_b128 v[196:199], v147
	ds_read_b128 v[200:203], v147 offset:1024
	ds_read_b128 v[204:207], v147 offset:2048
	ds_read_b128 v[208:211], v147 offset:3072
	global_load_lds_dwordx4 v[212:213], off
	s_add_i32 m0, s16, 0x2000
	v_lshl_add_u64 v[212:213], v[214:215], 0, s[10:11]
	global_load_lds_dwordx4 v[212:213], off
	s_barrier
	s_waitcnt lgkmcnt(0)
	s_waitcnt lgkmcnt(0)
	v_mfma_f32_16x16x32_bf16 v[108:111], v[196:199], v[164:167], v[108:111]
	v_mfma_f32_16x16x32_bf16 v[104:107], v[204:207], v[164:167], v[104:107]
	v_mfma_f32_16x16x32_bf16 v[92:95], v[196:199], v[172:175], v[92:95]
	v_mfma_f32_16x16x32_bf16 v[88:91], v[204:207], v[172:175], v[88:91]
	v_mfma_f32_16x16x32_bf16 v[76:79], v[196:199], v[180:183], v[76:79]
	v_mfma_f32_16x16x32_bf16 v[72:75], v[204:207], v[180:183], v[72:75]
	v_mfma_f32_16x16x32_bf16 v[68:71], v[196:199], v[188:191], v[68:71]
	v_mfma_f32_16x16x32_bf16 v[64:67], v[204:207], v[188:191], v[64:67]
	v_mfma_f32_16x16x32_bf16 v[108:111], v[200:203], v[168:171], v[108:111]
	v_mfma_f32_16x16x32_bf16 v[104:107], v[208:211], v[168:171], v[104:107]
	v_mfma_f32_16x16x32_bf16 v[92:95], v[200:203], v[176:179], v[92:95]
	v_mfma_f32_16x16x32_bf16 v[88:91], v[208:211], v[176:179], v[88:91]
	v_mfma_f32_16x16x32_bf16 v[76:79], v[200:203], v[184:187], v[76:79]
	v_mfma_f32_16x16x32_bf16 v[72:75], v[208:211], v[184:187], v[72:75]
	v_mfma_f32_16x16x32_bf16 v[68:71], v[200:203], v[192:195], v[68:71]
	v_mfma_f32_16x16x32_bf16 v[64:67], v[208:211], v[192:195], v[64:67]
	s_mov_b32 m0, s36
	v_lshl_add_u64 v[212:213], v[216:217], 0, s[10:11]
	s_barrier
	ds_read_b128 v[164:167], v145 offset:49152
	ds_read_b128 v[168:171], v145 offset:50176
	ds_read_b128 v[172:175], v145 offset:51200
	ds_read_b128 v[176:179], v145 offset:52224
	ds_read_b128 v[180:183], v145 offset:53248
	ds_read_b128 v[184:187], v145 offset:54272
	ds_read_b128 v[188:191], v145 offset:55296
	ds_read_b128 v[192:195], v145 offset:56320
	global_load_lds_dwordx4 v[212:213], off
	s_mov_b32 m0, s37
	v_lshl_add_u64 v[212:213], v[218:219], 0, s[10:11]
	global_load_lds_dwordx4 v[212:213], off
	s_barrier
; #define STG(P, GB) do { const char* _gb = (GB); \
;     _Pragma("unroll") for (int _i = 0; _i < 2; ++_i) { \
;       __builtin_amdgcn_global_load_lds((const unsigned*)(_gb + voff[_i]), \
;         (LAS unsigned*)((LAS char*)(P) + ldsw + _i * 8192), 16, 0, 0); } } while (0)
; #define LDA(dst, b, h) _Pragma("unroll") for (int m = 0; m < 4; ++m) _Pragma("unroll") for (int k = 0; k < 2; ++k) \
;     dst[m][k] = *(const LAS bf16x8*)((LAS char*)SA(b, h) + aoff + m * 2048 + k * 1024)
; #define MMA(ai, bj, At_, Bt_) do { __builtin_amdgcn_s_setprio(1); \
;     _Pragma("unroll") for (int m = 0; m < 4; ++m) _Pragma("unroll") for (int n = 0; n < 2; ++n) _Pragma("unroll") for (int k = 0; k < 2; ++k) \
;       acc[ai][bj][m][n] = __builtin_amdgcn_mfma_f32_16x16x32_bf16(Bt_[n][k], At_[m][k], acc[ai][bj][m][n], 0, 0, 0); \
;     __builtin_amdgcn_s_setprio(0); } while (0)
; #define WAIT_V(n) asm volatile("s_waitcnt vmcnt(" #n ")" ::: "memory")
; #define WAIT_L(n) asm volatile("s_waitcnt lgkmcnt(" #n ")" ::: "memory")
; #define BAR __builtin_amdgcn_s_barrier()
; #define SCHED __builtin_amdgcn_sched_barrier(0)
; __device__ __forceinline__ void gemm_phase(const bf16_t* __restrict__ A, const bf16_t* __restrict__ Bt, bf16_t* __restrict__ C, int M, int N, int K,
;                                            int ldc, const int EPI, char* smem, const int wid_u) {
;     ...
;       BAR; WAIT_L(0); MMA(0, 1, At, B1); BAR;
;       LDA(At, 1, 1); STG(SA(1, 0), a3);
;       BAR; WAIT_L(0); MMA(1, 0, At, B0); BAR; SCHED;
;       STG(SB(1, 1), b3 + hstep);
;       WAIT_V(6); BAR; MMA(1, 1, At, B1); BAR;
	s_waitcnt lgkmcnt(0)
	s_waitcnt lgkmcnt(0)
	v_mfma_f32_16x16x32_bf16 v[60:63], v[148:151], v[164:167], v[60:63]
	v_mfma_f32_16x16x32_bf16 v[56:59], v[156:159], v[164:167], v[56:59]
	v_mfma_f32_16x16x32_bf16 v[52:55], v[148:151], v[172:175], v[52:55]
	v_mfma_f32_16x16x32_bf16 v[48:51], v[156:159], v[172:175], v[48:51]
	v_mfma_f32_16x16x32_bf16 v[36:39], v[148:151], v[180:183], v[36:39]
	v_mfma_f32_16x16x32_bf16 v[32:35], v[156:159], v[180:183], v[32:35]
	v_mfma_f32_16x16x32_bf16 v[20:23], v[148:151], v[188:191], v[20:23]
	v_mfma_f32_16x16x32_bf16 v[16:19], v[156:159], v[188:191], v[16:19]
	v_mfma_f32_16x16x32_bf16 v[60:63], v[152:155], v[168:171], v[60:63]
	v_mfma_f32_16x16x32_bf16 v[56:59], v[160:163], v[168:171], v[56:59]
	v_mfma_f32_16x16x32_bf16 v[52:55], v[152:155], v[176:179], v[52:55]
	v_mfma_f32_16x16x32_bf16 v[48:51], v[160:163], v[176:179], v[48:51]
	v_mfma_f32_16x16x32_bf16 v[36:39], v[152:155], v[184:187], v[36:39]
	v_mfma_f32_16x16x32_bf16 v[32:35], v[160:163], v[184:187], v[32:35]
	v_mfma_f32_16x16x32_bf16 v[20:23], v[152:155], v[192:195], v[20:23]
	v_mfma_f32_16x16x32_bf16 v[16:19], v[160:163], v[192:195], v[16:19]
	s_barrier
	s_add_u32 s16, s20, 0x40080
	s_addc_u32 s17, s21, 0
	s_add_i32 s20, s22, s29
	s_mov_b32 m0, s20
	v_lshl_add_u64 v[148:149], s[16:17], 0, v[130:131]
	global_load_lds_dwordx4 v[148:149], off
	s_add_i32 m0, s20, 0x2000
	v_lshl_add_u64 v[148:149], s[16:17], 0, v[128:129]
	global_load_lds_dwordx4 v[148:149], off
	s_waitcnt vmcnt(6)
	s_barrier
	v_mfma_f32_16x16x32_bf16 v[44:47], v[196:199], v[164:167], v[44:47]
	v_mfma_f32_16x16x32_bf16 v[40:43], v[204:207], v[164:167], v[40:43]
	v_mfma_f32_16x16x32_bf16 v[28:31], v[196:199], v[172:175], v[28:31]
	v_mfma_f32_16x16x32_bf16 v[24:27], v[204:207], v[172:175], v[24:27]
	v_mfma_f32_16x16x32_bf16 v[12:15], v[196:199], v[180:183], v[12:15]
	v_mfma_f32_16x16x32_bf16 v[8:11], v[204:207], v[180:183], v[8:11]
	v_mfma_f32_16x16x32_bf16 v[4:7], v[196:199], v[188:191], v[4:7]
	v_mfma_f32_16x16x32_bf16 v[0:3], v[204:207], v[188:191], v[0:3]
	v_mfma_f32_16x16x32_bf16 v[44:47], v[200:203], v[168:171], v[44:47]
	v_mfma_f32_16x16x32_bf16 v[40:43], v[208:211], v[168:171], v[40:43]
	v_mfma_f32_16x16x32_bf16 v[28:31], v[200:203], v[176:179], v[28:31]
	v_mfma_f32_16x16x32_bf16 v[24:27], v[208:211], v[176:179], v[24:27]
	v_mfma_f32_16x16x32_bf16 v[12:15], v[200:203], v[184:187], v[12:15]
	v_mfma_f32_16x16x32_bf16 v[8:11], v[208:211], v[184:187], v[8:11]
	v_mfma_f32_16x16x32_bf16 v[4:7], v[200:203], v[192:195], v[4:7]
	v_mfma_f32_16x16x32_bf16 v[0:3], v[208:211], v[192:195], v[0:3]
	s_add_i32 s55, s55, 2
	s_add_u32 s53, s53, 0x100
	s_addc_u32 s54, s54, 0
	s_cmp_gt_u32 s55, 13
	s_mov_b64 s[16:17], s[18:19]
	s_barrier
	s_cbranch_scc0 .LBB0_905
; #define WAIT_V(n) asm volatile("s_waitcnt vmcnt(" #n ")" ::: "memory")
; #define BAR __builtin_amdgcn_s_barrier()
; __device__ __forceinline__ void gemm_phase(const bf16_t* __restrict__ A, const bf16_t* __restrict__ Bt, bf16_t* __restrict__ C, int M, int N, int K,
;                                            int ldc, const int EPI, char* smem, const int wid_u) {
;     ...
;       const int brow = pm * BM, bcol = pn * BM;
; #pragma unroll
;       for (int ai = 0; ai < 2; ++ai)
; #pragma unroll
;         for (int m = 0; m < 4; ++m) {
;           const size_t row = (size_t)(brow + ai * HALF + wr * 64 + m * 16 + fr);
;           if (EPI == 0) {
; #pragma unroll
;             for (int bj = 0; bj < 2; ++bj) {
;               const f32x4 v0 = acc[ai][bj][m][0], v1 = acc[ai][bj][m][1];
;               uint4 u; u.x = cvt_pk_bf16(v0[0], v0[1]); u.y = cvt_pk_bf16(v0[2], v0[3]); u.z = cvt_pk_bf16(v1[0], v1[1]); u.w = cvt_pk_bf16(v1[2], v1[3]);
;               *(uint4*)(C + row * ldc + bcol + bj * HALF + wc * 32 + fq * 8) = u;
;             }
;           } else {
;             float o[8];
; #pragma unroll
;             for (int n = 0; n < 2; ++n) {
;               const f32x4 a = acc[ai][0][m][n], b = acc[ai][1][m][n];
; #pragma unroll
;               for (int j = 0; j < 4; ++j) o[n * 4 + j] = a[j] * __builtin_amdgcn_rcpf(1.f + __expf(-a[j])) * b[j];
;             }
;             *(uint4*)(C + row * ldc + (bcol >> 1) + wc * 32 + fq * 8) = pack8(o);
;           }
;         }
;     }
;     if (!has_next) break;
; #pragma unroll
;     for (int a = 0; a < 2; ++a)
; #pragma unroll
;       for (int b = 0; b < 2; ++b)
; #pragma unroll
;         for (int m = 0; m < 4; ++m)
; #pragma unroll
;           for (int n = 0; n < 2; ++n) acc[a][b][m][n] = (f32x4){0.f, 0.f, 0.f, 0.f};
;     pm = npm; pn = npn; cA = nA; cB = nB; ++ui;
;   }
;   WAIT_V(0);
;   if (wr == 0) BAR;
;   BAR;
	v_lshl_add_u32 v148, s47, 8, v142
	v_cvt_pk_bf16_f32 v68, v68, v69
	v_cvt_pk_bf16_f32 v69, v70, v71
	v_cvt_pk_bf16_f32 v70, v64, v65
	v_add_u32_e32 v64, 0x80, v148
	s_lshl_b32 s16, s48, 9
	s_mov_b32 s17, s9
	v_ashrrev_i32_e32 v149, 31, v148
	v_cvt_pk_bf16_f32 v108, v108, v109
	v_cvt_pk_bf16_f32 v109, v110, v111
	v_cvt_pk_bf16_f32 v110, v104, v105
	v_or_b32_e32 v104, 16, v148
	v_ashrrev_i32_e32 v65, 31, v64
	v_cvt_pk_bf16_f32 v44, v44, v45
	v_cvt_pk_bf16_f32 v45, v46, v47
	v_cvt_pk_bf16_f32 v46, v40, v41
	v_add_u32_e32 v40, 0x90, v148
	v_lshl_add_u64 v[150:151], v[132:133], 0, s[16:17]
	v_lshlrev_b64 v[152:153], 11, v[148:149]
	v_ashrrev_i32_e32 v105, 31, v104
	v_cvt_pk_bf16_f32 v92, v92, v93
	v_cvt_pk_bf16_f32 v93, v94, v95
	v_cvt_pk_bf16_f32 v94, v88, v89
	v_or_b32_e32 v88, 32, v148
	v_lshlrev_b64 v[64:65], 11, v[64:65]
	v_ashrrev_i32_e32 v41, 31, v40
	v_cvt_pk_bf16_f32 v28, v28, v29
	v_cvt_pk_bf16_f32 v29, v30, v31
	v_cvt_pk_bf16_f32 v30, v24, v25
	v_add_u32_e32 v24, 0xa0, v148
	v_lshl_add_u64 v[152:153], v[150:151], 0, v[152:153]
	v_cvt_pk_bf16_f32 v111, v106, v107
	v_lshlrev_b64 v[104:105], 11, v[104:105]
	v_ashrrev_i32_e32 v89, 31, v88
	v_cvt_pk_bf16_f32 v76, v76, v77
	v_cvt_pk_bf16_f32 v77, v78, v79
	v_cvt_pk_bf16_f32 v78, v72, v73
	v_or_b32_e32 v72, 48, v148
	v_lshl_add_u64 v[64:65], v[150:151], 0, v[64:65]
	v_cvt_pk_bf16_f32 v47, v42, v43
	v_lshlrev_b64 v[40:41], 11, v[40:41]
	v_ashrrev_i32_e32 v25, 31, v24
	v_cvt_pk_bf16_f32 v12, v12, v13
	v_cvt_pk_bf16_f32 v13, v14, v15
	v_cvt_pk_bf16_f32 v14, v8, v9
	v_add_u32_e32 v8, 0xb0, v148
	global_store_dwordx4 v[152:153], v[108:111], off offset:256
	v_cvt_pk_bf16_f32 v95, v90, v91
	v_lshlrev_b64 v[88:89], 11, v[88:89]
	v_lshl_add_u64 v[108:109], v[150:151], 0, v[104:105]
	v_ashrrev_i32_e32 v73, 31, v72
	global_store_dwordx4 v[64:65], v[44:47], off offset:256
	v_cvt_pk_bf16_f32 v31, v26, v27
	v_lshlrev_b64 v[24:25], 11, v[24:25]
	v_lshl_add_u64 v[44:45], v[150:151], 0, v[40:41]
	v_ashrrev_i32_e32 v9, 31, v8
	global_store_dwordx4 v[108:109], v[92:95], off offset:256
	v_cvt_pk_bf16_f32 v79, v74, v75
	v_lshlrev_b64 v[72:73], 11, v[72:73]
	v_lshl_add_u64 v[92:93], v[150:151], 0, v[88:89]
	global_store_dwordx4 v[44:45], v[28:31], off offset:256
	v_cvt_pk_bf16_f32 v15, v10, v11
	v_lshlrev_b64 v[8:9], 11, v[8:9]
	v_lshl_add_u64 v[28:29], v[150:151], 0, v[24:25]
	v_cvt_pk_bf16_f32 v124, v124, v125
	v_cvt_pk_bf16_f32 v125, v126, v127
	v_cvt_pk_bf16_f32 v126, v120, v121
	v_cvt_pk_bf16_f32 v127, v122, v123
	v_cvt_pk_bf16_f32 v104, v116, v117
	v_cvt_pk_bf16_f32 v105, v118, v119
	v_cvt_pk_bf16_f32 v106, v112, v113
	v_cvt_pk_bf16_f32 v107, v114, v115
	v_cvt_pk_bf16_f32 v88, v100, v101
	v_cvt_pk_bf16_f32 v89, v102, v103
	v_cvt_pk_bf16_f32 v90, v96, v97
	v_cvt_pk_bf16_f32 v91, v98, v99
	global_store_dwordx4 v[92:93], v[76:79], off offset:256
	v_cvt_pk_bf16_f32 v74, v80, v81
	v_cvt_pk_bf16_f32 v75, v82, v83
	v_lshl_add_u64 v[76:77], v[150:151], 0, v[72:73]
	v_cvt_pk_bf16_f32 v72, v84, v85
	v_cvt_pk_bf16_f32 v73, v86, v87
	v_cvt_pk_bf16_f32 v71, v66, v67
	v_cvt_pk_bf16_f32 v60, v60, v61
	v_cvt_pk_bf16_f32 v61, v62, v63
	v_cvt_pk_bf16_f32 v62, v56, v57
	v_cvt_pk_bf16_f32 v63, v58, v59
	v_cvt_pk_bf16_f32 v40, v52, v53
	v_cvt_pk_bf16_f32 v41, v54, v55
	v_cvt_pk_bf16_f32 v42, v48, v49
	v_cvt_pk_bf16_f32 v43, v50, v51
	v_cvt_pk_bf16_f32 v24, v36, v37
	v_cvt_pk_bf16_f32 v25, v38, v39
	v_cvt_pk_bf16_f32 v26, v32, v33
	v_cvt_pk_bf16_f32 v27, v34, v35
	global_store_dwordx4 v[28:29], v[12:15], off offset:256
	v_cvt_pk_bf16_f32 v10, v16, v17
	v_cvt_pk_bf16_f32 v11, v18, v19
	v_lshl_add_u64 v[12:13], v[150:151], 0, v[8:9]
	v_cvt_pk_bf16_f32 v8, v20, v21
	v_cvt_pk_bf16_f32 v9, v22, v23
	v_cvt_pk_bf16_f32 v4, v4, v5
	v_cvt_pk_bf16_f32 v5, v6, v7
	v_cvt_pk_bf16_f32 v6, v0, v1
	v_cvt_pk_bf16_f32 v7, v2, v3
	s_and_b64 vcc, exec, s[4:5]
	s_mov_b32 s47, s8
	s_mov_b32 s48, s46
	s_mov_b64 s[18:19], s[14:15]
	s_mov_b64 s[16:17], s[12:13]
	global_store_dwordx4 v[152:153], v[124:127], off
	global_store_dwordx4 v[108:109], v[104:107], off
	global_store_dwordx4 v[92:93], v[88:91], off
	global_store_dwordx4 v[76:77], v[72:75], off
	global_store_dwordx4 v[76:77], v[68:71], off offset:256
	global_store_dwordx4 v[64:65], v[60:63], off
	global_store_dwordx4 v[44:45], v[40:43], off
	global_store_dwordx4 v[28:29], v[24:27], off
	global_store_dwordx4 v[12:13], v[8:11], off
	global_store_dwordx4 v[12:13], v[4:7], off offset:256
	s_cbranch_vccz .LBB0_902
	s_waitcnt vmcnt(0)
	s_cmpk_gt_u32 s24, 0xff
	s_cbranch_scc1 .LBB0_909
	s_barrier

; #define STG(P, GB) do { const char* _gb = (GB); \
;     _Pragma("unroll") for (int _i = 0; _i < 2; ++_i) { \
;       __builtin_amdgcn_global_load_lds((const unsigned*)(_gb + voff[_i]), \
;         (LAS unsigned*)((LAS char*)(P) + ldsw + _i * 8192), 16, 0, 0); } } while (0)
; #define LDA(dst, b, h) _Pragma("unroll") for (int m = 0; m < 4; ++m) _Pragma("unroll") for (int k = 0; k < 2; ++k) \
;     dst[m][k] = *(const LAS bf16x8*)((LAS char*)SA(b, h) + aoff + m * 2048 + k * 1024)
; #define LDB(dst, b, h) _Pragma("unroll") for (int n = 0; n < 2; ++n) _Pragma("unroll") for (int k = 0; k < 2; ++k) \
;     dst[n][k] = *(const LAS bf16x8*)((LAS char*)SB(b, h) + boff + n * 2048 + k * 1024)
; #define MMA(ai, bj, At_, Bt_) do { __builtin_amdgcn_s_setprio(1); \
;     _Pragma("unroll") for (int m = 0; m < 4; ++m) _Pragma("unroll") for (int n = 0; n < 2; ++n) _Pragma("unroll") for (int k = 0; k < 2; ++k) \
;       acc[ai][bj][m][n] = __builtin_amdgcn_mfma_f32_16x16x32_bf16(Bt_[n][k], At_[m][k], acc[ai][bj][m][n], 0, 0, 0); \
;     __builtin_amdgcn_s_setprio(0); } while (0)
; #define WAIT_V(n) asm volatile("s_waitcnt vmcnt(" #n ")" ::: "memory")
; #define WAIT_L(n) asm volatile("s_waitcnt lgkmcnt(" #n ")" ::: "memory")
; #define BAR __builtin_amdgcn_s_barrier()
; #define SCHED __builtin_amdgcn_sched_barrier(0)
; __device__ __forceinline__ void gemm_phase(const bf16_t* __restrict__ A, const bf16_t* __restrict__ Bt, bf16_t* __restrict__ C, int M, int N, int K,
;                                            int ldc, const int EPI, char* smem, const int wid_u) {
;     ...
;       LDB(B0, 0, 0); SCHED; LDA(At, 0, 0); STG(SA(1, 1), a1 + hstep);
;       WAIT_L(8); BAR; WAIT_L(0); MMA(0, 0, At, B0); BAR; SCHED;
;       LDB(B1, 0, 1); STG(SB(0, 0), b2);
;       BAR; WAIT_L(0); MMA(0, 1, At, B1); BAR;
;       LDA(At, 0, 1); STG(SA(0, 0), a2);
;       BAR; WAIT_L(0); MMA(1, 0, At, B0); BAR; SCHED;
;       STG(SB(0, 1), b2 + hstep);
;       WAIT_V(6); BAR; MMA(1, 1, At, B1); BAR;
;       LDB(B0, 1, 0); SCHED; LDA(At, 1, 0); STG(SA(0, 1), a2 + hstep);
;       WAIT_L(8); BAR; WAIT_L(0); MMA(0, 0, At, B0); BAR; SCHED;
;       LDB(B1, 1, 1); STG(SB(1, 0), b3);
;       BAR; WAIT_L(0); MMA(0, 1, At, B1); BAR;
;       LDA(At, 1, 1); STG(SA(1, 0), a3);
;       BAR; WAIT_L(0); MMA(1, 0, At, B0); BAR; SCHED;
;       STG(SB(1, 1), b3 + hstep);
;       WAIT_V(6); BAR; MMA(1, 1, At, B1); BAR;
.LBB0_1026:
	ds_read_b128 v[150:153], v146
	ds_read_b128 v[154:157], v146 offset:1024
	ds_read_b128 v[158:161], v146 offset:2048
	ds_read_b128 v[162:165], v146 offset:3072
	s_add_u32 s20, s18, 0x100
	s_addc_u32 s21, s19, 0
	s_cmp_eq_u32 s53, 12
	s_cselect_b32 s25, s48, s21
	s_cselect_b32 s24, s49, s20
	s_cselect_b32 s23, s13, s52
	s_cselect_b32 s22, s50, s51
	v_lshl_add_u64 v[142:143], s[18:19], 0, v[136:137]
	s_add_i32 m0, s34, 0xc000
	ds_read_b128 v[166:169], v147
	ds_read_b128 v[170:173], v147 offset:1024
	ds_read_b128 v[174:177], v147 offset:2048
	ds_read_b128 v[178:181], v147 offset:3072
	ds_read_b128 v[182:185], v147 offset:4096
	ds_read_b128 v[186:189], v147 offset:5120
	ds_read_b128 v[190:193], v147 offset:6144
	ds_read_b128 v[194:197], v147 offset:7168
	global_load_lds_dwordx4 v[142:143], off
	s_add_i32 m0, s34, 0xe000
	v_lshl_add_u64 v[142:143], s[18:19], 0, v[134:135]
	global_load_lds_dwordx4 v[142:143], off
	s_waitcnt lgkmcnt(8)
	s_barrier
	s_waitcnt lgkmcnt(0)
	s_waitcnt lgkmcnt(0)
	v_mfma_f32_16x16x32_bf16 v[124:127], v[150:153], v[166:169], v[124:127]
	v_mfma_f32_16x16x32_bf16 v[120:123], v[158:161], v[166:169], v[120:123]
	v_mfma_f32_16x16x32_bf16 v[108:111], v[150:153], v[174:177], v[108:111]
	v_mfma_f32_16x16x32_bf16 v[104:107], v[158:161], v[174:177], v[104:107]
	v_mfma_f32_16x16x32_bf16 v[92:95], v[150:153], v[182:185], v[92:95]
	v_mfma_f32_16x16x32_bf16 v[88:91], v[158:161], v[182:185], v[88:91]
	v_mfma_f32_16x16x32_bf16 v[76:79], v[150:153], v[190:193], v[76:79]
	v_mfma_f32_16x16x32_bf16 v[72:75], v[158:161], v[190:193], v[72:75]
	v_mfma_f32_16x16x32_bf16 v[124:127], v[154:157], v[170:173], v[124:127]
	v_mfma_f32_16x16x32_bf16 v[120:123], v[162:165], v[170:173], v[120:123]
	v_mfma_f32_16x16x32_bf16 v[108:111], v[154:157], v[178:181], v[108:111]
	v_mfma_f32_16x16x32_bf16 v[104:107], v[162:165], v[178:181], v[104:107]
	v_mfma_f32_16x16x32_bf16 v[92:95], v[154:157], v[186:189], v[92:95]
	v_mfma_f32_16x16x32_bf16 v[88:91], v[162:165], v[186:189], v[88:91]
	v_mfma_f32_16x16x32_bf16 v[76:79], v[154:157], v[194:197], v[76:79]
	v_mfma_f32_16x16x32_bf16 v[72:75], v[162:165], v[194:197], v[72:75]
	s_barrier
	s_add_i32 s18, s40, s31
	v_lshl_add_u64 v[142:143], s[22:23], 0, v[130:131]
	s_mov_b32 m0, s18
	ds_read_b128 v[198:201], v148
	ds_read_b128 v[202:205], v148 offset:1024
	ds_read_b128 v[206:209], v148 offset:2048
	ds_read_b128 v[210:213], v148 offset:3072
	global_load_lds_dwordx4 v[142:143], off
	s_add_i32 m0, s18, 0x2000
	v_lshl_add_u64 v[214:215], s[22:23], 0, v[128:129]
	global_load_lds_dwordx4 v[214:215], off
	s_barrier
	s_waitcnt lgkmcnt(0)
	s_waitcnt lgkmcnt(0)
	v_mfma_f32_16x16x32_bf16 v[116:119], v[198:201], v[166:169], v[116:119]
	v_mfma_f32_16x16x32_bf16 v[112:115], v[206:209], v[166:169], v[112:115]
	v_mfma_f32_16x16x32_bf16 v[100:103], v[198:201], v[174:177], v[100:103]
	v_mfma_f32_16x16x32_bf16 v[96:99], v[206:209], v[174:177], v[96:99]
	v_mfma_f32_16x16x32_bf16 v[84:87], v[198:201], v[182:185], v[84:87]
	v_mfma_f32_16x16x32_bf16 v[80:83], v[206:209], v[182:185], v[80:83]
	v_mfma_f32_16x16x32_bf16 v[68:71], v[198:201], v[190:193], v[68:71]
	v_mfma_f32_16x16x32_bf16 v[64:67], v[206:209], v[190:193], v[64:67]
	v_mfma_f32_16x16x32_bf16 v[116:119], v[202:205], v[170:173], v[116:119]
	v_mfma_f32_16x16x32_bf16 v[112:115], v[210:213], v[170:173], v[112:115]
	v_mfma_f32_16x16x32_bf16 v[100:103], v[202:205], v[178:181], v[100:103]
	v_mfma_f32_16x16x32_bf16 v[96:99], v[210:213], v[178:181], v[96:99]
	v_mfma_f32_16x16x32_bf16 v[84:87], v[202:205], v[186:189], v[84:87]
	v_mfma_f32_16x16x32_bf16 v[80:83], v[210:213], v[186:189], v[80:83]
	v_mfma_f32_16x16x32_bf16 v[68:71], v[202:205], v[194:197], v[68:71]
	v_mfma_f32_16x16x32_bf16 v[64:67], v[210:213], v[194:197], v[64:67]
	s_mov_b32 m0, s34
	v_lshl_add_u64 v[216:217], s[24:25], 0, v[130:131]
	s_barrier
	ds_read_b128 v[166:169], v147 offset:16384
	ds_read_b128 v[170:173], v147 offset:17408
	ds_read_b128 v[174:177], v147 offset:18432
	ds_read_b128 v[178:181], v147 offset:19456
	ds_read_b128 v[182:185], v147 offset:20480
	ds_read_b128 v[186:189], v147 offset:21504
	ds_read_b128 v[190:193], v147 offset:22528
	ds_read_b128 v[194:197], v147 offset:23552
	global_load_lds_dwordx4 v[216:217], off
	s_mov_b32 m0, s35
	v_lshl_add_u64 v[218:219], s[24:25], 0, v[128:129]
	global_load_lds_dwordx4 v[218:219], off
	s_barrier
	s_waitcnt lgkmcnt(0)
	s_waitcnt lgkmcnt(0)
	v_mfma_f32_16x16x32_bf16 v[60:63], v[150:153], v[166:169], v[60:63]
	v_mfma_f32_16x16x32_bf16 v[56:59], v[158:161], v[166:169], v[56:59]
	v_mfma_f32_16x16x32_bf16 v[44:47], v[150:153], v[174:177], v[44:47]
	v_mfma_f32_16x16x32_bf16 v[40:43], v[158:161], v[174:177], v[40:43]
	v_mfma_f32_16x16x32_bf16 v[28:31], v[150:153], v[182:185], v[28:31]
	v_mfma_f32_16x16x32_bf16 v[24:27], v[158:161], v[182:185], v[24:27]
	v_mfma_f32_16x16x32_bf16 v[12:15], v[150:153], v[190:193], v[12:15]
	v_mfma_f32_16x16x32_bf16 v[8:11], v[158:161], v[190:193], v[8:11]
	v_mfma_f32_16x16x32_bf16 v[60:63], v[154:157], v[170:173], v[60:63]
	v_mfma_f32_16x16x32_bf16 v[56:59], v[162:165], v[170:173], v[56:59]
	v_mfma_f32_16x16x32_bf16 v[44:47], v[154:157], v[178:181], v[44:47]
	v_mfma_f32_16x16x32_bf16 v[40:43], v[162:165], v[178:181], v[40:43]
	v_mfma_f32_16x16x32_bf16 v[28:31], v[154:157], v[186:189], v[28:31]
	v_mfma_f32_16x16x32_bf16 v[24:27], v[162:165], v[186:189], v[24:27]
	v_mfma_f32_16x16x32_bf16 v[12:15], v[154:157], v[194:197], v[12:15]
	v_mfma_f32_16x16x32_bf16 v[8:11], v[162:165], v[194:197], v[8:11]
	s_barrier
; #define STG(P, GB) do { const char* _gb = (GB); \
;     _Pragma("unroll") for (int _i = 0; _i < 2; ++_i) { \
;       __builtin_amdgcn_global_load_lds((const unsigned*)(_gb + voff[_i]), \
;         (LAS unsigned*)((LAS char*)(P) + ldsw + _i * 8192), 16, 0, 0); } } while (0)
; #define LDA(dst, b, h) _Pragma("unroll") for (int m = 0; m < 4; ++m) _Pragma("unroll") for (int k = 0; k < 2; ++k) \
;     dst[m][k] = *(const LAS bf16x8*)((LAS char*)SA(b, h) + aoff + m * 2048 + k * 1024)
; #define LDB(dst, b, h) _Pragma("unroll") for (int n = 0; n < 2; ++n) _Pragma("unroll") for (int k = 0; k < 2; ++k) \
;     dst[n][k] = *(const LAS bf16x8*)((LAS char*)SB(b, h) + boff + n * 2048 + k * 1024)
; #define MMA(ai, bj, At_, Bt_) do { __builtin_amdgcn_s_setprio(1); \
;     _Pragma("unroll") for (int m = 0; m < 4; ++m) _Pragma("unroll") for (int n = 0; n < 2; ++n) _Pragma("unroll") for (int k = 0; k < 2; ++k) \
;       acc[ai][bj][m][n] = __builtin_amdgcn_mfma_f32_16x16x32_bf16(Bt_[n][k], At_[m][k], acc[ai][bj][m][n], 0, 0, 0); \
;     __builtin_amdgcn_s_setprio(0); } while (0)
; #define WAIT_V(n) asm volatile("s_waitcnt vmcnt(" #n ")" ::: "memory")
; #define WAIT_L(n) asm volatile("s_waitcnt lgkmcnt(" #n ")" ::: "memory")
; #define BAR __builtin_amdgcn_s_barrier()
; #define SCHED __builtin_amdgcn_sched_barrier(0)
; __device__ __forceinline__ void gemm_phase(const bf16_t* __restrict__ A, const bf16_t* __restrict__ Bt, bf16_t* __restrict__ C, int M, int N, int K,
;                                            int ldc, const int EPI, char* smem, const int wid_u) {
;     ...
;       LDB(B0, 0, 0); SCHED; LDA(At, 0, 0); STG(SA(1, 1), a1 + hstep);
;       WAIT_L(8); BAR; WAIT_L(0); MMA(0, 0, At, B0); BAR; SCHED;
;       LDB(B1, 0, 1); STG(SB(0, 0), b2);
;       BAR; WAIT_L(0); MMA(0, 1, At, B1); BAR;
;       LDA(At, 0, 1); STG(SA(0, 0), a2);
;       BAR; WAIT_L(0); MMA(1, 0, At, B0); BAR; SCHED;
;       STG(SB(0, 1), b2 + hstep);
;       WAIT_V(6); BAR; MMA(1, 1, At, B1); BAR;
;       LDB(B0, 1, 0); SCHED; LDA(At, 1, 0); STG(SA(0, 1), a2 + hstep);
;       WAIT_L(8); BAR; WAIT_L(0); MMA(0, 0, At, B0); BAR; SCHED;
;       LDB(B1, 1, 1); STG(SB(1, 0), b3);
;       BAR; WAIT_L(0); MMA(0, 1, At, B1); BAR;
;       LDA(At, 1, 1); STG(SA(1, 0), a3);
;       BAR; WAIT_L(0); MMA(1, 0, At, B0); BAR; SCHED;
;       STG(SB(1, 1), b3 + hstep);
;       WAIT_V(6); BAR; MMA(1, 1, At, B1); BAR;
	s_add_u32 s18, s22, 0x40000
	s_addc_u32 s19, s23, 0
	s_add_i32 s54, s41, s31
	s_mov_b32 m0, s54
	v_lshl_add_u64 v[150:151], s[18:19], 0, v[130:131]
	global_load_lds_dwordx4 v[150:151], off
	s_add_i32 m0, s54, 0x2000
	v_lshl_add_u64 v[150:151], s[18:19], 0, v[128:129]
	global_load_lds_dwordx4 v[150:151], off
	s_waitcnt vmcnt(6)
	s_barrier
	v_mfma_f32_16x16x32_bf16 v[52:55], v[198:201], v[166:169], v[52:55]
	v_mfma_f32_16x16x32_bf16 v[48:51], v[206:209], v[166:169], v[48:51]
	v_mfma_f32_16x16x32_bf16 v[36:39], v[198:201], v[174:177], v[36:39]
	v_mfma_f32_16x16x32_bf16 v[32:35], v[206:209], v[174:177], v[32:35]
	v_mfma_f32_16x16x32_bf16 v[20:23], v[198:201], v[182:185], v[20:23]
	v_mfma_f32_16x16x32_bf16 v[16:19], v[206:209], v[182:185], v[16:19]
	v_mfma_f32_16x16x32_bf16 v[4:7], v[198:201], v[190:193], v[4:7]
	v_mfma_f32_16x16x32_bf16 v[0:3], v[206:209], v[190:193], v[0:3]
	v_mfma_f32_16x16x32_bf16 v[52:55], v[202:205], v[170:173], v[52:55]
	v_mfma_f32_16x16x32_bf16 v[48:51], v[210:213], v[170:173], v[48:51]
	v_mfma_f32_16x16x32_bf16 v[36:39], v[202:205], v[178:181], v[36:39]
	v_mfma_f32_16x16x32_bf16 v[32:35], v[210:213], v[178:181], v[32:35]
	v_mfma_f32_16x16x32_bf16 v[20:23], v[202:205], v[186:189], v[20:23]
	v_mfma_f32_16x16x32_bf16 v[16:19], v[210:213], v[186:189], v[16:19]
	v_mfma_f32_16x16x32_bf16 v[4:7], v[202:205], v[194:197], v[4:7]
	v_mfma_f32_16x16x32_bf16 v[0:3], v[210:213], v[194:197], v[0:3]
	s_add_i32 s54, 0, 0x18000
	v_add_u32_e32 v149, s54, v145
	s_barrier
	ds_read_b128 v[150:153], v149
	ds_read_b128 v[154:157], v149 offset:1024
	ds_read_b128 v[158:161], v149 offset:2048
	ds_read_b128 v[162:165], v149 offset:3072
	s_add_u32 s18, s24, 0x40000
	s_addc_u32 s19, s25, 0
	s_mov_b32 m0, s36
	v_lshl_add_u64 v[198:199], s[18:19], 0, v[130:131]
	ds_read_b128 v[166:169], v147 offset:32768
	ds_read_b128 v[170:173], v147 offset:33792
	ds_read_b128 v[174:177], v147 offset:34816
	ds_read_b128 v[178:181], v147 offset:35840
	ds_read_b128 v[182:185], v147 offset:36864
	ds_read_b128 v[186:189], v147 offset:37888
	ds_read_b128 v[190:193], v147 offset:38912
	ds_read_b128 v[194:197], v147 offset:39936
	global_load_lds_dwordx4 v[198:199], off
	s_mov_b32 m0, s37
	v_lshl_add_u64 v[198:199], s[18:19], 0, v[128:129]
	global_load_lds_dwordx4 v[198:199], off
	s_waitcnt lgkmcnt(8)
	s_barrier
	s_waitcnt lgkmcnt(0)
	s_waitcnt lgkmcnt(0)
	v_mfma_f32_16x16x32_bf16 v[124:127], v[150:153], v[166:169], v[124:127]
	v_mfma_f32_16x16x32_bf16 v[120:123], v[158:161], v[166:169], v[120:123]
	v_mfma_f32_16x16x32_bf16 v[108:111], v[150:153], v[174:177], v[108:111]
	v_mfma_f32_16x16x32_bf16 v[104:107], v[158:161], v[174:177], v[104:107]
	v_mfma_f32_16x16x32_bf16 v[92:95], v[150:153], v[182:185], v[92:95]
	v_mfma_f32_16x16x32_bf16 v[88:91], v[158:161], v[182:185], v[88:91]
	v_mfma_f32_16x16x32_bf16 v[76:79], v[150:153], v[190:193], v[76:79]
	v_mfma_f32_16x16x32_bf16 v[72:75], v[158:161], v[190:193], v[72:75]
	v_mfma_f32_16x16x32_bf16 v[124:127], v[154:157], v[170:173], v[124:127]
	v_mfma_f32_16x16x32_bf16 v[120:123], v[162:165], v[170:173], v[120:123]
	v_mfma_f32_16x16x32_bf16 v[108:111], v[154:157], v[178:181], v[108:111]
	v_mfma_f32_16x16x32_bf16 v[104:107], v[162:165], v[178:181], v[104:107]
	v_mfma_f32_16x16x32_bf16 v[92:95], v[154:157], v[186:189], v[92:95]
	v_mfma_f32_16x16x32_bf16 v[88:91], v[162:165], v[186:189], v[88:91]
	v_mfma_f32_16x16x32_bf16 v[76:79], v[154:157], v[194:197], v[76:79]
	v_mfma_f32_16x16x32_bf16 v[72:75], v[162:165], v[194:197], v[72:75]
	s_barrier
	s_add_i32 s24, 0, 0x1c000
	s_add_i32 s18, s54, s31
	v_add_u32_e32 v149, s24, v145
	v_lshl_add_u64 v[142:143], v[142:143], 0, s[10:11]
	s_mov_b32 m0, s18
	ds_read_b128 v[198:201], v149
	ds_read_b128 v[202:205], v149 offset:1024
	ds_read_b128 v[206:209], v149 offset:2048
	ds_read_b128 v[210:213], v149 offset:3072
	global_load_lds_dwordx4 v[142:143], off
	s_add_i32 m0, s18, 0x2000
	v_lshl_add_u64 v[142:143], v[214:215], 0, s[10:11]
	global_load_lds_dwordx4 v[142:143], off
	s_barrier
	s_waitcnt lgkmcnt(0)
	s_waitcnt lgkmcnt(0)
	v_mfma_f32_16x16x32_bf16 v[116:119], v[198:201], v[166:169], v[116:119]
	v_mfma_f32_16x16x32_bf16 v[112:115], v[206:209], v[166:169], v[112:115]
	v_mfma_f32_16x16x32_bf16 v[100:103], v[198:201], v[174:177], v[100:103]
	v_mfma_f32_16x16x32_bf16 v[96:99], v[206:209], v[174:177], v[96:99]
	v_mfma_f32_16x16x32_bf16 v[84:87], v[198:201], v[182:185], v[84:87]
	v_mfma_f32_16x16x32_bf16 v[80:83], v[206:209], v[182:185], v[80:83]
	v_mfma_f32_16x16x32_bf16 v[68:71], v[198:201], v[190:193], v[68:71]
	v_mfma_f32_16x16x32_bf16 v[64:67], v[206:209], v[190:193], v[64:67]
	v_mfma_f32_16x16x32_bf16 v[116:119], v[202:205], v[170:173], v[116:119]
	v_mfma_f32_16x16x32_bf16 v[112:115], v[210:213], v[170:173], v[112:115]
	v_mfma_f32_16x16x32_bf16 v[100:103], v[202:205], v[178:181], v[100:103]
	v_mfma_f32_16x16x32_bf16 v[96:99], v[210:213], v[178:181], v[96:99]
	v_mfma_f32_16x16x32_bf16 v[84:87], v[202:205], v[186:189], v[84:87]
	v_mfma_f32_16x16x32_bf16 v[80:83], v[210:213], v[186:189], v[80:83]
	v_mfma_f32_16x16x32_bf16 v[68:71], v[202:205], v[194:197], v[68:71]
	v_mfma_f32_16x16x32_bf16 v[64:67], v[210:213], v[194:197], v[64:67]
	s_mov_b32 m0, s38
	v_lshl_add_u64 v[142:143], v[216:217], 0, s[10:11]
	s_barrier
	ds_read_b128 v[166:169], v147 offset:49152
	ds_read_b128 v[170:173], v147 offset:50176
	ds_read_b128 v[174:177], v147 offset:51200
	ds_read_b128 v[178:181], v147 offset:52224
	ds_read_b128 v[182:185], v147 offset:53248
	ds_read_b128 v[186:189], v147 offset:54272
	ds_read_b128 v[190:193], v147 offset:55296
	ds_read_b128 v[194:197], v147 offset:56320
	global_load_lds_dwordx4 v[142:143], off
	s_mov_b32 m0, s39
	v_lshl_add_u64 v[142:143], v[218:219], 0, s[10:11]
	global_load_lds_dwordx4 v[142:143], off
	s_barrier
; #define STG(P, GB) do { const char* _gb = (GB); \
;     _Pragma("unroll") for (int _i = 0; _i < 2; ++_i) { \
;       __builtin_amdgcn_global_load_lds((const unsigned*)(_gb + voff[_i]), \
;         (LAS unsigned*)((LAS char*)(P) + ldsw + _i * 8192), 16, 0, 0); } } while (0)
; #define LDA(dst, b, h) _Pragma("unroll") for (int m = 0; m < 4; ++m) _Pragma("unroll") for (int k = 0; k < 2; ++k) \
;     dst[m][k] = *(const LAS bf16x8*)((LAS char*)SA(b, h) + aoff + m * 2048 + k * 1024)
; #define LDB(dst, b, h) _Pragma("unroll") for (int n = 0; n < 2; ++n) _Pragma("unroll") for (int k = 0; k < 2; ++k) \
;     dst[n][k] = *(const LAS bf16x8*)((LAS char*)SB(b, h) + boff + n * 2048 + k * 1024)
; __device__ __forceinline__ void gemm_phase(const bf16_t* __restrict__ A, const bf16_t* __restrict__ Bt, bf16_t* __restrict__ C, int M, int N, int K,
;                                            int ldc, const int EPI, char* smem, const int wid_u) {
;     ...
;       WAIT_L(8); BAR; WAIT_L(0); MMA(0, 0, At, B0); BAR; SCHED;
;       LDB(B1, 1, 1); STG(SB(1, 0), b3);
;       BAR; WAIT_L(0); MMA(0, 1, At, B1); BAR;
;       LDA(At, 1, 1); STG(SA(1, 0), a3);
;       BAR; WAIT_L(0); MMA(1, 0, At, B0); BAR; SCHED;
;       STG(SB(1, 1), b3 + hstep);
;       WAIT_V(6); BAR; MMA(1, 1, At, B1); BAR;
;     }
;     {
;       const int brow = pm * BM, bcol = pn * BM;
; #pragma unroll
;       for (int ai = 0; ai < 2; ++ai)
; #pragma unroll
;         for (int m = 0; m < 4; ++m) {
;           const size_t row = (size_t)(brow + ai * HALF + wr * 64 + m * 16 + fr);
;           if (EPI == 0) {
; #pragma unroll
;             for (int bj = 0; bj < 2; ++bj) {
;               const f32x4 v0 = acc[ai][bj][m][0], v1 = acc[ai][bj][m][1];
;               uint4 u; u.x = cvt_pk_bf16(v0[0], v0[1]); u.y = cvt_pk_bf16(v0[2], v0[3]); u.z = cvt_pk_bf16(v1[0], v1[1]); u.w = cvt_pk_bf16(v1[2], v1[3]);
;               *(uint4*)(C + row * ldc + bcol + bj * HALF + wc * 32 + fq * 8) = u;
;             }
;           } else {
;             float o[8];
; #pragma unroll
;             for (int n = 0; n < 2; ++n) {
;               const f32x4 a = acc[ai][0][m][n], b = acc[ai][1][m][n];
; #pragma unroll
;               for (int j = 0; j < 4; ++j) o[n * 4 + j] = a[j] * __builtin_amdgcn_rcpf(1.f + __expf(-a[j])) * b[j];
;             }
;             *(uint4*)(C + row * ldc + (bcol >> 1) + wc * 32 + fq * 8) = pack8(o);
	s_waitcnt lgkmcnt(0)
	s_waitcnt lgkmcnt(0)
	v_mfma_f32_16x16x32_bf16 v[60:63], v[150:153], v[166:169], v[60:63]
	v_mfma_f32_16x16x32_bf16 v[56:59], v[158:161], v[166:169], v[56:59]
	v_mfma_f32_16x16x32_bf16 v[44:47], v[150:153], v[174:177], v[44:47]
	v_mfma_f32_16x16x32_bf16 v[40:43], v[158:161], v[174:177], v[40:43]
	v_mfma_f32_16x16x32_bf16 v[28:31], v[150:153], v[182:185], v[28:31]
	v_mfma_f32_16x16x32_bf16 v[24:27], v[158:161], v[182:185], v[24:27]
	v_mfma_f32_16x16x32_bf16 v[12:15], v[150:153], v[190:193], v[12:15]
	v_mfma_f32_16x16x32_bf16 v[8:11], v[158:161], v[190:193], v[8:11]
	v_mfma_f32_16x16x32_bf16 v[60:63], v[154:157], v[170:173], v[60:63]
	v_mfma_f32_16x16x32_bf16 v[56:59], v[162:165], v[170:173], v[56:59]
	v_mfma_f32_16x16x32_bf16 v[44:47], v[154:157], v[178:181], v[44:47]
	v_mfma_f32_16x16x32_bf16 v[40:43], v[162:165], v[178:181], v[40:43]
	v_mfma_f32_16x16x32_bf16 v[28:31], v[154:157], v[186:189], v[28:31]
	v_mfma_f32_16x16x32_bf16 v[24:27], v[162:165], v[186:189], v[24:27]
	v_mfma_f32_16x16x32_bf16 v[12:15], v[154:157], v[194:197], v[12:15]
	v_mfma_f32_16x16x32_bf16 v[8:11], v[162:165], v[194:197], v[8:11]
	s_barrier
	s_add_u32 s18, s22, 0x40080
	s_addc_u32 s19, s23, 0
	s_add_i32 s22, s24, s31
	s_mov_b32 m0, s22
	v_lshl_add_u64 v[142:143], s[18:19], 0, v[130:131]
	global_load_lds_dwordx4 v[142:143], off
	s_add_i32 m0, s22, 0x2000
	v_lshl_add_u64 v[142:143], s[18:19], 0, v[128:129]
	global_load_lds_dwordx4 v[142:143], off
	s_waitcnt vmcnt(6)
	s_barrier
	v_mfma_f32_16x16x32_bf16 v[52:55], v[198:201], v[166:169], v[52:55]
	v_mfma_f32_16x16x32_bf16 v[48:51], v[206:209], v[166:169], v[48:51]
	v_mfma_f32_16x16x32_bf16 v[36:39], v[198:201], v[174:177], v[36:39]
	v_mfma_f32_16x16x32_bf16 v[32:35], v[206:209], v[174:177], v[32:35]
	v_mfma_f32_16x16x32_bf16 v[20:23], v[198:201], v[182:185], v[20:23]
	v_mfma_f32_16x16x32_bf16 v[16:19], v[206:209], v[182:185], v[16:19]
	v_mfma_f32_16x16x32_bf16 v[4:7], v[198:201], v[190:193], v[4:7]
	v_mfma_f32_16x16x32_bf16 v[0:3], v[206:209], v[190:193], v[0:3]
	v_mfma_f32_16x16x32_bf16 v[52:55], v[202:205], v[170:173], v[52:55]
	v_mfma_f32_16x16x32_bf16 v[48:51], v[210:213], v[170:173], v[48:51]
	v_mfma_f32_16x16x32_bf16 v[36:39], v[202:205], v[178:181], v[36:39]
	v_mfma_f32_16x16x32_bf16 v[32:35], v[210:213], v[178:181], v[32:35]
	v_mfma_f32_16x16x32_bf16 v[20:23], v[202:205], v[186:189], v[20:23]
	v_mfma_f32_16x16x32_bf16 v[16:19], v[210:213], v[186:189], v[16:19]
	v_mfma_f32_16x16x32_bf16 v[4:7], v[202:205], v[194:197], v[4:7]
	v_mfma_f32_16x16x32_bf16 v[0:3], v[210:213], v[194:197], v[0:3]
	s_add_i32 s53, s53, 2
	s_add_u32 s51, s51, 0x100
	s_addc_u32 s52, s52, 0
	s_cmp_gt_u32 s53, 13
	s_mov_b64 s[18:19], s[20:21]
	s_barrier
	s_cbranch_scc0 .LBB0_1026
	v_mul_f32_e32 v142, 0xbfb8aa3b, v124
	v_exp_f32_e32 v142, v142
	v_mul_f32_e32 v143, 0xbfb8aa3b, v125
	v_exp_f32_e32 v143, v143
	s_lshl_b32 s18, s46, 8
	v_add_f32_e32 v142, 1.0, v142
	v_rcp_f32_e32 v150, v142
	v_add_f32_e32 v142, 1.0, v143
	v_rcp_f32_e32 v151, v142
	s_mov_b32 s19, s9
	v_lshl_add_u32 v149, s47, 8, v144
	v_lshl_add_u64 v[142:143], v[132:133], 0, s[18:19]
	v_pk_mul_f32 v[124:125], v[124:125], v[150:151]
	v_mul_f32_e32 v150, 0xbfb8aa3b, v126
	v_mul_f32_e32 v151, 0xbfb8aa3b, v127
	v_exp_f32_e32 v150, v150
	v_exp_f32_e32 v151, v151
	v_pk_mul_f32 v[116:117], v[124:125], v[116:117]
	s_and_b64 vcc, exec, s[4:5]
	v_add_f32_e32 v124, 1.0, v150
	v_add_f32_e32 v125, 1.0, v151
	v_mul_f32_e32 v150, 0xbfb8aa3b, v120
	v_mul_f32_e32 v151, 0xbfb8aa3b, v121
	v_rcp_f32_e32 v124, v124
	v_rcp_f32_e32 v125, v125
	v_exp_f32_e32 v150, v150
	v_exp_f32_e32 v151, v151
	s_mov_b32 s47, s8
	v_pk_mul_f32 v[124:125], v[126:127], v[124:125]
	v_add_f32_e32 v126, 1.0, v150
	v_add_f32_e32 v127, 1.0, v151
	v_mul_f32_e32 v150, 0xbfb8aa3b, v122
	v_mul_f32_e32 v151, 0xbfb8aa3b, v123
	v_exp_f32_e32 v150, v150
	v_exp_f32_e32 v151, v151
	v_rcp_f32_e32 v126, v126
	v_rcp_f32_e32 v127, v127
	v_add_f32_e32 v150, 1.0, v150
	v_add_f32_e32 v151, 1.0, v151
	v_rcp_f32_e32 v150, v150
	v_rcp_f32_e32 v151, v151
	v_pk_mul_f32 v[120:121], v[120:121], v[126:127]
	v_pk_mul_f32 v[118:119], v[124:125], v[118:119]
	v_pk_mul_f32 v[120:121], v[120:121], v[112:113]
	v_pk_mul_f32 v[112:113], v[122:123], v[150:151]
	s_mov_b32 s46, s12
	v_pk_mul_f32 v[122:123], v[112:113], v[114:115]
	v_mul_f32_e32 v115, 0xbfb8aa3b, v108
	v_cvt_pk_bf16_f32 v112, v116, v117
	v_exp_f32_e32 v116, v115
	v_mul_f32_e32 v115, 0xbfb8aa3b, v109
	v_exp_f32_e32 v117, v115
	v_cvt_pk_bf16_f32 v113, v118, v119
	v_cvt_pk_bf16_f32 v114, v120, v121
	v_cvt_pk_bf16_f32 v115, v122, v123
	v_add_f32_e32 v116, 1.0, v116
	v_add_f32_e32 v117, 1.0, v117
	v_mad_i64_i32 v[118:119], s[18:19], v149, s44, v[142:143]
	v_rcp_f32_e32 v116, v116
	v_rcp_f32_e32 v117, v117
	global_store_dwordx4 v[118:119], v[112:115], off
	s_mov_b64 s[20:21], s[16:17]
	v_pk_mul_f32 v[108:109], v[108:109], v[116:117]
	v_mul_f32_e32 v112, 0xbfb8aa3b, v110
	v_mul_f32_e32 v113, 0xbfb8aa3b, v111
	v_exp_f32_e32 v112, v112
	v_exp_f32_e32 v113, v113
	v_pk_mul_f32 v[100:101], v[108:109], v[100:101]
	v_or_b32_e32 v114, 16, v149
	v_add_f32_e32 v108, 1.0, v112
	v_add_f32_e32 v109, 1.0, v113
	v_mul_f32_e32 v112, 0xbfb8aa3b, v104
	v_mul_f32_e32 v113, 0xbfb8aa3b, v105
	v_rcp_f32_e32 v108, v108
	v_rcp_f32_e32 v109, v109
	v_exp_f32_e32 v112, v112
	v_exp_f32_e32 v113, v113
	v_pk_mul_f32 v[108:109], v[110:111], v[108:109]
	v_add_f32_e32 v110, 1.0, v112
	v_add_f32_e32 v111, 1.0, v113
	v_mul_f32_e32 v112, 0xbfb8aa3b, v106
	v_mul_f32_e32 v113, 0xbfb8aa3b, v107
	v_exp_f32_e32 v112, v112
	v_exp_f32_e32 v113, v113
	v_rcp_f32_e32 v110, v110
	v_rcp_f32_e32 v111, v111
	v_add_f32_e32 v112, 1.0, v112
; __device__ __forceinline__ void gemm_phase(const bf16_t* __restrict__ A, const bf16_t* __restrict__ Bt, bf16_t* __restrict__ C, int M, int N, int K,
;                                            int ldc, const int EPI, char* smem, const int wid_u) {
;     ...
;             float o[8];
; #pragma unroll
;             for (int n = 0; n < 2; ++n) {
;               const f32x4 a = acc[ai][0][m][n], b = acc[ai][1][m][n];
; #pragma unroll
;               for (int j = 0; j < 4; ++j) o[n * 4 + j] = a[j] * __builtin_amdgcn_rcpf(1.f + __expf(-a[j])) * b[j];
;             }
;             *(uint4*)(C + row * ldc + (bcol >> 1) + wc * 32 + fq * 8) = pack8(o);
	v_add_f32_e32 v113, 1.0, v113
	v_rcp_f32_e32 v112, v112
	v_rcp_f32_e32 v113, v113
	v_pk_mul_f32 v[104:105], v[104:105], v[110:111]
	v_pk_mul_f32 v[102:103], v[108:109], v[102:103]
	v_pk_mul_f32 v[104:105], v[104:105], v[96:97]
	v_pk_mul_f32 v[96:97], v[106:107], v[112:113]
	s_nop 0
	v_pk_mul_f32 v[106:107], v[96:97], v[98:99]
	v_mul_f32_e32 v99, 0xbfb8aa3b, v92
	v_cvt_pk_bf16_f32 v96, v100, v101
	v_exp_f32_e32 v100, v99
	v_mul_f32_e32 v99, 0xbfb8aa3b, v93
	v_exp_f32_e32 v101, v99
	v_cvt_pk_bf16_f32 v97, v102, v103
	v_cvt_pk_bf16_f32 v98, v104, v105
	v_cvt_pk_bf16_f32 v99, v106, v107
	v_add_f32_e32 v100, 1.0, v100
	v_add_f32_e32 v101, 1.0, v101
	v_mad_i64_i32 v[102:103], s[18:19], v114, s44, v[142:143]
	v_rcp_f32_e32 v100, v100
	v_rcp_f32_e32 v101, v101
	global_store_dwordx4 v[102:103], v[96:99], off
	v_pk_mul_f32 v[92:93], v[92:93], v[100:101]
	s_nop 0
	v_mul_f32_e32 v96, 0xbfb8aa3b, v94
	v_mul_f32_e32 v97, 0xbfb8aa3b, v95
	v_exp_f32_e32 v96, v96
	v_exp_f32_e32 v97, v97
	v_pk_mul_f32 v[84:85], v[92:93], v[84:85]
	v_or_b32_e32 v98, 32, v149
	v_add_f32_e32 v92, 1.0, v96
	v_add_f32_e32 v93, 1.0, v97
	v_mul_f32_e32 v96, 0xbfb8aa3b, v88
	v_mul_f32_e32 v97, 0xbfb8aa3b, v89
	v_rcp_f32_e32 v92, v92
	v_rcp_f32_e32 v93, v93
	v_exp_f32_e32 v96, v96
	v_exp_f32_e32 v97, v97
	v_pk_mul_f32 v[92:93], v[94:95], v[92:93]
	v_add_f32_e32 v94, 1.0, v96
	v_add_f32_e32 v95, 1.0, v97
	v_mul_f32_e32 v96, 0xbfb8aa3b, v90
	v_mul_f32_e32 v97, 0xbfb8aa3b, v91
	v_exp_f32_e32 v96, v96
	v_exp_f32_e32 v97, v97
	v_rcp_f32_e32 v94, v94
	v_rcp_f32_e32 v95, v95
	v_add_f32_e32 v96, 1.0, v96
	v_add_f32_e32 v97, 1.0, v97
	v_rcp_f32_e32 v96, v96
	v_rcp_f32_e32 v97, v97
	v_pk_mul_f32 v[88:89], v[88:89], v[94:95]
	v_pk_mul_f32 v[86:87], v[92:93], v[86:87]
	v_pk_mul_f32 v[88:89], v[88:89], v[80:81]
	v_pk_mul_f32 v[80:81], v[90:91], v[96:97]
	s_nop 0
	v_pk_mul_f32 v[90:91], v[80:81], v[82:83]
	v_mul_f32_e32 v83, 0xbfb8aa3b, v76
	v_cvt_pk_bf16_f32 v80, v84, v85
	v_exp_f32_e32 v84, v83
	v_mul_f32_e32 v83, 0xbfb8aa3b, v77
	v_exp_f32_e32 v85, v83
	v_cvt_pk_bf16_f32 v81, v86, v87
	v_cvt_pk_bf16_f32 v82, v88, v89
	v_cvt_pk_bf16_f32 v83, v90, v91
	v_add_f32_e32 v84, 1.0, v84
	v_add_f32_e32 v85, 1.0, v85
	v_mad_i64_i32 v[86:87], s[18:19], v98, s44, v[142:143]
	v_rcp_f32_e32 v84, v84
	v_rcp_f32_e32 v85, v85
	global_store_dwordx4 v[86:87], v[80:83], off
	v_pk_mul_f32 v[76:77], v[76:77], v[84:85]
	s_nop 0
	v_mul_f32_e32 v80, 0xbfb8aa3b, v78
	v_mul_f32_e32 v81, 0xbfb8aa3b, v79
	v_exp_f32_e32 v80, v80
	v_exp_f32_e32 v81, v81
	v_pk_mul_f32 v[68:69], v[76:77], v[68:69]
	v_or_b32_e32 v82, 48, v149
	v_add_f32_e32 v76, 1.0, v80
	v_add_f32_e32 v77, 1.0, v81
	v_mul_f32_e32 v80, 0xbfb8aa3b, v72
	v_mul_f32_e32 v81, 0xbfb8aa3b, v73
	v_rcp_f32_e32 v76, v76
	v_rcp_f32_e32 v77, v77
	v_exp_f32_e32 v80, v80
	v_exp_f32_e32 v81, v81
	v_pk_mul_f32 v[76:77], v[78:79], v[76:77]
	v_add_f32_e32 v78, 1.0, v80
	v_add_f32_e32 v79, 1.0, v81
	v_mul_f32_e32 v80, 0xbfb8aa3b, v74
	v_mul_f32_e32 v81, 0xbfb8aa3b, v75
	v_exp_f32_e32 v80, v80
	v_exp_f32_e32 v81, v81
	v_rcp_f32_e32 v78, v78
	v_rcp_f32_e32 v79, v79
	v_add_f32_e32 v80, 1.0, v80
	v_add_f32_e32 v81, 1.0, v81
	v_rcp_f32_e32 v80, v80
	v_rcp_f32_e32 v81, v81
	v_pk_mul_f32 v[72:73], v[72:73], v[78:79]
	v_pk_mul_f32 v[70:71], v[76:77], v[70:71]
	v_pk_mul_f32 v[72:73], v[72:73], v[64:65]
	v_pk_mul_f32 v[64:65], v[74:75], v[80:81]
	s_nop 0
	v_pk_mul_f32 v[74:75], v[64:65], v[66:67]
	v_mul_f32_e32 v67, 0xbfb8aa3b, v60
	v_cvt_pk_bf16_f32 v64, v68, v69
	v_exp_f32_e32 v68, v67
	v_mul_f32_e32 v67, 0xbfb8aa3b, v61
	v_exp_f32_e32 v69, v67
	v_cvt_pk_bf16_f32 v65, v70, v71
	v_cvt_pk_bf16_f32 v66, v72, v73
	v_cvt_pk_bf16_f32 v67, v74, v75
	v_add_f32_e32 v68, 1.0, v68
	v_add_f32_e32 v69, 1.0, v69
	v_mad_i64_i32 v[70:71], s[18:19], v82, s44, v[142:143]
	v_rcp_f32_e32 v68, v68
	v_rcp_f32_e32 v69, v69
	global_store_dwordx4 v[70:71], v[64:67], off
	v_pk_mul_f32 v[60:61], v[60:61], v[68:69]
	s_nop 0
	v_mul_f32_e32 v64, 0xbfb8aa3b, v62
	v_mul_f32_e32 v65, 0xbfb8aa3b, v63
	v_exp_f32_e32 v64, v64
	v_exp_f32_e32 v65, v65
	v_pk_mul_f32 v[52:53], v[60:61], v[52:53]
	v_add_u32_e32 v66, 0x80, v149
	v_add_f32_e32 v60, 1.0, v64
	v_add_f32_e32 v61, 1.0, v65
	v_mul_f32_e32 v64, 0xbfb8aa3b, v56
	v_mul_f32_e32 v65, 0xbfb8aa3b, v57
	v_rcp_f32_e32 v60, v60
	v_rcp_f32_e32 v61, v61
	v_exp_f32_e32 v64, v64
	v_exp_f32_e32 v65, v65
	v_pk_mul_f32 v[60:61], v[62:63], v[60:61]
	v_add_f32_e32 v62, 1.0, v64
	v_add_f32_e32 v63, 1.0, v65
	v_mul_f32_e32 v64, 0xbfb8aa3b, v58
	v_mul_f32_e32 v65, 0xbfb8aa3b, v59
	v_exp_f32_e32 v64, v64
	v_exp_f32_e32 v65, v65
	v_rcp_f32_e32 v62, v62
	v_rcp_f32_e32 v63, v63
	v_add_f32_e32 v64, 1.0, v64
	v_add_f32_e32 v65, 1.0, v65
	v_rcp_f32_e32 v64, v64
	v_rcp_f32_e32 v65, v65
	v_pk_mul_f32 v[56:57], v[56:57], v[62:63]
	v_pk_mul_f32 v[54:55], v[60:61], v[54:55]
	v_pk_mul_f32 v[56:57], v[56:57], v[48:49]
	v_pk_mul_f32 v[48:49], v[58:59], v[64:65]
	s_nop 0
	v_pk_mul_f32 v[58:59], v[48:49], v[50:51]
; #define WAIT_V(n) asm volatile("s_waitcnt vmcnt(" #n ")" ::: "memory")
; #define BAR __builtin_amdgcn_s_barrier()
; __device__ __forceinline__ void gemm_phase(const bf16_t* __restrict__ A, const bf16_t* __restrict__ Bt, bf16_t* __restrict__ C, int M, int N, int K,
;                                            int ldc, const int EPI, char* smem, const int wid_u) {
;     ...
;         for (int m = 0; m < 4; ++m) {
;           const size_t row = (size_t)(brow + ai * HALF + wr * 64 + m * 16 + fr);
;           if (EPI == 0) {
; #pragma unroll
;             for (int bj = 0; bj < 2; ++bj) {
;               const f32x4 v0 = acc[ai][bj][m][0], v1 = acc[ai][bj][m][1];
;               uint4 u; u.x = cvt_pk_bf16(v0[0], v0[1]); u.y = cvt_pk_bf16(v0[2], v0[3]); u.z = cvt_pk_bf16(v1[0], v1[1]); u.w = cvt_pk_bf16(v1[2], v1[3]);
;               *(uint4*)(C + row * ldc + bcol + bj * HALF + wc * 32 + fq * 8) = u;
;             }
;           } else {
;             float o[8];
; #pragma unroll
;             for (int n = 0; n < 2; ++n) {
;               const f32x4 a = acc[ai][0][m][n], b = acc[ai][1][m][n];
; #pragma unroll
;               for (int j = 0; j < 4; ++j) o[n * 4 + j] = a[j] * __builtin_amdgcn_rcpf(1.f + __expf(-a[j])) * b[j];
;             }
;             *(uint4*)(C + row * ldc + (bcol >> 1) + wc * 32 + fq * 8) = pack8(o);
;           }
;         }
;     }
;     if (!has_next) break;
; #pragma unroll
;     for (int a = 0; a < 2; ++a)
; #pragma unroll
;       for (int b = 0; b < 2; ++b)
; #pragma unroll
;         for (int m = 0; m < 4; ++m)
; #pragma unroll
;           for (int n = 0; n < 2; ++n) acc[a][b][m][n] = (f32x4){0.f, 0.f, 0.f, 0.f};
;     pm = npm; pn = npn; cA = nA; cB = nB; ++ui;
;   }
;   WAIT_V(0);
;   if (wr == 0) BAR;
;   BAR;
	v_mul_f32_e32 v51, 0xbfb8aa3b, v44
	v_cvt_pk_bf16_f32 v48, v52, v53
	v_exp_f32_e32 v52, v51
	v_mul_f32_e32 v51, 0xbfb8aa3b, v45
	v_exp_f32_e32 v53, v51
	v_cvt_pk_bf16_f32 v49, v54, v55
	v_cvt_pk_bf16_f32 v50, v56, v57
	v_cvt_pk_bf16_f32 v51, v58, v59
	v_add_f32_e32 v52, 1.0, v52
	v_add_f32_e32 v53, 1.0, v53
	v_mad_i64_i32 v[54:55], s[18:19], v66, s44, v[142:143]
	v_rcp_f32_e32 v52, v52
	v_rcp_f32_e32 v53, v53
	global_store_dwordx4 v[54:55], v[48:51], off
	v_pk_mul_f32 v[44:45], v[44:45], v[52:53]
	s_nop 0
	v_mul_f32_e32 v48, 0xbfb8aa3b, v46
	v_mul_f32_e32 v49, 0xbfb8aa3b, v47
	v_exp_f32_e32 v48, v48
	v_exp_f32_e32 v49, v49
	v_pk_mul_f32 v[36:37], v[44:45], v[36:37]
	v_add_u32_e32 v50, 0x90, v149
	v_add_f32_e32 v44, 1.0, v48
	v_add_f32_e32 v45, 1.0, v49
	v_mul_f32_e32 v48, 0xbfb8aa3b, v40
	v_mul_f32_e32 v49, 0xbfb8aa3b, v41
	v_rcp_f32_e32 v44, v44
	v_rcp_f32_e32 v45, v45
	v_exp_f32_e32 v48, v48
	v_exp_f32_e32 v49, v49
	v_pk_mul_f32 v[44:45], v[46:47], v[44:45]
	v_add_f32_e32 v46, 1.0, v48
	v_add_f32_e32 v47, 1.0, v49
	v_mul_f32_e32 v48, 0xbfb8aa3b, v42
	v_mul_f32_e32 v49, 0xbfb8aa3b, v43
	v_exp_f32_e32 v48, v48
	v_exp_f32_e32 v49, v49
	v_rcp_f32_e32 v46, v46
	v_rcp_f32_e32 v47, v47
	v_add_f32_e32 v48, 1.0, v48
	v_add_f32_e32 v49, 1.0, v49
	v_rcp_f32_e32 v48, v48
	v_rcp_f32_e32 v49, v49
	v_pk_mul_f32 v[40:41], v[40:41], v[46:47]
	v_pk_mul_f32 v[38:39], v[44:45], v[38:39]
	v_pk_mul_f32 v[40:41], v[40:41], v[32:33]
	v_pk_mul_f32 v[32:33], v[42:43], v[48:49]
	s_nop 0
	v_pk_mul_f32 v[42:43], v[32:33], v[34:35]
	v_mul_f32_e32 v35, 0xbfb8aa3b, v28
	v_cvt_pk_bf16_f32 v32, v36, v37
	v_exp_f32_e32 v36, v35
	v_mul_f32_e32 v35, 0xbfb8aa3b, v29
	v_exp_f32_e32 v37, v35
	v_cvt_pk_bf16_f32 v33, v38, v39
	v_cvt_pk_bf16_f32 v34, v40, v41
	v_cvt_pk_bf16_f32 v35, v42, v43
	v_add_f32_e32 v36, 1.0, v36
	v_add_f32_e32 v37, 1.0, v37
	v_mad_i64_i32 v[38:39], s[18:19], v50, s44, v[142:143]
	v_rcp_f32_e32 v36, v36
	v_rcp_f32_e32 v37, v37
	global_store_dwordx4 v[38:39], v[32:35], off
	v_pk_mul_f32 v[28:29], v[28:29], v[36:37]
	s_nop 0
	v_mul_f32_e32 v32, 0xbfb8aa3b, v30
	v_mul_f32_e32 v33, 0xbfb8aa3b, v31
	v_exp_f32_e32 v32, v32
	v_exp_f32_e32 v33, v33
	v_pk_mul_f32 v[20:21], v[28:29], v[20:21]
	v_add_u32_e32 v34, 0xa0, v149
	v_add_f32_e32 v28, 1.0, v32
	v_add_f32_e32 v29, 1.0, v33
	v_mul_f32_e32 v32, 0xbfb8aa3b, v24
	v_mul_f32_e32 v33, 0xbfb8aa3b, v25
	v_rcp_f32_e32 v28, v28
	v_rcp_f32_e32 v29, v29
	v_exp_f32_e32 v32, v32
	v_exp_f32_e32 v33, v33
	v_pk_mul_f32 v[28:29], v[30:31], v[28:29]
	v_add_f32_e32 v30, 1.0, v32
	v_add_f32_e32 v31, 1.0, v33
	v_mul_f32_e32 v32, 0xbfb8aa3b, v26
	v_mul_f32_e32 v33, 0xbfb8aa3b, v27
	v_exp_f32_e32 v32, v32
	v_exp_f32_e32 v33, v33
	v_rcp_f32_e32 v30, v30
	v_rcp_f32_e32 v31, v31
	v_add_f32_e32 v32, 1.0, v32
	v_add_f32_e32 v33, 1.0, v33
	v_rcp_f32_e32 v32, v32
	v_rcp_f32_e32 v33, v33
	v_pk_mul_f32 v[24:25], v[24:25], v[30:31]
	v_pk_mul_f32 v[22:23], v[28:29], v[22:23]
	v_pk_mul_f32 v[24:25], v[24:25], v[16:17]
	v_pk_mul_f32 v[16:17], v[26:27], v[32:33]
	s_nop 0
	v_pk_mul_f32 v[26:27], v[16:17], v[18:19]
	v_mul_f32_e32 v19, 0xbfb8aa3b, v12
	v_cvt_pk_bf16_f32 v16, v20, v21
	v_exp_f32_e32 v20, v19
	v_mul_f32_e32 v19, 0xbfb8aa3b, v13
	v_exp_f32_e32 v21, v19
	v_cvt_pk_bf16_f32 v17, v22, v23
	v_cvt_pk_bf16_f32 v18, v24, v25
	v_cvt_pk_bf16_f32 v19, v26, v27
	v_add_f32_e32 v20, 1.0, v20
	v_add_f32_e32 v21, 1.0, v21
	v_mad_i64_i32 v[22:23], s[18:19], v34, s44, v[142:143]
	v_rcp_f32_e32 v20, v20
	v_rcp_f32_e32 v21, v21
	global_store_dwordx4 v[22:23], v[16:19], off
	v_pk_mul_f32 v[12:13], v[12:13], v[20:21]
	s_nop 0
	v_mul_f32_e32 v16, 0xbfb8aa3b, v14
	v_mul_f32_e32 v17, 0xbfb8aa3b, v15
	v_exp_f32_e32 v16, v16
	v_exp_f32_e32 v17, v17
	v_pk_mul_f32 v[4:5], v[12:13], v[4:5]
	v_add_u32_e32 v18, 0xb0, v149
	v_add_f32_e32 v12, 1.0, v16
	v_add_f32_e32 v13, 1.0, v17
	v_mul_f32_e32 v16, 0xbfb8aa3b, v8
	v_mul_f32_e32 v17, 0xbfb8aa3b, v9
	v_rcp_f32_e32 v12, v12
	v_rcp_f32_e32 v13, v13
	v_exp_f32_e32 v16, v16
	v_exp_f32_e32 v17, v17
	v_pk_mul_f32 v[12:13], v[14:15], v[12:13]
	v_add_f32_e32 v14, 1.0, v16
	v_add_f32_e32 v15, 1.0, v17
	v_mul_f32_e32 v16, 0xbfb8aa3b, v10
	v_mul_f32_e32 v17, 0xbfb8aa3b, v11
	v_exp_f32_e32 v16, v16
	v_exp_f32_e32 v17, v17
	v_rcp_f32_e32 v14, v14
	v_rcp_f32_e32 v15, v15
	v_add_f32_e32 v16, 1.0, v16
	v_add_f32_e32 v17, 1.0, v17
	v_rcp_f32_e32 v16, v16
	v_rcp_f32_e32 v17, v17
	v_pk_mul_f32 v[8:9], v[8:9], v[14:15]
	v_pk_mul_f32 v[6:7], v[12:13], v[6:7]
	v_pk_mul_f32 v[8:9], v[8:9], v[0:1]
	v_pk_mul_f32 v[0:1], v[10:11], v[16:17]
	s_nop 0
	v_pk_mul_f32 v[10:11], v[0:1], v[2:3]
	v_cvt_pk_bf16_f32 v0, v4, v5
	v_mad_i64_i32 v[4:5], s[18:19], v18, s44, v[142:143]
	v_cvt_pk_bf16_f32 v1, v6, v7
	v_cvt_pk_bf16_f32 v2, v8, v9
	v_cvt_pk_bf16_f32 v3, v10, v11
	s_mov_b64 s[18:19], s[14:15]
	global_store_dwordx4 v[4:5], v[0:3], off
	s_cbranch_vccz .LBB0_1023
	s_waitcnt vmcnt(0)
	s_cmpk_gt_u32 s26, 0xff
	s_cbranch_scc1 .LBB0_1030
	s_barrier

; #define STG(P, GB) do { const char* _gb = (GB); \
;     _Pragma("unroll") for (int _i = 0; _i < 2; ++_i) { \
;       __builtin_amdgcn_global_load_lds((const unsigned*)(_gb + voff[_i]), \
;         (LAS unsigned*)((LAS char*)(P) + ldsw + _i * 8192), 16, 0, 0); } } while (0)
; #define LDA(dst, b, h) _Pragma("unroll") for (int m = 0; m < 4; ++m) _Pragma("unroll") for (int k = 0; k < 2; ++k) \
;     dst[m][k] = *(const LAS bf16x8*)((LAS char*)SA(b, h) + aoff + m * 2048 + k * 1024)
; #define LDB(dst, b, h) _Pragma("unroll") for (int n = 0; n < 2; ++n) _Pragma("unroll") for (int k = 0; k < 2; ++k) \
;     dst[n][k] = *(const LAS bf16x8*)((LAS char*)SB(b, h) + boff + n * 2048 + k * 1024)
; #define MMA(ai, bj, At_, Bt_) do { __builtin_amdgcn_s_setprio(1); \
;     _Pragma("unroll") for (int m = 0; m < 4; ++m) _Pragma("unroll") for (int n = 0; n < 2; ++n) _Pragma("unroll") for (int k = 0; k < 2; ++k) \
;       acc[ai][bj][m][n] = __builtin_amdgcn_mfma_f32_16x16x32_bf16(Bt_[n][k], At_[m][k], acc[ai][bj][m][n], 0, 0, 0); \
;     __builtin_amdgcn_s_setprio(0); } while (0)
; #define WAIT_V(n) asm volatile("s_waitcnt vmcnt(" #n ")" ::: "memory")
; #define WAIT_L(n) asm volatile("s_waitcnt lgkmcnt(" #n ")" ::: "memory")
; #define BAR __builtin_amdgcn_s_barrier()
; #define SCHED __builtin_amdgcn_sched_barrier(0)
; __device__ __forceinline__ void gemm_phase(const bf16_t* __restrict__ A, const bf16_t* __restrict__ Bt, bf16_t* __restrict__ C, int M, int N, int K,
;                                            int ldc, const int EPI, char* smem, const int wid_u) {
;     ...
;       LDB(B0, 0, 0); SCHED; LDA(At, 0, 0); STG(SA(1, 1), a1 + hstep);
;       WAIT_L(8); BAR; WAIT_L(0); MMA(0, 0, At, B0); BAR; SCHED;
;       LDB(B1, 0, 1); STG(SB(0, 0), b2);
;       BAR; WAIT_L(0); MMA(0, 1, At, B1); BAR;
;       LDA(At, 0, 1); STG(SA(0, 0), a2);
;       BAR; WAIT_L(0); MMA(1, 0, At, B0); BAR; SCHED;
;       STG(SB(0, 1), b2 + hstep);
;       WAIT_V(6); BAR; MMA(1, 1, At, B1); BAR;
;       LDB(B0, 1, 0); SCHED; LDA(At, 1, 0); STG(SA(0, 1), a2 + hstep);
;       WAIT_L(8); BAR; WAIT_L(0); MMA(0, 0, At, B0); BAR; SCHED;
;       LDB(B1, 1, 1); STG(SB(1, 0), b3);
;       BAR; WAIT_L(0); MMA(0, 1, At, B1); BAR;
;       LDA(At, 1, 1); STG(SA(1, 0), a3);
;       BAR; WAIT_L(0); MMA(1, 0, At, B0); BAR; SCHED;
;       STG(SB(1, 1), b3 + hstep);
;       WAIT_V(6); BAR; MMA(1, 1, At, B1); BAR;
.LBB1_431:
	ds_read_b128 v[140:143], v146
	ds_read_b128 v[150:153], v146 offset:1024
	ds_read_b128 v[154:157], v146 offset:2048
	ds_read_b128 v[158:161], v146 offset:3072
	s_add_i32 s54, s28, 2
	s_add_u32 s30, s4, 0x80
	s_addc_u32 s29, s5, 0
	s_cmp_eq_u32 s46, s28
	s_cselect_b32 s28, s24, s30
	s_cselect_b32 s29, s25, s29
	s_cselect_b32 s31, s7, s53
	s_cselect_b32 s30, s6, s52
	v_lshl_add_u64 v[194:195], s[4:5], 0, v[136:137]
	s_add_i32 m0, s36, 0xc000
	ds_read_b128 v[162:165], v147
	ds_read_b128 v[166:169], v147 offset:1024
	ds_read_b128 v[170:173], v147 offset:2048
	ds_read_b128 v[174:177], v147 offset:3072
	ds_read_b128 v[178:181], v147 offset:4096
	ds_read_b128 v[182:185], v147 offset:5120
	ds_read_b128 v[186:189], v147 offset:6144
	ds_read_b128 v[190:193], v147 offset:7168
	global_load_lds_dwordx4 v[194:195], off
	s_add_i32 m0, s36, 0xe000
	v_lshl_add_u64 v[194:195], s[4:5], 0, v[134:135]
	global_load_lds_dwordx4 v[194:195], off
	s_waitcnt lgkmcnt(8)
	s_barrier
	s_waitcnt lgkmcnt(0)
	s_setprio 1
	s_waitcnt lgkmcnt(0)
	v_mfma_f32_16x16x32_bf16 v[124:127], v[140:143], v[162:165], v[124:127]
	v_mfma_f32_16x16x32_bf16 v[120:123], v[154:157], v[162:165], v[120:123]
	v_mfma_f32_16x16x32_bf16 v[108:111], v[140:143], v[170:173], v[108:111]
	v_mfma_f32_16x16x32_bf16 v[104:107], v[154:157], v[170:173], v[104:107]
	v_mfma_f32_16x16x32_bf16 v[92:95], v[140:143], v[178:181], v[92:95]
	v_mfma_f32_16x16x32_bf16 v[88:91], v[154:157], v[178:181], v[88:91]
	v_mfma_f32_16x16x32_bf16 v[76:79], v[140:143], v[186:189], v[76:79]
	v_mfma_f32_16x16x32_bf16 v[72:75], v[154:157], v[186:189], v[72:75]
	v_mfma_f32_16x16x32_bf16 v[124:127], v[150:153], v[166:169], v[124:127]
	v_mfma_f32_16x16x32_bf16 v[120:123], v[158:161], v[166:169], v[120:123]
	v_mfma_f32_16x16x32_bf16 v[108:111], v[150:153], v[174:177], v[108:111]
	v_mfma_f32_16x16x32_bf16 v[104:107], v[158:161], v[174:177], v[104:107]
	v_mfma_f32_16x16x32_bf16 v[92:95], v[150:153], v[182:185], v[92:95]
	v_mfma_f32_16x16x32_bf16 v[88:91], v[158:161], v[182:185], v[88:91]
	v_mfma_f32_16x16x32_bf16 v[76:79], v[150:153], v[190:193], v[76:79]
	v_mfma_f32_16x16x32_bf16 v[72:75], v[158:161], v[190:193], v[72:75]
	s_setprio 0
	s_barrier
	s_add_i32 s55, s48, s34
	v_lshl_add_u64 v[210:211], s[30:31], 0, v[128:129]
	s_mov_b32 m0, s55
	ds_read_b128 v[194:197], v148
	ds_read_b128 v[198:201], v148 offset:1024
	ds_read_b128 v[202:205], v148 offset:2048
	ds_read_b128 v[206:209], v148 offset:3072
	global_load_lds_dwordx4 v[210:211], off
	s_add_i32 m0, s55, 0x2000
	v_lshl_add_u64 v[212:213], s[30:31], 0, v[130:131]
	global_load_lds_dwordx4 v[212:213], off
	s_barrier
	s_waitcnt lgkmcnt(0)
	s_setprio 1
	s_waitcnt lgkmcnt(0)
	v_mfma_f32_16x16x32_bf16 v[116:119], v[194:197], v[162:165], v[116:119]
	v_mfma_f32_16x16x32_bf16 v[112:115], v[202:205], v[162:165], v[112:115]
	v_mfma_f32_16x16x32_bf16 v[100:103], v[194:197], v[170:173], v[100:103]
	v_mfma_f32_16x16x32_bf16 v[96:99], v[202:205], v[170:173], v[96:99]
	v_mfma_f32_16x16x32_bf16 v[84:87], v[194:197], v[178:181], v[84:87]
	v_mfma_f32_16x16x32_bf16 v[80:83], v[202:205], v[178:181], v[80:83]
	v_mfma_f32_16x16x32_bf16 v[68:71], v[194:197], v[186:189], v[68:71]
	v_mfma_f32_16x16x32_bf16 v[64:67], v[202:205], v[186:189], v[64:67]
	v_mfma_f32_16x16x32_bf16 v[116:119], v[198:201], v[166:169], v[116:119]
	v_mfma_f32_16x16x32_bf16 v[112:115], v[206:209], v[166:169], v[112:115]
	v_mfma_f32_16x16x32_bf16 v[100:103], v[198:201], v[174:177], v[100:103]
	v_mfma_f32_16x16x32_bf16 v[96:99], v[206:209], v[174:177], v[96:99]
	v_mfma_f32_16x16x32_bf16 v[84:87], v[198:201], v[182:185], v[84:87]
	v_mfma_f32_16x16x32_bf16 v[80:83], v[206:209], v[182:185], v[80:83]
	v_mfma_f32_16x16x32_bf16 v[68:71], v[198:201], v[190:193], v[68:71]
	v_mfma_f32_16x16x32_bf16 v[64:67], v[206:209], v[190:193], v[64:67]
	s_setprio 0
	s_mov_b32 m0, s36
	v_lshl_add_u64 v[214:215], s[28:29], 0, v[128:129]
	s_barrier
	ds_read_b128 v[162:165], v147 offset:16384
	ds_read_b128 v[166:169], v147 offset:17408
	ds_read_b128 v[170:173], v147 offset:18432
	ds_read_b128 v[174:177], v147 offset:19456
	ds_read_b128 v[178:181], v147 offset:20480
	ds_read_b128 v[182:185], v147 offset:21504
	ds_read_b128 v[186:189], v147 offset:22528
	ds_read_b128 v[190:193], v147 offset:23552
	global_load_lds_dwordx4 v[214:215], off
	s_mov_b32 m0, s37
	v_lshl_add_u64 v[216:217], s[28:29], 0, v[130:131]
	global_load_lds_dwordx4 v[216:217], off
	s_barrier
	s_waitcnt lgkmcnt(0)
	s_setprio 1
	s_waitcnt lgkmcnt(0)
	v_mfma_f32_16x16x32_bf16 v[60:63], v[140:143], v[162:165], v[60:63]
	v_mfma_f32_16x16x32_bf16 v[56:59], v[154:157], v[162:165], v[56:59]
	v_mfma_f32_16x16x32_bf16 v[44:47], v[140:143], v[170:173], v[44:47]
	v_mfma_f32_16x16x32_bf16 v[40:43], v[154:157], v[170:173], v[40:43]
	v_mfma_f32_16x16x32_bf16 v[28:31], v[140:143], v[178:181], v[28:31]
	v_mfma_f32_16x16x32_bf16 v[24:27], v[154:157], v[178:181], v[24:27]
	v_mfma_f32_16x16x32_bf16 v[12:15], v[140:143], v[186:189], v[12:15]
	v_mfma_f32_16x16x32_bf16 v[8:11], v[154:157], v[186:189], v[8:11]
	v_mfma_f32_16x16x32_bf16 v[60:63], v[150:153], v[166:169], v[60:63]
	v_mfma_f32_16x16x32_bf16 v[56:59], v[158:161], v[166:169], v[56:59]
	v_mfma_f32_16x16x32_bf16 v[44:47], v[150:153], v[174:177], v[44:47]
	v_mfma_f32_16x16x32_bf16 v[40:43], v[158:161], v[174:177], v[40:43]
	v_mfma_f32_16x16x32_bf16 v[28:31], v[150:153], v[182:185], v[28:31]
	v_mfma_f32_16x16x32_bf16 v[24:27], v[158:161], v[182:185], v[24:27]
	v_mfma_f32_16x16x32_bf16 v[12:15], v[150:153], v[190:193], v[12:15]
	v_mfma_f32_16x16x32_bf16 v[8:11], v[158:161], v[190:193], v[8:11]
	s_setprio 0
	s_barrier
; #define STG(P, GB) do { const char* _gb = (GB); \
;     _Pragma("unroll") for (int _i = 0; _i < 2; ++_i) { \
;       __builtin_amdgcn_global_load_lds((const unsigned*)(_gb + voff[_i]), \
;         (LAS unsigned*)((LAS char*)(P) + ldsw + _i * 8192), 16, 0, 0); } } while (0)
; #define LDA(dst, b, h) _Pragma("unroll") for (int m = 0; m < 4; ++m) _Pragma("unroll") for (int k = 0; k < 2; ++k) \
;     dst[m][k] = *(const LAS bf16x8*)((LAS char*)SA(b, h) + aoff + m * 2048 + k * 1024)
; #define LDB(dst, b, h) _Pragma("unroll") for (int n = 0; n < 2; ++n) _Pragma("unroll") for (int k = 0; k < 2; ++k) \
;     dst[n][k] = *(const LAS bf16x8*)((LAS char*)SB(b, h) + boff + n * 2048 + k * 1024)
; #define MMA(ai, bj, At_, Bt_) do { __builtin_amdgcn_s_setprio(1); \
;     _Pragma("unroll") for (int m = 0; m < 4; ++m) _Pragma("unroll") for (int n = 0; n < 2; ++n) _Pragma("unroll") for (int k = 0; k < 2; ++k) \
;       acc[ai][bj][m][n] = __builtin_amdgcn_mfma_f32_16x16x32_bf16(Bt_[n][k], At_[m][k], acc[ai][bj][m][n], 0, 0, 0); \
;     __builtin_amdgcn_s_setprio(0); } while (0)
; #define WAIT_V(n) asm volatile("s_waitcnt vmcnt(" #n ")" ::: "memory")
; #define WAIT_L(n) asm volatile("s_waitcnt lgkmcnt(" #n ")" ::: "memory")
; #define BAR __builtin_amdgcn_s_barrier()
; #define SCHED __builtin_amdgcn_sched_barrier(0)
; __device__ __forceinline__ void gemm_phase(const bf16_t* __restrict__ A, const bf16_t* __restrict__ Bt, bf16_t* __restrict__ C, int M, int N, int K,
;                                            int ldc, const int EPI, char* smem, const int wid_u) {
;     ...
;       LDB(B0, 0, 0); SCHED; LDA(At, 0, 0); STG(SA(1, 1), a1 + hstep);
;       WAIT_L(8); BAR; WAIT_L(0); MMA(0, 0, At, B0); BAR; SCHED;
;       LDB(B1, 0, 1); STG(SB(0, 0), b2);
;       BAR; WAIT_L(0); MMA(0, 1, At, B1); BAR;
;       LDA(At, 0, 1); STG(SA(0, 0), a2);
;       BAR; WAIT_L(0); MMA(1, 0, At, B0); BAR; SCHED;
;       STG(SB(0, 1), b2 + hstep);
;       WAIT_V(6); BAR; MMA(1, 1, At, B1); BAR;
;       LDB(B0, 1, 0); SCHED; LDA(At, 1, 0); STG(SA(0, 1), a2 + hstep);
;       WAIT_L(8); BAR; WAIT_L(0); MMA(0, 0, At, B0); BAR; SCHED;
;       LDB(B1, 1, 1); STG(SB(1, 0), b3);
;       BAR; WAIT_L(0); MMA(0, 1, At, B1); BAR;
;       LDA(At, 1, 1); STG(SA(1, 0), a3);
;       BAR; WAIT_L(0); MMA(1, 0, At, B0); BAR; SCHED;
;       STG(SB(1, 1), b3 + hstep);
;       WAIT_V(6); BAR; MMA(1, 1, At, B1); BAR;
	s_add_u32 s30, s30, s18
	s_addc_u32 s31, s31, 0
	s_add_i32 s55, s49, s34
	v_lshl_add_u64 v[218:219], s[30:31], 0, v[128:129]
	s_mov_b32 m0, s55
	v_lshl_add_u64 v[220:221], s[30:31], 0, v[130:131]
	global_load_lds_dwordx4 v[218:219], off
	s_add_i32 m0, s55, 0x2000
	s_nop 0
	global_load_lds_dwordx4 v[220:221], off
	s_waitcnt vmcnt(6)
	s_barrier
	s_setprio 1
	v_mfma_f32_16x16x32_bf16 v[52:55], v[194:197], v[162:165], v[52:55]
	v_mfma_f32_16x16x32_bf16 v[48:51], v[202:205], v[162:165], v[48:51]
	v_mfma_f32_16x16x32_bf16 v[36:39], v[194:197], v[170:173], v[36:39]
	v_mfma_f32_16x16x32_bf16 v[32:35], v[202:205], v[170:173], v[32:35]
	v_mfma_f32_16x16x32_bf16 v[20:23], v[194:197], v[178:181], v[20:23]
	v_mfma_f32_16x16x32_bf16 v[16:19], v[202:205], v[178:181], v[16:19]
	v_mfma_f32_16x16x32_bf16 v[4:7], v[194:197], v[186:189], v[4:7]
	v_mfma_f32_16x16x32_bf16 v[0:3], v[202:205], v[186:189], v[0:3]
	v_mfma_f32_16x16x32_bf16 v[52:55], v[198:201], v[166:169], v[52:55]
	v_mfma_f32_16x16x32_bf16 v[48:51], v[206:209], v[166:169], v[48:51]
	v_mfma_f32_16x16x32_bf16 v[36:39], v[198:201], v[174:177], v[36:39]
	v_mfma_f32_16x16x32_bf16 v[32:35], v[206:209], v[174:177], v[32:35]
	v_mfma_f32_16x16x32_bf16 v[20:23], v[198:201], v[182:185], v[20:23]
	v_mfma_f32_16x16x32_bf16 v[16:19], v[206:209], v[182:185], v[16:19]
	v_mfma_f32_16x16x32_bf16 v[4:7], v[198:201], v[190:193], v[4:7]
	v_mfma_f32_16x16x32_bf16 v[0:3], v[206:209], v[190:193], v[0:3]
	s_setprio 0
	s_add_i32 s30, 0, 0x18000
	v_add_u32_e32 v149, s30, v145
	s_barrier
	ds_read_b128 v[140:143], v149
	ds_read_b128 v[150:153], v149 offset:1024
	ds_read_b128 v[154:157], v149 offset:2048
	ds_read_b128 v[158:161], v149 offset:3072
	s_add_u32 s28, s28, s18
	s_addc_u32 s29, s29, 0
	s_mov_b32 m0, s38
	v_lshl_add_u64 v[194:195], s[28:29], 0, v[128:129]
	ds_read_b128 v[162:165], v147 offset:32768
	ds_read_b128 v[166:169], v147 offset:33792
	ds_read_b128 v[170:173], v147 offset:34816
	ds_read_b128 v[174:177], v147 offset:35840
	ds_read_b128 v[178:181], v147 offset:36864
	ds_read_b128 v[182:185], v147 offset:37888
	ds_read_b128 v[186:189], v147 offset:38912
	ds_read_b128 v[190:193], v147 offset:39936
	global_load_lds_dwordx4 v[194:195], off
	s_mov_b32 m0, s39
	v_lshl_add_u64 v[194:195], s[28:29], 0, v[130:131]
	global_load_lds_dwordx4 v[194:195], off
	s_waitcnt lgkmcnt(8)
	s_barrier
	s_waitcnt lgkmcnt(0)
	s_setprio 1
	s_waitcnt lgkmcnt(0)
	v_mfma_f32_16x16x32_bf16 v[124:127], v[140:143], v[162:165], v[124:127]
	v_mfma_f32_16x16x32_bf16 v[120:123], v[154:157], v[162:165], v[120:123]
	v_mfma_f32_16x16x32_bf16 v[108:111], v[140:143], v[170:173], v[108:111]
	v_mfma_f32_16x16x32_bf16 v[104:107], v[154:157], v[170:173], v[104:107]
	v_mfma_f32_16x16x32_bf16 v[92:95], v[140:143], v[178:181], v[92:95]
	v_mfma_f32_16x16x32_bf16 v[88:91], v[154:157], v[178:181], v[88:91]
	v_mfma_f32_16x16x32_bf16 v[76:79], v[140:143], v[186:189], v[76:79]
	v_mfma_f32_16x16x32_bf16 v[72:75], v[154:157], v[186:189], v[72:75]
	v_mfma_f32_16x16x32_bf16 v[124:127], v[150:153], v[166:169], v[124:127]
	v_mfma_f32_16x16x32_bf16 v[120:123], v[158:161], v[166:169], v[120:123]
	v_mfma_f32_16x16x32_bf16 v[108:111], v[150:153], v[174:177], v[108:111]
	v_mfma_f32_16x16x32_bf16 v[104:107], v[158:161], v[174:177], v[104:107]
	v_mfma_f32_16x16x32_bf16 v[92:95], v[150:153], v[182:185], v[92:95]
	v_mfma_f32_16x16x32_bf16 v[88:91], v[158:161], v[182:185], v[88:91]
	v_mfma_f32_16x16x32_bf16 v[76:79], v[150:153], v[190:193], v[76:79]
	v_mfma_f32_16x16x32_bf16 v[72:75], v[158:161], v[190:193], v[72:75]
	s_setprio 0
	s_barrier
	s_add_i32 s28, 0, 0x1c000
	s_add_i32 s29, s30, s34
	v_add_u32_e32 v149, s28, v145
	v_lshl_add_u64 v[210:211], v[210:211], 0, s[20:21]
	s_mov_b32 m0, s29
	ds_read_b128 v[194:197], v149
	ds_read_b128 v[198:201], v149 offset:1024
	ds_read_b128 v[202:205], v149 offset:2048
	ds_read_b128 v[206:209], v149 offset:3072
	global_load_lds_dwordx4 v[210:211], off
	s_add_i32 m0, s29, 0x2000
	v_lshl_add_u64 v[210:211], v[212:213], 0, s[20:21]
	global_load_lds_dwordx4 v[210:211], off
	s_barrier
	s_waitcnt lgkmcnt(0)
	s_setprio 1
	s_waitcnt lgkmcnt(0)
	v_mfma_f32_16x16x32_bf16 v[116:119], v[194:197], v[162:165], v[116:119]
	v_mfma_f32_16x16x32_bf16 v[112:115], v[202:205], v[162:165], v[112:115]
	v_mfma_f32_16x16x32_bf16 v[100:103], v[194:197], v[170:173], v[100:103]
	v_mfma_f32_16x16x32_bf16 v[96:99], v[202:205], v[170:173], v[96:99]
	v_mfma_f32_16x16x32_bf16 v[84:87], v[194:197], v[178:181], v[84:87]
	v_mfma_f32_16x16x32_bf16 v[80:83], v[202:205], v[178:181], v[80:83]
	v_mfma_f32_16x16x32_bf16 v[68:71], v[194:197], v[186:189], v[68:71]
	v_mfma_f32_16x16x32_bf16 v[64:67], v[202:205], v[186:189], v[64:67]
	v_mfma_f32_16x16x32_bf16 v[116:119], v[198:201], v[166:169], v[116:119]
	v_mfma_f32_16x16x32_bf16 v[112:115], v[206:209], v[166:169], v[112:115]
	v_mfma_f32_16x16x32_bf16 v[100:103], v[198:201], v[174:177], v[100:103]
	v_mfma_f32_16x16x32_bf16 v[96:99], v[206:209], v[174:177], v[96:99]
	v_mfma_f32_16x16x32_bf16 v[84:87], v[198:201], v[182:185], v[84:87]
	v_mfma_f32_16x16x32_bf16 v[80:83], v[206:209], v[182:185], v[80:83]
	v_mfma_f32_16x16x32_bf16 v[68:71], v[198:201], v[190:193], v[68:71]
	v_mfma_f32_16x16x32_bf16 v[64:67], v[206:209], v[190:193], v[64:67]
	s_setprio 0
	s_mov_b32 m0, s41
	v_lshl_add_u64 v[210:211], v[214:215], 0, s[20:21]
	s_barrier
; #define STG(P, GB) do { const char* _gb = (GB); \
;     _Pragma("unroll") for (int _i = 0; _i < 2; ++_i) { \
;       __builtin_amdgcn_global_load_lds((const unsigned*)(_gb + voff[_i]), \
;         (LAS unsigned*)((LAS char*)(P) + ldsw + _i * 8192), 16, 0, 0); } } while (0)
; #define LDA(dst, b, h) _Pragma("unroll") for (int m = 0; m < 4; ++m) _Pragma("unroll") for (int k = 0; k < 2; ++k) \
;     dst[m][k] = *(const LAS bf16x8*)((LAS char*)SA(b, h) + aoff + m * 2048 + k * 1024)
; #define WAIT_V(n) asm volatile("s_waitcnt vmcnt(" #n ")" ::: "memory")
; #define WAIT_L(n) asm volatile("s_waitcnt lgkmcnt(" #n ")" ::: "memory")
; #define BAR __builtin_amdgcn_s_barrier()
; #define SCHED __builtin_amdgcn_sched_barrier(0)
; __device__ __forceinline__ void gemm_phase(const bf16_t* __restrict__ A, const bf16_t* __restrict__ Bt, bf16_t* __restrict__ C, int M, int N, int K,
;                                            int ldc, const int EPI, char* smem, const int wid_u) {
;     ...
;       LDA(At, 1, 1); STG(SA(1, 0), a3);
;       BAR; WAIT_L(0); MMA(1, 0, At, B0); BAR; SCHED;
;       STG(SB(1, 1), b3 + hstep);
;       WAIT_V(6); BAR; MMA(1, 1, At, B1); BAR;
;     }
;     {
;       const int brow = pm * BM, bcol = pn * BM;
; #pragma unroll
;       for (int ai = 0; ai < 2; ++ai)
; #pragma unroll
;         for (int m = 0; m < 4; ++m) {
;           const size_t row = (size_t)(brow + ai * HALF + wr * 64 + m * 16 + fr);
;           if (EPI == 0) {
; #pragma unroll
;             for (int bj = 0; bj < 2; ++bj) {
;               const f32x4 v0 = acc[ai][bj][m][0], v1 = acc[ai][bj][m][1];
;               uint4 u; u.x = cvt_pk_bf16(v0[0], v0[1]); u.y = cvt_pk_bf16(v0[2], v0[3]); u.z = cvt_pk_bf16(v1[0], v1[1]); u.w = cvt_pk_bf16(v1[2], v1[3]);
;               *(uint4*)(C + row * ldc + bcol + bj * HALF + wc * 32 + fq * 8) = u;
;             }
;           } else {
;             float o[8];
; #pragma unroll
;             for (int n = 0; n < 2; ++n) {
;               const f32x4 a = acc[ai][0][m][n], b = acc[ai][1][m][n];
; #pragma unroll
;               for (int j = 0; j < 4; ++j) o[n * 4 + j] = a[j] * __builtin_amdgcn_rcpf(1.f + __expf(-a[j])) * b[j];
;             }
;             *(uint4*)(C + row * ldc + (bcol >> 1) + wc * 32 + fq * 8) = pack8(o);
	ds_read_b128 v[162:165], v147 offset:49152
	ds_read_b128 v[166:169], v147 offset:50176
	ds_read_b128 v[170:173], v147 offset:51200
	ds_read_b128 v[174:177], v147 offset:52224
	ds_read_b128 v[178:181], v147 offset:53248
	ds_read_b128 v[182:185], v147 offset:54272
	ds_read_b128 v[186:189], v147 offset:55296
	ds_read_b128 v[190:193], v147 offset:56320
	global_load_lds_dwordx4 v[210:211], off
	s_mov_b32 m0, s42
	v_lshl_add_u64 v[210:211], v[216:217], 0, s[20:21]
	global_load_lds_dwordx4 v[210:211], off
	s_barrier
	s_waitcnt lgkmcnt(0)
	s_setprio 1
	s_waitcnt lgkmcnt(0)
	v_mfma_f32_16x16x32_bf16 v[60:63], v[140:143], v[162:165], v[60:63]
	v_mfma_f32_16x16x32_bf16 v[56:59], v[154:157], v[162:165], v[56:59]
	v_mfma_f32_16x16x32_bf16 v[44:47], v[140:143], v[170:173], v[44:47]
	v_mfma_f32_16x16x32_bf16 v[40:43], v[154:157], v[170:173], v[40:43]
	v_mfma_f32_16x16x32_bf16 v[28:31], v[140:143], v[178:181], v[28:31]
	v_mfma_f32_16x16x32_bf16 v[24:27], v[154:157], v[178:181], v[24:27]
	v_mfma_f32_16x16x32_bf16 v[12:15], v[140:143], v[186:189], v[12:15]
	v_mfma_f32_16x16x32_bf16 v[8:11], v[154:157], v[186:189], v[8:11]
	v_mfma_f32_16x16x32_bf16 v[60:63], v[150:153], v[166:169], v[60:63]
	v_mfma_f32_16x16x32_bf16 v[56:59], v[158:161], v[166:169], v[56:59]
	v_mfma_f32_16x16x32_bf16 v[44:47], v[150:153], v[174:177], v[44:47]
	v_mfma_f32_16x16x32_bf16 v[40:43], v[158:161], v[174:177], v[40:43]
	v_mfma_f32_16x16x32_bf16 v[28:31], v[150:153], v[182:185], v[28:31]
	v_mfma_f32_16x16x32_bf16 v[24:27], v[158:161], v[182:185], v[24:27]
	v_mfma_f32_16x16x32_bf16 v[12:15], v[150:153], v[190:193], v[12:15]
	v_mfma_f32_16x16x32_bf16 v[8:11], v[158:161], v[190:193], v[8:11]
	s_setprio 0
	s_barrier
	s_add_i32 s28, s28, s34
	s_mov_b32 m0, s28
	v_lshl_add_u64 v[140:141], v[218:219], 0, s[20:21]
	global_load_lds_dwordx4 v[140:141], off
	s_add_i32 m0, s28, 0x2000
	v_lshl_add_u64 v[140:141], v[220:221], 0, s[20:21]
	global_load_lds_dwordx4 v[140:141], off
	s_waitcnt vmcnt(6)
	s_barrier
	s_setprio 1
	v_mfma_f32_16x16x32_bf16 v[52:55], v[194:197], v[162:165], v[52:55]
	v_mfma_f32_16x16x32_bf16 v[48:51], v[202:205], v[162:165], v[48:51]
	v_mfma_f32_16x16x32_bf16 v[36:39], v[194:197], v[170:173], v[36:39]
	v_mfma_f32_16x16x32_bf16 v[32:35], v[202:205], v[170:173], v[32:35]
	v_mfma_f32_16x16x32_bf16 v[20:23], v[194:197], v[178:181], v[20:23]
	v_mfma_f32_16x16x32_bf16 v[16:19], v[202:205], v[178:181], v[16:19]
	v_mfma_f32_16x16x32_bf16 v[4:7], v[194:197], v[186:189], v[4:7]
	v_mfma_f32_16x16x32_bf16 v[0:3], v[202:205], v[186:189], v[0:3]
	v_mfma_f32_16x16x32_bf16 v[52:55], v[198:201], v[166:169], v[52:55]
	v_mfma_f32_16x16x32_bf16 v[48:51], v[206:209], v[166:169], v[48:51]
	v_mfma_f32_16x16x32_bf16 v[36:39], v[198:201], v[174:177], v[36:39]
	v_mfma_f32_16x16x32_bf16 v[32:35], v[206:209], v[174:177], v[32:35]
	v_mfma_f32_16x16x32_bf16 v[20:23], v[198:201], v[182:185], v[20:23]
	v_mfma_f32_16x16x32_bf16 v[16:19], v[206:209], v[182:185], v[16:19]
	v_mfma_f32_16x16x32_bf16 v[4:7], v[198:201], v[190:193], v[4:7]
	v_mfma_f32_16x16x32_bf16 v[0:3], v[206:209], v[190:193], v[0:3]
	s_setprio 0
	s_add_u32 s52, s52, 0x100
	s_addc_u32 s53, s53, 0
	s_add_u32 s4, s4, 0x100
	s_addc_u32 s5, s5, 0
	s_cmp_ge_u32 s54, s43
	s_mov_b32 s28, s54
	s_barrier
	s_cbranch_scc0 .LBB1_431
	s_lshl_b32 s4, s26, 7
	s_ashr_i32 s5, s4, 31
	v_lshl_add_u32 v149, s27, 8, v144
	v_lshl_add_u64 v[140:141], s[4:5], 1, v[132:133]
	s_mov_b64 s[4:5], -1
	s_and_b64 vcc, exec, s[22:23]
	s_cbranch_vccz .LBB1_434
	v_mul_f32_e32 v150, 0xbfb8aa3b, v126
	v_mul_f32_e32 v151, 0xbfb8aa3b, v127
	v_mul_f32_e32 v142, 0xbfb8aa3b, v124
	v_mul_f32_e32 v143, 0xbfb8aa3b, v125
	v_exp_f32_e32 v150, v150
	v_exp_f32_e32 v151, v151
	v_mul_f32_e32 v152, 0xbfb8aa3b, v120
	v_mul_f32_e32 v153, 0xbfb8aa3b, v121
	v_exp_f32_e32 v142, v142
	v_exp_f32_e32 v143, v143
	v_exp_f32_e32 v152, v152
	v_exp_f32_e32 v153, v153
	v_mul_f32_e32 v154, 0xbfb8aa3b, v122
	v_mul_f32_e32 v155, 0xbfb8aa3b, v123
	v_exp_f32_e32 v154, v154
	v_exp_f32_e32 v155, v155
	v_add_f32_e32 v150, 1.0, v150
	v_add_f32_e32 v151, 1.0, v151
	v_add_f32_e32 v142, 1.0, v142
	v_add_f32_e32 v143, 1.0, v143
	v_rcp_f32_e32 v150, v150
	v_rcp_f32_e32 v151, v151
	v_add_f32_e32 v152, 1.0, v152
	v_add_f32_e32 v153, 1.0, v153
	v_rcp_f32_e32 v142, v142
	v_rcp_f32_e32 v143, v143
	v_rcp_f32_e32 v152, v152
	v_rcp_f32_e32 v153, v153
	v_add_f32_e32 v154, 1.0, v154
	v_add_f32_e32 v155, 1.0, v155
	v_rcp_f32_e32 v154, v154
	v_rcp_f32_e32 v155, v155
	v_pk_mul_f32 v[150:151], v[126:127], v[150:151]
	v_pk_mul_f32 v[142:143], v[124:125], v[142:143]
	v_pk_mul_f32 v[156:157], v[150:151], v[118:119]
	v_pk_mul_f32 v[150:151], v[120:121], v[152:153]
	v_pk_mul_f32 v[142:143], v[142:143], v[116:117]
	v_pk_mul_f32 v[152:153], v[150:151], v[112:113]
	v_pk_mul_f32 v[150:151], v[122:123], v[154:155]
	v_cvt_pk_bf16_f32 v152, v152, v153
	v_pk_mul_f32 v[154:155], v[150:151], v[114:115]
	v_cvt_pk_bf16_f32 v150, v142, v143
	v_mad_i64_i32 v[142:143], s[4:5], s10, v149, 0
	v_cvt_pk_bf16_f32 v151, v156, v157
	v_cvt_pk_bf16_f32 v153, v154, v155
	v_lshl_add_u64 v[142:143], v[142:143], 1, v[140:141]
	global_store_dwordx4 v[142:143], v[150:153], off
	s_mov_b64 s[4:5], 0
